# EpiResid epilogue: LN scale/shift vectors cached in wave-private LDS, no per-group vmcnt drains; ticket atomics deferred; conv loops pipelined
# speedup vs baseline: 1.0303x; 1.0303x over previous
; __device__ __forceinline__ float bflo(unsigned w) { return __uint_as_float(w << 16); }
; __device__ __forceinline__ float bfhi(unsigned w) { return __uint_as_float(w & 0xffff0000u); }
; __device__ __forceinline__ u32x2 pack4(const f32x4 a) { u32x2 v; v.x = cvt_pk_bf16(a[0], a[1]); v.y = cvt_pk_bf16(a[2], a[3]); return v; }
;     __device__ __forceinline__ void apply(const RowInfo& ri, const ColInfo& ci, int row, int col, f32x4 a, f32x4 pv, float& s1, float& s2) const {
;         f32x4 h = pv;
;         if (!ident) { const f32x4 gg = *(const f32x4*)(g + col), bb = *(const f32x4*)(b + col); h = (pv - ri.mu) * ri.rstd * gg + bb; }
;         const f32x4 v = h * ALPHA + a;
;         *(u32x2*)(xb + (size_t)row * DM + col) = pack4(v);
;         s1 += (v[0] + v[1]) + (v[2] + v[3]); s2 += (v[0] * v[0] + v[1] * v[1]) + (v[2] * v[2] + v[3] * v[3]);
;     }
; template <class Epi>
; __device__ __forceinline__ void gemm_phase(LAS unsigned char* lds, const bf16_t* Ag, const bf16_t* Btg, const int K, const int nM, const int nN, const Epi& E) {
;     ...
;                 f32x4 pv[2][2];
; #pragma unroll
;                 for (int bj = 0; bj < 2; ++bj)
; #pragma unroll
;                     for (int n = 0; n < 2; ++n) { const u32x2 w = pk[m][bj][n]; pv[bj][n] = (f32x4){bflo(w.x), bfhi(w.x), bflo(w.y), bfhi(w.y)}; }
;                 const RowInfo ri = E.rowinfo(row, lrow, par, lds);
;                 float s1 = 0.f, s2 = 0.f;
; #pragma unroll
;                 for (int bj = 0; bj < 2; ++bj)
; #pragma unroll
;                     for (int n = 0; n < 2; ++n) E.apply(ri, ci[bj][n], row, pn * 256 + bj * 128 + wc * 32 + n * 16 + fq * 4, acc[ai][bj][m][n], pv[bj][n], s1, s2);
.LBB0_160:
	v_lshlrev_b64 v[142:143], 2, v[144:145]
	s_waitcnt vmcnt(0)
	v_lshlrev_b32_e32 v192, 16, v140
	v_and_b32_e32 v193, 0xffff0000, v140
	v_lshlrev_b32_e32 v196, 16, v141
	v_and_b32_e32 v197, 0xffff0000, v141
	v_mov_b32_e32 v183, v182
	s_and_b64 vcc, exec, s[40:41]
	v_lshl_add_u64 v[140:141], s[24:25], 0, v[142:143]
	v_lshl_add_u64 v[142:143], s[22:23], 0, v[142:143]
	s_cbranch_vccnz .Lgbfill_skip1
	v_and_b32_e32 v234, 7, v204
	v_bfe_u32 v235, v204, 3, 1
	v_lshrrev_b32_e32 v236, 4, v204
	v_lshlrev_b32_e32 v238, 4, v234
	v_lshl_add_u32 v238, v235, 9, v238
	v_lshlrev_b32_e32 v236, 4, v236
	v_sub_u32_e32 v238, v238, v236
	v_ashrrev_i32_e32 v239, 31, v238
	v_lshl_add_u64 v[240:241], v[140:141], 0, v[238:239]
	v_lshl_add_u64 v[242:243], v[142:143], 0, v[238:239]
	global_load_dwordx4 v[244:247], v[240:241], off
	global_load_dwordx4 v[248:251], v[242:243], off
	v_lshrrev_b32_e32 v237, 6, v198
	v_lshlrev_b32_e32 v237, 9, v237
	v_add_u32_e32 v237, 0x21000, v237
	v_add_u32_e32 v238, v237, v236
	v_lshl_add_u32 v237, v235, 7, v237
	v_lshl_add_u32 v237, v234, 4, v237
	s_waitcnt vmcnt(0)
	ds_write_b128 v237, v[244:247]
	ds_write_b128 v237, v[248:251] offset:256
	s_waitcnt lgkmcnt(0)
.Lgbfill_skip1:
	s_cbranch_vccnz .LBB0_162
	v_sub_f32_e32 v193, v193, v180
	v_sub_f32_e32 v192, v192, v180
	v_sub_f32_e32 v191, v197, v180
	v_sub_f32_e32 v190, v196, v180
	v_pk_mul_f32 v[210:211], v[182:183], v[192:193]
	v_mov_b32_e32 v192, v182
	v_mov_b32_e32 v193, v182
	v_pk_mul_f32 v[216:217], v[192:193], v[190:191]
	ds_read_b128 v[190:193], v238
	ds_read_b128 v[194:197], v238 offset:256
	s_waitcnt lgkmcnt(0)
	v_pk_fma_f32 v[196:197], v[216:217], v[192:193], v[196:197]
	v_pk_fma_f32 v[192:193], v[210:211], v[190:191], v[194:195]
.LBB0_162:
	v_pk_fma_f32 v[134:135], v[196:197], s[4:5], v[134:135] op_sel_hi:[1,0,1]
	v_pk_fma_f32 v[132:133], v[192:193], s[4:5], v[132:133] op_sel_hi:[1,0,1]
	v_lshlrev_b32_e32 v190, 16, v188
	v_and_b32_e32 v191, 0xffff0000, v188
	v_lshlrev_b32_e32 v194, 16, v189
	v_and_b32_e32 v195, 0xffff0000, v189
	v_cvt_pk_bf16_f32 v188, v132, v133
	v_cvt_pk_bf16_f32 v189, v134, v135
	s_and_b64 vcc, exec, s[40:41]
	global_store_dwordx2 v[174:175], v[188:189], off
	s_cbranch_vccnz .LBB0_164
	v_sub_f32_e32 v191, v191, v180
	v_sub_f32_e32 v190, v190, v180
	v_sub_f32_e32 v189, v195, v180
	v_sub_f32_e32 v188, v194, v180
	v_pk_mul_f32 v[196:197], v[182:183], v[190:191]
	v_mov_b32_e32 v190, v182
	v_mov_b32_e32 v191, v182
	v_pk_mul_f32 v[210:211], v[190:191], v[188:189]
	ds_read_b128 v[188:191], v238 offset:64
	ds_read_b128 v[192:195], v238 offset:320
	s_waitcnt lgkmcnt(0)
	v_pk_fma_f32 v[194:195], v[210:211], v[190:191], v[194:195]
	v_pk_fma_f32 v[190:191], v[196:197], v[188:189], v[192:193]
.LBB0_164:
	v_pk_fma_f32 v[130:131], v[194:195], s[4:5], v[130:131] op_sel_hi:[1,0,1]
	v_pk_fma_f32 v[128:129], v[190:191], s[4:5], v[128:129] op_sel_hi:[1,0,1]
	v_lshlrev_b32_e32 v188, 16, v186
	v_and_b32_e32 v189, 0xffff0000, v186
	v_lshlrev_b32_e32 v192, 16, v187
	v_and_b32_e32 v193, 0xffff0000, v187
	v_cvt_pk_bf16_f32 v186, v128, v129
	v_cvt_pk_bf16_f32 v187, v130, v131
	s_and_b64 vcc, exec, s[40:41]
	global_store_dwordx2 v[174:175], v[186:187], off offset:32
	s_cbranch_vccnz .LBB0_166
	v_sub_f32_e32 v189, v189, v180
	v_sub_f32_e32 v188, v188, v180
	v_sub_f32_e32 v187, v193, v180
	v_sub_f32_e32 v186, v192, v180
	v_pk_mul_f32 v[194:195], v[182:183], v[188:189]
	v_mov_b32_e32 v188, v182
	v_mov_b32_e32 v189, v182
	v_pk_mul_f32 v[196:197], v[188:189], v[186:187]
	ds_read_b128 v[186:189], v238 offset:128
	ds_read_b128 v[190:193], v238 offset:384
	s_waitcnt lgkmcnt(0)
	v_pk_fma_f32 v[192:193], v[196:197], v[188:189], v[192:193]
	v_pk_fma_f32 v[188:189], v[194:195], v[186:187], v[190:191]
.LBB0_166:
	v_pk_fma_f32 v[126:127], v[192:193], s[4:5], v[126:127] op_sel_hi:[1,0,1]
	v_pk_fma_f32 v[124:125], v[188:189], s[4:5], v[124:125] op_sel_hi:[1,0,1]
	v_lshlrev_b32_e32 v186, 16, v184
	v_and_b32_e32 v187, 0xffff0000, v184
	v_lshlrev_b32_e32 v184, 16, v185
	v_and_b32_e32 v185, 0xffff0000, v185
	v_cvt_pk_bf16_f32 v188, v124, v125
	v_cvt_pk_bf16_f32 v189, v126, v127
	s_and_b64 vcc, exec, s[40:41]
	global_store_dwordx2 v[174:175], v[188:189], off offset:256
	s_cbranch_vccnz .LBB0_168
	v_sub_f32_e32 v185, v185, v180
	v_sub_f32_e32 v184, v184, v180
	v_sub_f32_e32 v181, v187, v180
	v_sub_f32_e32 v180, v186, v180
	v_pk_mul_f32 v[190:191], v[182:183], v[180:181]
	v_mov_b32_e32 v183, v182
	v_pk_mul_f32 v[184:185], v[182:183], v[184:185]
	ds_read_b128 v[180:183], v238 offset:192
	ds_read_b128 v[186:189], v238 offset:448
	s_waitcnt lgkmcnt(0)
	v_pk_fma_f32 v[184:185], v[184:185], v[182:183], v[188:189]
	v_pk_fma_f32 v[186:187], v[190:191], v[180:181], v[186:187]

; __device__ __forceinline__ float bflo(unsigned w) { return __uint_as_float(w << 16); }
; __device__ __forceinline__ float bfhi(unsigned w) { return __uint_as_float(w & 0xffff0000u); }
; __device__ __forceinline__ u32x2 pack4(const f32x4 a) { u32x2 v; v.x = cvt_pk_bf16(a[0], a[1]); v.y = cvt_pk_bf16(a[2], a[3]); return v; }
;     __device__ __forceinline__ void apply(const RowInfo& ri, const ColInfo& ci, int row, int col, f32x4 a, f32x4 pv, float& s1, float& s2) const {
;         f32x4 h = pv;
;         if (!ident) { const f32x4 gg = *(const f32x4*)(g + col), bb = *(const f32x4*)(b + col); h = (pv - ri.mu) * ri.rstd * gg + bb; }
;         const f32x4 v = h * ALPHA + a;
;         *(u32x2*)(xb + (size_t)row * DM + col) = pack4(v);
;         s1 += (v[0] + v[1]) + (v[2] + v[3]); s2 += (v[0] * v[0] + v[1] * v[1]) + (v[2] * v[2] + v[3] * v[3]);
;     }
; template <class Epi>
; __device__ __forceinline__ void gemm_phase(LAS unsigned char* lds, const bf16_t* Ag, const bf16_t* Btg, const int K, const int nM, const int nN, const Epi& E) {
;     ...
;                 f32x4 pv[2][2];
; #pragma unroll
;                 for (int bj = 0; bj < 2; ++bj)
; #pragma unroll
;                     for (int n = 0; n < 2; ++n) { const u32x2 w = pk[m][bj][n]; pv[bj][n] = (f32x4){bflo(w.x), bfhi(w.x), bflo(w.y), bfhi(w.y)}; }
;                 const RowInfo ri = E.rowinfo(row, lrow, par, lds);
;                 float s1 = 0.f, s2 = 0.f;
; #pragma unroll
;                 for (int bj = 0; bj < 2; ++bj)
; #pragma unroll
;                     for (int n = 0; n < 2; ++n) E.apply(ri, ci[bj][n], row, pn * 256 + bj * 128 + wc * 32 + n * 16 + fq * 4, acc[ai][bj][m][n], pv[bj][n], s1, s2);
.LBB0_173:
	v_lshlrev_b32_e32 v126, 16, v172
	v_and_b32_e32 v127, 0xffff0000, v172
	v_lshlrev_b32_e32 v132, 16, v173
	v_and_b32_e32 v133, 0xffff0000, v173
	s_and_b64 vcc, exec, s[40:41]
	v_mov_b32_e32 v125, v124
	s_cbranch_vccnz .LBB0_175
	v_sub_f32_e32 v127, v127, v122
	v_sub_f32_e32 v126, v126, v122
	v_sub_f32_e32 v121, v133, v122
	v_sub_f32_e32 v120, v132, v122
	v_pk_mul_f32 v[134:135], v[124:125], v[126:127]
	v_mov_b32_e32 v126, v124
	v_mov_b32_e32 v127, v124
	v_pk_mul_f32 v[120:121], v[126:127], v[120:121]
	ds_read_b128 v[126:129], v238
	ds_read_b128 v[130:133], v238 offset:256
	s_waitcnt lgkmcnt(0)
	v_pk_fma_f32 v[132:133], v[120:121], v[128:129], v[132:133]
	v_pk_fma_f32 v[126:127], v[134:135], v[126:127], v[130:131]
.LBB0_175:
	v_add_u32_e32 v120, s57, v223
	v_ashrrev_i32_e32 v121, 31, v120
	v_lshlrev_b64 v[134:135], 11, v[120:121]
	v_pk_fma_f32 v[118:119], v[132:133], s[4:5], v[118:119] op_sel_hi:[1,0,1]
	v_pk_fma_f32 v[126:127], v[126:127], s[4:5], v[116:117] op_sel_hi:[1,0,1]
	v_lshl_add_u64 v[116:117], s[36:37], 0, v[134:135]
	v_lshlrev_b32_e32 v128, 16, v170
	v_and_b32_e32 v129, 0xffff0000, v170
	v_lshlrev_b32_e32 v130, 16, v171
	v_and_b32_e32 v131, 0xffff0000, v171
	v_cvt_pk_bf16_f32 v132, v126, v127
	v_cvt_pk_bf16_f32 v133, v118, v119
	v_lshl_add_u64 v[116:117], v[144:145], 1, v[116:117]
	s_and_b64 vcc, exec, s[40:41]
	global_store_dwordx2 v[116:117], v[132:133], off
	s_cbranch_vccnz .LBB0_177
	v_sub_f32_e32 v129, v129, v122
	v_sub_f32_e32 v128, v128, v122
	v_sub_f32_e32 v131, v131, v122
	v_sub_f32_e32 v130, v130, v122
	v_pk_mul_f32 v[170:171], v[124:125], v[128:129]
	v_mov_b32_e32 v128, v124
	v_mov_b32_e32 v129, v124
	v_pk_mul_f32 v[172:173], v[128:129], v[130:131]
	ds_read_b128 v[128:131], v238 offset:64
	ds_read_b128 v[132:135], v238 offset:320
	s_waitcnt lgkmcnt(0)
	v_pk_fma_f32 v[130:131], v[172:173], v[130:131], v[134:135]
	v_pk_fma_f32 v[128:129], v[170:171], v[128:129], v[132:133]
.LBB0_177:
	v_pk_fma_f32 v[114:115], v[130:131], s[4:5], v[114:115] op_sel_hi:[1,0,1]
	v_pk_fma_f32 v[112:113], v[128:129], s[4:5], v[112:113] op_sel_hi:[1,0,1]
	v_lshlrev_b32_e32 v132, 16, v168
	v_and_b32_e32 v133, 0xffff0000, v168
	v_lshlrev_b32_e32 v134, 16, v169
	v_and_b32_e32 v135, 0xffff0000, v169
	v_cvt_pk_bf16_f32 v128, v112, v113
	v_cvt_pk_bf16_f32 v129, v114, v115
	s_and_b64 vcc, exec, s[40:41]
	global_store_dwordx2 v[116:117], v[128:129], off offset:32
	s_cbranch_vccnz .LBB0_179
	v_sub_f32_e32 v131, v133, v122
	v_sub_f32_e32 v130, v132, v122
	v_sub_f32_e32 v129, v135, v122
	v_sub_f32_e32 v128, v134, v122
	v_pk_mul_f32 v[168:169], v[124:125], v[130:131]
	v_mov_b32_e32 v130, v124
	v_mov_b32_e32 v131, v124
	v_pk_mul_f32 v[170:171], v[130:131], v[128:129]
	ds_read_b128 v[128:131], v238 offset:128
	ds_read_b128 v[132:135], v238 offset:384
	s_waitcnt lgkmcnt(0)
	v_pk_fma_f32 v[134:135], v[170:171], v[130:131], v[134:135]
	v_pk_fma_f32 v[132:133], v[168:169], v[128:129], v[132:133]
.LBB0_179:
	v_pk_fma_f32 v[110:111], v[134:135], s[4:5], v[110:111] op_sel_hi:[1,0,1]
	v_pk_fma_f32 v[108:109], v[132:133], s[4:5], v[108:109] op_sel_hi:[1,0,1]
	v_lshlrev_b32_e32 v128, 16, v166
	v_and_b32_e32 v129, 0xffff0000, v166
	v_lshlrev_b32_e32 v130, 16, v167
	v_and_b32_e32 v131, 0xffff0000, v167
	v_cvt_pk_bf16_f32 v132, v108, v109
	v_cvt_pk_bf16_f32 v133, v110, v111
	s_and_b64 vcc, exec, s[40:41]
	global_store_dwordx2 v[116:117], v[132:133], off offset:256
	s_cbranch_vccnz .LBB0_181
	v_sub_f32_e32 v131, v131, v122
	v_sub_f32_e32 v130, v130, v122
	s_waitcnt lgkmcnt(0)
	v_sub_f32_e32 v123, v129, v122
	v_sub_f32_e32 v122, v128, v122
	v_pk_mul_f32 v[132:133], v[124:125], v[122:123]
	v_mov_b32_e32 v125, v124
	v_pk_mul_f32 v[134:135], v[124:125], v[130:131]
	ds_read_b128 v[122:125], v238 offset:192
	ds_read_b128 v[128:131], v238 offset:448
	s_waitcnt lgkmcnt(0)
	v_pk_fma_f32 v[130:131], v[134:135], v[124:125], v[130:131]
	v_pk_fma_f32 v[128:129], v[132:133], v[122:123], v[128:129]

; __device__ __forceinline__ float bflo(unsigned w) { return __uint_as_float(w << 16); }
; __device__ __forceinline__ float bfhi(unsigned w) { return __uint_as_float(w & 0xffff0000u); }
; __device__ __forceinline__ u32x2 pack4(const f32x4 a) { u32x2 v; v.x = cvt_pk_bf16(a[0], a[1]); v.y = cvt_pk_bf16(a[2], a[3]); return v; }
;     __device__ __forceinline__ void apply(const RowInfo& ri, const ColInfo& ci, int row, int col, f32x4 a, f32x4 pv, float& s1, float& s2) const {
;         f32x4 h = pv;
;         if (!ident) { const f32x4 gg = *(const f32x4*)(g + col), bb = *(const f32x4*)(b + col); h = (pv - ri.mu) * ri.rstd * gg + bb; }
;         const f32x4 v = h * ALPHA + a;
;         *(u32x2*)(xb + (size_t)row * DM + col) = pack4(v);
;         s1 += (v[0] + v[1]) + (v[2] + v[3]); s2 += (v[0] * v[0] + v[1] * v[1]) + (v[2] * v[2] + v[3] * v[3]);
;     }
; template <class Epi>
; __device__ __forceinline__ void gemm_phase(LAS unsigned char* lds, const bf16_t* Ag, const bf16_t* Btg, const int K, const int nM, const int nN, const Epi& E) {
;     ...
;                 f32x4 pv[2][2];
; #pragma unroll
;                 for (int bj = 0; bj < 2; ++bj)
; #pragma unroll
;                     for (int n = 0; n < 2; ++n) { const u32x2 w = pk[m][bj][n]; pv[bj][n] = (f32x4){bflo(w.x), bfhi(w.x), bflo(w.y), bfhi(w.y)}; }
;                 const RowInfo ri = E.rowinfo(row, lrow, par, lds);
;                 float s1 = 0.f, s2 = 0.f;
; #pragma unroll
;                 for (int bj = 0; bj < 2; ++bj)
; #pragma unroll
;                     for (int n = 0; n < 2; ++n) E.apply(ri, ci[bj][n], row, pn * 256 + bj * 128 + wc * 32 + n * 16 + fq * 4, acc[ai][bj][m][n], pv[bj][n], s1, s2);
.LBB0_186:
	v_lshlrev_b32_e32 v110, 16, v164
	v_and_b32_e32 v111, 0xffff0000, v164
	v_lshlrev_b32_e32 v116, 16, v165
	v_and_b32_e32 v117, 0xffff0000, v165
	s_and_b64 vcc, exec, s[40:41]
	v_mov_b32_e32 v109, v108
	s_cbranch_vccnz .LBB0_188
	v_sub_f32_e32 v111, v111, v106
	v_sub_f32_e32 v110, v110, v106
	v_sub_f32_e32 v105, v117, v106
	v_sub_f32_e32 v104, v116, v106
	v_pk_mul_f32 v[118:119], v[108:109], v[110:111]
	v_mov_b32_e32 v110, v108
	v_mov_b32_e32 v111, v108
	v_pk_mul_f32 v[104:105], v[110:111], v[104:105]
	ds_read_b128 v[110:113], v238
	ds_read_b128 v[114:117], v238 offset:256
	s_waitcnt lgkmcnt(0)
	v_pk_fma_f32 v[116:117], v[104:105], v[112:113], v[116:117]
	v_pk_fma_f32 v[110:111], v[118:119], v[110:111], v[114:115]
.LBB0_188:
	v_add_u32_e32 v104, s57, v224
	v_ashrrev_i32_e32 v105, 31, v104
	v_lshlrev_b64 v[118:119], 11, v[104:105]
	v_pk_fma_f32 v[102:103], v[116:117], s[4:5], v[102:103] op_sel_hi:[1,0,1]
	v_pk_fma_f32 v[110:111], v[110:111], s[4:5], v[100:101] op_sel_hi:[1,0,1]
	v_lshl_add_u64 v[100:101], s[36:37], 0, v[118:119]
	v_lshlrev_b32_e32 v112, 16, v162
	v_and_b32_e32 v113, 0xffff0000, v162
	v_lshlrev_b32_e32 v114, 16, v163
	v_and_b32_e32 v115, 0xffff0000, v163
	v_cvt_pk_bf16_f32 v116, v110, v111
	v_cvt_pk_bf16_f32 v117, v102, v103
	v_lshl_add_u64 v[100:101], v[144:145], 1, v[100:101]
	s_and_b64 vcc, exec, s[40:41]
	global_store_dwordx2 v[100:101], v[116:117], off
	s_cbranch_vccnz .LBB0_190
	v_sub_f32_e32 v113, v113, v106
	v_sub_f32_e32 v112, v112, v106
	v_sub_f32_e32 v115, v115, v106
	v_sub_f32_e32 v114, v114, v106
	v_pk_mul_f32 v[120:121], v[108:109], v[112:113]
	v_mov_b32_e32 v112, v108
	v_mov_b32_e32 v113, v108
	v_pk_mul_f32 v[122:123], v[112:113], v[114:115]
	ds_read_b128 v[112:115], v238 offset:64
	ds_read_b128 v[116:119], v238 offset:320
	s_waitcnt lgkmcnt(0)
	v_pk_fma_f32 v[114:115], v[122:123], v[114:115], v[118:119]
	v_pk_fma_f32 v[112:113], v[120:121], v[112:113], v[116:117]
.LBB0_190:
	v_pk_fma_f32 v[98:99], v[114:115], s[4:5], v[98:99] op_sel_hi:[1,0,1]
	v_pk_fma_f32 v[96:97], v[112:113], s[4:5], v[96:97] op_sel_hi:[1,0,1]
	v_lshlrev_b32_e32 v116, 16, v160
	v_and_b32_e32 v117, 0xffff0000, v160
	v_lshlrev_b32_e32 v118, 16, v161
	v_and_b32_e32 v119, 0xffff0000, v161
	v_cvt_pk_bf16_f32 v112, v96, v97
	v_cvt_pk_bf16_f32 v113, v98, v99
	s_and_b64 vcc, exec, s[40:41]
	global_store_dwordx2 v[100:101], v[112:113], off offset:32
	s_cbranch_vccnz .LBB0_192
	v_sub_f32_e32 v115, v117, v106
	v_sub_f32_e32 v114, v116, v106
	v_sub_f32_e32 v113, v119, v106
	v_sub_f32_e32 v112, v118, v106
	v_pk_mul_f32 v[120:121], v[108:109], v[114:115]
	v_mov_b32_e32 v114, v108
	v_mov_b32_e32 v115, v108
	v_pk_mul_f32 v[122:123], v[114:115], v[112:113]
	ds_read_b128 v[112:115], v238 offset:128
	ds_read_b128 v[116:119], v238 offset:384
	s_waitcnt lgkmcnt(0)
	v_pk_fma_f32 v[118:119], v[122:123], v[114:115], v[118:119]
	v_pk_fma_f32 v[116:117], v[120:121], v[112:113], v[116:117]
.LBB0_192:
	v_pk_fma_f32 v[94:95], v[118:119], s[4:5], v[94:95] op_sel_hi:[1,0,1]
	v_pk_fma_f32 v[92:93], v[116:117], s[4:5], v[92:93] op_sel_hi:[1,0,1]
	v_lshlrev_b32_e32 v112, 16, v158
	v_and_b32_e32 v113, 0xffff0000, v158
	v_lshlrev_b32_e32 v114, 16, v159
	v_and_b32_e32 v115, 0xffff0000, v159
	v_cvt_pk_bf16_f32 v116, v92, v93
	v_cvt_pk_bf16_f32 v117, v94, v95
	s_and_b64 vcc, exec, s[40:41]
	global_store_dwordx2 v[100:101], v[116:117], off offset:256
	s_cbranch_vccnz .LBB0_194
	v_sub_f32_e32 v115, v115, v106
	v_sub_f32_e32 v114, v114, v106
	s_waitcnt lgkmcnt(0)
	v_sub_f32_e32 v107, v113, v106
	v_sub_f32_e32 v106, v112, v106
	v_pk_mul_f32 v[116:117], v[108:109], v[106:107]
	v_mov_b32_e32 v109, v108
	v_pk_mul_f32 v[118:119], v[108:109], v[114:115]
	ds_read_b128 v[106:109], v238 offset:192
	ds_read_b128 v[112:115], v238 offset:448
	s_waitcnt lgkmcnt(0)
	v_pk_fma_f32 v[114:115], v[118:119], v[108:109], v[114:115]
	v_pk_fma_f32 v[112:113], v[116:117], v[106:107], v[112:113]

; __device__ __forceinline__ float bflo(unsigned w) { return __uint_as_float(w << 16); }
; __device__ __forceinline__ float bfhi(unsigned w) { return __uint_as_float(w & 0xffff0000u); }
; __device__ __forceinline__ u32x2 pack4(const f32x4 a) { u32x2 v; v.x = cvt_pk_bf16(a[0], a[1]); v.y = cvt_pk_bf16(a[2], a[3]); return v; }
;     __device__ __forceinline__ void apply(const RowInfo& ri, const ColInfo& ci, int row, int col, f32x4 a, f32x4 pv, float& s1, float& s2) const {
;         f32x4 h = pv;
;         if (!ident) { const f32x4 gg = *(const f32x4*)(g + col), bb = *(const f32x4*)(b + col); h = (pv - ri.mu) * ri.rstd * gg + bb; }
;         const f32x4 v = h * ALPHA + a;
;         *(u32x2*)(xb + (size_t)row * DM + col) = pack4(v);
;         s1 += (v[0] + v[1]) + (v[2] + v[3]); s2 += (v[0] * v[0] + v[1] * v[1]) + (v[2] * v[2] + v[3] * v[3]);
;     }
; template <class Epi>
; __device__ __forceinline__ void gemm_phase(LAS unsigned char* lds, const bf16_t* Ag, const bf16_t* Btg, const int K, const int nM, const int nN, const Epi& E) {
;     ...
;                 f32x4 pv[2][2];
; #pragma unroll
;                 for (int bj = 0; bj < 2; ++bj)
; #pragma unroll
;                     for (int n = 0; n < 2; ++n) { const u32x2 w = pk[m][bj][n]; pv[bj][n] = (f32x4){bflo(w.x), bfhi(w.x), bflo(w.y), bfhi(w.y)}; }
;                 const RowInfo ri = E.rowinfo(row, lrow, par, lds);
;                 float s1 = 0.f, s2 = 0.f;
; #pragma unroll
;                 for (int bj = 0; bj < 2; ++bj)
; #pragma unroll
;                     for (int n = 0; n < 2; ++n) E.apply(ri, ci[bj][n], row, pn * 256 + bj * 128 + wc * 32 + n * 16 + fq * 4, acc[ai][bj][m][n], pv[bj][n], s1, s2);
.LBB0_199:
	v_lshlrev_b32_e32 v94, 16, v156
	v_and_b32_e32 v95, 0xffff0000, v156
	v_lshlrev_b32_e32 v100, 16, v157
	v_and_b32_e32 v101, 0xffff0000, v157
	s_and_b64 vcc, exec, s[40:41]
	v_mov_b32_e32 v93, v92
	s_cbranch_vccnz .LBB0_201
	v_sub_f32_e32 v95, v95, v90
	v_sub_f32_e32 v94, v94, v90
	v_sub_f32_e32 v89, v101, v90
	v_sub_f32_e32 v88, v100, v90
	v_pk_mul_f32 v[102:103], v[92:93], v[94:95]
	v_mov_b32_e32 v94, v92
	v_mov_b32_e32 v95, v92
	v_pk_mul_f32 v[88:89], v[94:95], v[88:89]
	ds_read_b128 v[94:97], v238
	ds_read_b128 v[98:101], v238 offset:256
	s_waitcnt lgkmcnt(0)
	v_pk_fma_f32 v[100:101], v[88:89], v[96:97], v[100:101]
	v_pk_fma_f32 v[94:95], v[102:103], v[94:95], v[98:99]
.LBB0_201:
	v_add_u32_e32 v88, s57, v225
	v_ashrrev_i32_e32 v89, 31, v88
	v_lshlrev_b64 v[102:103], 11, v[88:89]
	v_pk_fma_f32 v[86:87], v[100:101], s[4:5], v[86:87] op_sel_hi:[1,0,1]
	v_pk_fma_f32 v[94:95], v[94:95], s[4:5], v[84:85] op_sel_hi:[1,0,1]
	v_lshl_add_u64 v[84:85], s[36:37], 0, v[102:103]
	v_lshlrev_b32_e32 v96, 16, v154
	v_and_b32_e32 v97, 0xffff0000, v154
	v_lshlrev_b32_e32 v98, 16, v155
	v_and_b32_e32 v99, 0xffff0000, v155
	v_cvt_pk_bf16_f32 v100, v94, v95
	v_cvt_pk_bf16_f32 v101, v86, v87
	v_lshl_add_u64 v[84:85], v[144:145], 1, v[84:85]
	s_and_b64 vcc, exec, s[40:41]
	global_store_dwordx2 v[84:85], v[100:101], off
	s_cbranch_vccnz .LBB0_203
	v_sub_f32_e32 v97, v97, v90
	v_sub_f32_e32 v96, v96, v90
	v_sub_f32_e32 v99, v99, v90
	v_sub_f32_e32 v98, v98, v90
	v_pk_mul_f32 v[104:105], v[92:93], v[96:97]
	v_mov_b32_e32 v96, v92
	v_mov_b32_e32 v97, v92
	v_pk_mul_f32 v[106:107], v[96:97], v[98:99]
	ds_read_b128 v[96:99], v238 offset:64
	ds_read_b128 v[100:103], v238 offset:320
	s_waitcnt lgkmcnt(0)
	v_pk_fma_f32 v[98:99], v[106:107], v[98:99], v[102:103]
	v_pk_fma_f32 v[96:97], v[104:105], v[96:97], v[100:101]
.LBB0_203:
	v_pk_fma_f32 v[82:83], v[98:99], s[4:5], v[82:83] op_sel_hi:[1,0,1]
	v_pk_fma_f32 v[80:81], v[96:97], s[4:5], v[80:81] op_sel_hi:[1,0,1]
	v_lshlrev_b32_e32 v100, 16, v152
	v_and_b32_e32 v101, 0xffff0000, v152
	v_lshlrev_b32_e32 v102, 16, v153
	v_and_b32_e32 v103, 0xffff0000, v153
	v_cvt_pk_bf16_f32 v96, v80, v81
	v_cvt_pk_bf16_f32 v97, v82, v83
	s_and_b64 vcc, exec, s[40:41]
	global_store_dwordx2 v[84:85], v[96:97], off offset:32
	s_cbranch_vccnz .LBB0_205
	v_sub_f32_e32 v99, v101, v90
	v_sub_f32_e32 v98, v100, v90
	v_sub_f32_e32 v97, v103, v90
	v_sub_f32_e32 v96, v102, v90
	v_pk_mul_f32 v[104:105], v[92:93], v[98:99]
	v_mov_b32_e32 v98, v92
	v_mov_b32_e32 v99, v92
	v_pk_mul_f32 v[106:107], v[98:99], v[96:97]
	ds_read_b128 v[96:99], v238 offset:128
	ds_read_b128 v[100:103], v238 offset:384
	s_waitcnt lgkmcnt(0)
	v_pk_fma_f32 v[102:103], v[106:107], v[98:99], v[102:103]
	v_pk_fma_f32 v[100:101], v[104:105], v[96:97], v[100:101]
.LBB0_205:
	v_pk_fma_f32 v[78:79], v[102:103], s[4:5], v[78:79] op_sel_hi:[1,0,1]
	v_pk_fma_f32 v[76:77], v[100:101], s[4:5], v[76:77] op_sel_hi:[1,0,1]
	v_lshlrev_b32_e32 v96, 16, v150
	v_and_b32_e32 v97, 0xffff0000, v150
	v_lshlrev_b32_e32 v98, 16, v151
	v_and_b32_e32 v99, 0xffff0000, v151
	v_cvt_pk_bf16_f32 v100, v76, v77
	v_cvt_pk_bf16_f32 v101, v78, v79
	s_and_b64 vcc, exec, s[40:41]
	global_store_dwordx2 v[84:85], v[100:101], off offset:256
	s_cbranch_vccnz .LBB0_207
	v_sub_f32_e32 v99, v99, v90
	v_sub_f32_e32 v98, v98, v90
	s_waitcnt lgkmcnt(0)
	v_sub_f32_e32 v91, v97, v90
	v_sub_f32_e32 v90, v96, v90
	v_pk_mul_f32 v[100:101], v[92:93], v[90:91]
	v_mov_b32_e32 v93, v92
	v_pk_mul_f32 v[102:103], v[92:93], v[98:99]
	ds_read_b128 v[90:93], v238 offset:192
	ds_read_b128 v[96:99], v238 offset:448
	s_waitcnt lgkmcnt(0)
	v_pk_fma_f32 v[98:99], v[102:103], v[92:93], v[98:99]
	v_pk_fma_f32 v[96:97], v[100:101], v[90:91], v[96:97]

; __device__ __forceinline__ float bflo(unsigned w) { return __uint_as_float(w << 16); }
; __device__ __forceinline__ float bfhi(unsigned w) { return __uint_as_float(w & 0xffff0000u); }
; __device__ __forceinline__ u32x2 pack4(const f32x4 a) { u32x2 v; v.x = cvt_pk_bf16(a[0], a[1]); v.y = cvt_pk_bf16(a[2], a[3]); return v; }
; __device__ __forceinline__ int prow0(int pm) { return (pm >> 4) * LP + PADR + (pm & 15) * 256; }
;     __device__ __forceinline__ u32x2 preload_pk(int row, int col) const { return (u32x2){0u, 0u}; }
;     __device__ __forceinline__ u32x2 preload_pk(int row, int col) const { return (u32x2){0u, 0u}; }
;     __device__ __forceinline__ void apply(const RowInfo& ri, const ColInfo& ci, int row, int col, f32x4 a, f32x4 pv, float& s1, float& s2) const {
;         f32x4 h = pv;
;         if (!ident) { const f32x4 gg = *(const f32x4*)(g + col), bb = *(const f32x4*)(b + col); h = (pv - ri.mu) * ri.rstd * gg + bb; }
;         const f32x4 v = h * ALPHA + a;
;         *(u32x2*)(xb + (size_t)row * DM + col) = pack4(v);
;         s1 += (v[0] + v[1]) + (v[2] + v[3]); s2 += (v[0] * v[0] + v[1] * v[1]) + (v[2] * v[2] + v[3] * v[3]);
;     }
; template <class Epi>
; __device__ __forceinline__ void gemm_phase(LAS unsigned char* lds, const bf16_t* Ag, const bf16_t* Btg, const int K, const int nM, const int nN, const Epi& E) {
;     ...
;                 if (Epi::PRELOAD && m == 0) {
; #pragma unroll
;                     for (int g2 = 0; g2 < 4; ++g2)
; #pragma unroll
;                         for (int bj = 0; bj < 2; ++bj)
; #pragma unroll
;                             for (int n = 0; n < 2; ++n) pk[g2][bj][n] = E.preload_pk(prow0(pm) + ai * 128 + wr * 64 + g2 * 16 + fr, pn * 256 + bj * 128 + wc * 32 + n * 16 + fq * 4);
;                 }
;                 f32x4 pv[2][2];
; #pragma unroll
;                 for (int bj = 0; bj < 2; ++bj)
; #pragma unroll
;                     for (int n = 0; n < 2; ++n) { const u32x2 w = pk[m][bj][n]; pv[bj][n] = (f32x4){bflo(w.x), bfhi(w.x), bflo(w.y), bfhi(w.y)}; }
;                 const RowInfo ri = E.rowinfo(row, lrow, par, lds);
;                 float s1 = 0.f, s2 = 0.f;
; #pragma unroll
;                 for (int bj = 0; bj < 2; ++bj)
; #pragma unroll
;                     for (int n = 0; n < 2; ++n) E.apply(ri, ci[bj][n], row, pn * 256 + bj * 128 + wc * 32 + n * 16 + fq * 4, acc[ai][bj][m][n], pv[bj][n], s1, s2);
.LBB0_212:
	s_waitcnt vmcnt(0)
	v_lshlrev_b32_e32 v110, 16, v108
	v_and_b32_e32 v111, 0xffff0000, v108
	v_lshlrev_b32_e32 v114, 16, v109
	v_and_b32_e32 v115, 0xffff0000, v109
	s_and_b64 vcc, exec, s[40:41]
	v_mov_b32_e32 v101, v100
	s_cbranch_vccnz .LBB0_214
	v_sub_f32_e32 v111, v111, v98
	v_sub_f32_e32 v110, v110, v98
	v_sub_f32_e32 v109, v115, v98
	v_sub_f32_e32 v108, v114, v98
	v_pk_mul_f32 v[116:117], v[100:101], v[110:111]
	v_mov_b32_e32 v110, v100
	v_mov_b32_e32 v111, v100
	v_pk_mul_f32 v[118:119], v[110:111], v[108:109]
	ds_read_b128 v[108:111], v238
	ds_read_b128 v[112:115], v238 offset:256
	s_waitcnt lgkmcnt(0)
	v_pk_fma_f32 v[114:115], v[118:119], v[110:111], v[114:115]
	v_pk_fma_f32 v[110:111], v[116:117], v[108:109], v[112:113]
.LBB0_214:
	v_pk_fma_f32 v[70:71], v[114:115], s[4:5], v[70:71] op_sel_hi:[1,0,1]
	v_pk_fma_f32 v[68:69], v[110:111], s[4:5], v[68:69] op_sel_hi:[1,0,1]
	v_lshlrev_b32_e32 v108, 16, v106
	v_and_b32_e32 v109, 0xffff0000, v106
	v_lshlrev_b32_e32 v112, 16, v107
	v_and_b32_e32 v113, 0xffff0000, v107
	v_cvt_pk_bf16_f32 v106, v68, v69
	v_cvt_pk_bf16_f32 v107, v70, v71
	s_and_b64 vcc, exec, s[40:41]
	global_store_dwordx2 v[96:97], v[106:107], off
	s_cbranch_vccnz .LBB0_216
	v_sub_f32_e32 v109, v109, v98
	v_sub_f32_e32 v108, v108, v98
	v_sub_f32_e32 v107, v113, v98
	v_sub_f32_e32 v106, v112, v98
	v_pk_mul_f32 v[114:115], v[100:101], v[108:109]
	v_mov_b32_e32 v108, v100
	v_mov_b32_e32 v109, v100
	v_pk_mul_f32 v[116:117], v[108:109], v[106:107]
	ds_read_b128 v[106:109], v238 offset:64
	ds_read_b128 v[110:113], v238 offset:320
	s_waitcnt lgkmcnt(0)
	v_pk_fma_f32 v[112:113], v[116:117], v[108:109], v[112:113]
	v_pk_fma_f32 v[108:109], v[114:115], v[106:107], v[110:111]
.LBB0_216:
	v_pk_fma_f32 v[66:67], v[112:113], s[4:5], v[66:67] op_sel_hi:[1,0,1]
	v_pk_fma_f32 v[64:65], v[108:109], s[4:5], v[64:65] op_sel_hi:[1,0,1]
	v_lshlrev_b32_e32 v106, 16, v104
	v_and_b32_e32 v107, 0xffff0000, v104
	v_lshlrev_b32_e32 v110, 16, v105
	v_and_b32_e32 v111, 0xffff0000, v105
	v_cvt_pk_bf16_f32 v104, v64, v65
	v_cvt_pk_bf16_f32 v105, v66, v67
	s_and_b64 vcc, exec, s[40:41]
	global_store_dwordx2 v[96:97], v[104:105], off offset:32
	s_cbranch_vccnz .LBB0_218
	v_sub_f32_e32 v107, v107, v98
	v_sub_f32_e32 v106, v106, v98
	v_sub_f32_e32 v105, v111, v98
	v_sub_f32_e32 v104, v110, v98
	v_pk_mul_f32 v[112:113], v[100:101], v[106:107]
	v_mov_b32_e32 v106, v100
	v_mov_b32_e32 v107, v100
	v_pk_mul_f32 v[114:115], v[106:107], v[104:105]
	ds_read_b128 v[104:107], v238 offset:128
	ds_read_b128 v[108:111], v238 offset:384
	s_waitcnt lgkmcnt(0)
	v_pk_fma_f32 v[110:111], v[114:115], v[106:107], v[110:111]
	v_pk_fma_f32 v[106:107], v[112:113], v[104:105], v[108:109]
.LBB0_218:
	v_pk_fma_f32 v[62:63], v[110:111], s[4:5], v[62:63] op_sel_hi:[1,0,1]
	v_pk_fma_f32 v[60:61], v[106:107], s[4:5], v[60:61] op_sel_hi:[1,0,1]
	v_lshlrev_b32_e32 v104, 16, v102
	v_and_b32_e32 v105, 0xffff0000, v102
	v_lshlrev_b32_e32 v102, 16, v103
	v_and_b32_e32 v103, 0xffff0000, v103
	v_cvt_pk_bf16_f32 v106, v60, v61
	v_cvt_pk_bf16_f32 v107, v62, v63
	s_and_b64 vcc, exec, s[40:41]
	global_store_dwordx2 v[96:97], v[106:107], off offset:256
	s_cbranch_vccnz .LBB0_220
	v_sub_f32_e32 v103, v103, v98
	v_sub_f32_e32 v102, v102, v98
	v_sub_f32_e32 v99, v105, v98
	v_sub_f32_e32 v98, v104, v98
	v_pk_mul_f32 v[108:109], v[100:101], v[98:99]
	v_mov_b32_e32 v101, v100
	v_pk_mul_f32 v[102:103], v[100:101], v[102:103]
	ds_read_b128 v[98:101], v238 offset:192
	ds_read_b128 v[104:107], v238 offset:448
	s_waitcnt lgkmcnt(0)
	v_pk_fma_f32 v[102:103], v[102:103], v[100:101], v[106:107]
	v_pk_fma_f32 v[104:105], v[108:109], v[98:99], v[104:105]

; __device__ __forceinline__ float bflo(unsigned w) { return __uint_as_float(w << 16); }
; __device__ __forceinline__ float bfhi(unsigned w) { return __uint_as_float(w & 0xffff0000u); }
; __device__ __forceinline__ u32x2 pack4(const f32x4 a) { u32x2 v; v.x = cvt_pk_bf16(a[0], a[1]); v.y = cvt_pk_bf16(a[2], a[3]); return v; }
;     __device__ __forceinline__ void apply(const RowInfo& ri, const ColInfo& ci, int row, int col, f32x4 a, f32x4 pv, float& s1, float& s2) const {
;         f32x4 h = pv;
;         if (!ident) { const f32x4 gg = *(const f32x4*)(g + col), bb = *(const f32x4*)(b + col); h = (pv - ri.mu) * ri.rstd * gg + bb; }
;         const f32x4 v = h * ALPHA + a;
;         *(u32x2*)(xb + (size_t)row * DM + col) = pack4(v);
;         s1 += (v[0] + v[1]) + (v[2] + v[3]); s2 += (v[0] * v[0] + v[1] * v[1]) + (v[2] * v[2] + v[3] * v[3]);
; template <class Epi>
; __device__ __forceinline__ void gemm_phase(LAS unsigned char* lds, const bf16_t* Ag, const bf16_t* Btg, const int K, const int nM, const int nN, const Epi& E) {
;     ...
;                 f32x4 pv[2][2];
; #pragma unroll
;                 for (int bj = 0; bj < 2; ++bj)
; #pragma unroll
;                     for (int n = 0; n < 2; ++n) { const u32x2 w = pk[m][bj][n]; pv[bj][n] = (f32x4){bflo(w.x), bfhi(w.x), bflo(w.y), bfhi(w.y)}; }
;                 const RowInfo ri = E.rowinfo(row, lrow, par, lds);
;                 float s1 = 0.f, s2 = 0.f;
; #pragma unroll
;                 for (int bj = 0; bj < 2; ++bj)
; #pragma unroll
;                     for (int n = 0; n < 2; ++n) E.apply(ri, ci[bj][n], row, pn * 256 + bj * 128 + wc * 32 + n * 16 + fq * 4, acc[ai][bj][m][n], pv[bj][n], s1, s2);
.LBB0_225:
	v_lshlrev_b32_e32 v62, 16, v94
	v_and_b32_e32 v63, 0xffff0000, v94
	v_lshlrev_b32_e32 v68, 16, v95
	v_and_b32_e32 v69, 0xffff0000, v95
	s_and_b64 vcc, exec, s[40:41]
	v_mov_b32_e32 v61, v60
	s_cbranch_vccnz .LBB0_227
	v_sub_f32_e32 v63, v63, v58
	v_sub_f32_e32 v62, v62, v58
	v_sub_f32_e32 v57, v69, v58
	v_sub_f32_e32 v56, v68, v58
	v_pk_mul_f32 v[70:71], v[60:61], v[62:63]
	v_mov_b32_e32 v62, v60
	v_mov_b32_e32 v63, v60
	v_pk_mul_f32 v[56:57], v[62:63], v[56:57]
	ds_read_b128 v[62:65], v238
	ds_read_b128 v[66:69], v238 offset:256
	s_waitcnt lgkmcnt(0)
	v_pk_fma_f32 v[68:69], v[56:57], v[64:65], v[68:69]
	v_pk_fma_f32 v[62:63], v[70:71], v[62:63], v[66:67]
.LBB0_227:
	v_add_u32_e32 v56, s57, v227
	v_ashrrev_i32_e32 v57, 31, v56
	v_lshlrev_b64 v[70:71], 11, v[56:57]
	v_pk_fma_f32 v[54:55], v[68:69], s[4:5], v[54:55] op_sel_hi:[1,0,1]
	v_pk_fma_f32 v[62:63], v[62:63], s[4:5], v[52:53] op_sel_hi:[1,0,1]
	v_lshl_add_u64 v[52:53], s[36:37], 0, v[70:71]
	v_lshlrev_b32_e32 v64, 16, v92
	v_and_b32_e32 v65, 0xffff0000, v92
	v_lshlrev_b32_e32 v66, 16, v93
	v_and_b32_e32 v67, 0xffff0000, v93
	v_cvt_pk_bf16_f32 v68, v62, v63
	v_cvt_pk_bf16_f32 v69, v54, v55
	v_lshl_add_u64 v[52:53], v[144:145], 1, v[52:53]
	s_and_b64 vcc, exec, s[40:41]
	global_store_dwordx2 v[52:53], v[68:69], off
	s_cbranch_vccnz .LBB0_229
	v_sub_f32_e32 v65, v65, v58
	v_sub_f32_e32 v64, v64, v58
	v_sub_f32_e32 v67, v67, v58
	v_sub_f32_e32 v66, v66, v58
	v_pk_mul_f32 v[92:93], v[60:61], v[64:65]
	v_mov_b32_e32 v64, v60
	v_mov_b32_e32 v65, v60
	v_pk_mul_f32 v[94:95], v[64:65], v[66:67]
	ds_read_b128 v[64:67], v238 offset:64
	ds_read_b128 v[68:71], v238 offset:320
	s_waitcnt lgkmcnt(0)
	v_pk_fma_f32 v[66:67], v[94:95], v[66:67], v[70:71]
	v_pk_fma_f32 v[64:65], v[92:93], v[64:65], v[68:69]
.LBB0_229:
	v_pk_fma_f32 v[50:51], v[66:67], s[4:5], v[50:51] op_sel_hi:[1,0,1]
	v_pk_fma_f32 v[48:49], v[64:65], s[4:5], v[48:49] op_sel_hi:[1,0,1]
	v_lshlrev_b32_e32 v68, 16, v90
	v_and_b32_e32 v69, 0xffff0000, v90
	v_lshlrev_b32_e32 v70, 16, v91
	v_and_b32_e32 v71, 0xffff0000, v91
	v_cvt_pk_bf16_f32 v64, v48, v49
	v_cvt_pk_bf16_f32 v65, v50, v51
	s_and_b64 vcc, exec, s[40:41]
	global_store_dwordx2 v[52:53], v[64:65], off offset:32
	s_cbranch_vccnz .LBB0_231
	v_sub_f32_e32 v67, v69, v58
	v_sub_f32_e32 v66, v68, v58
	v_sub_f32_e32 v65, v71, v58
	v_sub_f32_e32 v64, v70, v58
	v_pk_mul_f32 v[90:91], v[60:61], v[66:67]
	v_mov_b32_e32 v66, v60
	v_mov_b32_e32 v67, v60
	v_pk_mul_f32 v[92:93], v[66:67], v[64:65]
	ds_read_b128 v[64:67], v238 offset:128
	ds_read_b128 v[68:71], v238 offset:384
	s_waitcnt lgkmcnt(0)
	v_pk_fma_f32 v[70:71], v[92:93], v[66:67], v[70:71]
	v_pk_fma_f32 v[68:69], v[90:91], v[64:65], v[68:69]
.LBB0_231:
	v_pk_fma_f32 v[46:47], v[70:71], s[4:5], v[46:47] op_sel_hi:[1,0,1]
	v_pk_fma_f32 v[44:45], v[68:69], s[4:5], v[44:45] op_sel_hi:[1,0,1]
	v_lshlrev_b32_e32 v64, 16, v88
	v_and_b32_e32 v65, 0xffff0000, v88
	v_lshlrev_b32_e32 v66, 16, v89
	v_and_b32_e32 v67, 0xffff0000, v89
	v_cvt_pk_bf16_f32 v68, v44, v45
	v_cvt_pk_bf16_f32 v69, v46, v47
	s_and_b64 vcc, exec, s[40:41]
	global_store_dwordx2 v[52:53], v[68:69], off offset:256
	s_cbranch_vccnz .LBB0_233
	v_sub_f32_e32 v67, v67, v58
	v_sub_f32_e32 v66, v66, v58
	s_waitcnt lgkmcnt(0)
	v_sub_f32_e32 v59, v65, v58
	v_sub_f32_e32 v58, v64, v58
	v_pk_mul_f32 v[68:69], v[60:61], v[58:59]
	v_mov_b32_e32 v61, v60
	v_pk_mul_f32 v[70:71], v[60:61], v[66:67]
	ds_read_b128 v[58:61], v238 offset:192
	ds_read_b128 v[64:67], v238 offset:448
	s_waitcnt lgkmcnt(0)
	v_pk_fma_f32 v[66:67], v[70:71], v[60:61], v[66:67]
	v_pk_fma_f32 v[64:65], v[68:69], v[58:59], v[64:65]

; __device__ __forceinline__ float bflo(unsigned w) { return __uint_as_float(w << 16); }
; __device__ __forceinline__ float bfhi(unsigned w) { return __uint_as_float(w & 0xffff0000u); }
; __device__ __forceinline__ u32x2 pack4(const f32x4 a) { u32x2 v; v.x = cvt_pk_bf16(a[0], a[1]); v.y = cvt_pk_bf16(a[2], a[3]); return v; }
;     __device__ __forceinline__ void apply(const RowInfo& ri, const ColInfo& ci, int row, int col, f32x4 a, f32x4 pv, float& s1, float& s2) const {
;         f32x4 h = pv;
;         if (!ident) { const f32x4 gg = *(const f32x4*)(g + col), bb = *(const f32x4*)(b + col); h = (pv - ri.mu) * ri.rstd * gg + bb; }
;         const f32x4 v = h * ALPHA + a;
;         *(u32x2*)(xb + (size_t)row * DM + col) = pack4(v);
;         s1 += (v[0] + v[1]) + (v[2] + v[3]); s2 += (v[0] * v[0] + v[1] * v[1]) + (v[2] * v[2] + v[3] * v[3]);
; template <class Epi>
; __device__ __forceinline__ void gemm_phase(LAS unsigned char* lds, const bf16_t* Ag, const bf16_t* Btg, const int K, const int nM, const int nN, const Epi& E) {
;     ...
;                 f32x4 pv[2][2];
; #pragma unroll
;                 for (int bj = 0; bj < 2; ++bj)
; #pragma unroll
;                     for (int n = 0; n < 2; ++n) { const u32x2 w = pk[m][bj][n]; pv[bj][n] = (f32x4){bflo(w.x), bfhi(w.x), bflo(w.y), bfhi(w.y)}; }
;                 const RowInfo ri = E.rowinfo(row, lrow, par, lds);
;                 float s1 = 0.f, s2 = 0.f;
; #pragma unroll
;                 for (int bj = 0; bj < 2; ++bj)
; #pragma unroll
;                     for (int n = 0; n < 2; ++n) E.apply(ri, ci[bj][n], row, pn * 256 + bj * 128 + wc * 32 + n * 16 + fq * 4, acc[ai][bj][m][n], pv[bj][n], s1, s2);
.LBB0_238:
	v_lshlrev_b32_e32 v46, 16, v86
	v_and_b32_e32 v47, 0xffff0000, v86
	v_lshlrev_b32_e32 v52, 16, v87
	v_and_b32_e32 v53, 0xffff0000, v87
	s_and_b64 vcc, exec, s[40:41]
	v_mov_b32_e32 v45, v44
	s_cbranch_vccnz .LBB0_240
	v_sub_f32_e32 v47, v47, v42
	v_sub_f32_e32 v46, v46, v42
	v_sub_f32_e32 v41, v53, v42
	v_sub_f32_e32 v40, v52, v42
	v_pk_mul_f32 v[54:55], v[44:45], v[46:47]
	v_mov_b32_e32 v46, v44
	v_mov_b32_e32 v47, v44
	v_pk_mul_f32 v[40:41], v[46:47], v[40:41]
	ds_read_b128 v[46:49], v238
	ds_read_b128 v[50:53], v238 offset:256
	s_waitcnt lgkmcnt(0)
	v_pk_fma_f32 v[52:53], v[40:41], v[48:49], v[52:53]
	v_pk_fma_f32 v[46:47], v[54:55], v[46:47], v[50:51]
.LBB0_240:
	v_add_u32_e32 v40, s57, v228
	v_ashrrev_i32_e32 v41, 31, v40
	v_lshlrev_b64 v[54:55], 11, v[40:41]
	v_pk_fma_f32 v[38:39], v[52:53], s[4:5], v[38:39] op_sel_hi:[1,0,1]
	v_pk_fma_f32 v[46:47], v[46:47], s[4:5], v[36:37] op_sel_hi:[1,0,1]
	v_lshl_add_u64 v[36:37], s[36:37], 0, v[54:55]
	v_lshlrev_b32_e32 v48, 16, v84
	v_and_b32_e32 v49, 0xffff0000, v84
	v_lshlrev_b32_e32 v50, 16, v85
	v_and_b32_e32 v51, 0xffff0000, v85
	v_cvt_pk_bf16_f32 v52, v46, v47
	v_cvt_pk_bf16_f32 v53, v38, v39
	v_lshl_add_u64 v[36:37], v[144:145], 1, v[36:37]
	s_and_b64 vcc, exec, s[40:41]
	global_store_dwordx2 v[36:37], v[52:53], off
	s_cbranch_vccnz .LBB0_242
	v_sub_f32_e32 v49, v49, v42
	v_sub_f32_e32 v48, v48, v42
	v_sub_f32_e32 v51, v51, v42
	v_sub_f32_e32 v50, v50, v42
	v_pk_mul_f32 v[56:57], v[44:45], v[48:49]
	v_mov_b32_e32 v48, v44
	v_mov_b32_e32 v49, v44
	v_pk_mul_f32 v[58:59], v[48:49], v[50:51]
	ds_read_b128 v[48:51], v238 offset:64
	ds_read_b128 v[52:55], v238 offset:320
	s_waitcnt lgkmcnt(0)
	v_pk_fma_f32 v[50:51], v[58:59], v[50:51], v[54:55]
	v_pk_fma_f32 v[48:49], v[56:57], v[48:49], v[52:53]
.LBB0_242:
	v_pk_fma_f32 v[34:35], v[50:51], s[4:5], v[34:35] op_sel_hi:[1,0,1]
	v_pk_fma_f32 v[32:33], v[48:49], s[4:5], v[32:33] op_sel_hi:[1,0,1]
	v_lshlrev_b32_e32 v52, 16, v82
	v_and_b32_e32 v53, 0xffff0000, v82
	v_lshlrev_b32_e32 v54, 16, v83
	v_and_b32_e32 v55, 0xffff0000, v83
	v_cvt_pk_bf16_f32 v48, v32, v33
	v_cvt_pk_bf16_f32 v49, v34, v35
	s_and_b64 vcc, exec, s[40:41]
	global_store_dwordx2 v[36:37], v[48:49], off offset:32
	s_cbranch_vccnz .LBB0_244
	v_sub_f32_e32 v51, v53, v42
	v_sub_f32_e32 v50, v52, v42
	v_sub_f32_e32 v49, v55, v42
	v_sub_f32_e32 v48, v54, v42
	v_pk_mul_f32 v[56:57], v[44:45], v[50:51]
	v_mov_b32_e32 v50, v44
	v_mov_b32_e32 v51, v44
	v_pk_mul_f32 v[58:59], v[50:51], v[48:49]
	ds_read_b128 v[48:51], v238 offset:128
	ds_read_b128 v[52:55], v238 offset:384
	s_waitcnt lgkmcnt(0)
	v_pk_fma_f32 v[54:55], v[58:59], v[50:51], v[54:55]
	v_pk_fma_f32 v[52:53], v[56:57], v[48:49], v[52:53]
.LBB0_244:
	v_pk_fma_f32 v[30:31], v[54:55], s[4:5], v[30:31] op_sel_hi:[1,0,1]
	v_pk_fma_f32 v[28:29], v[52:53], s[4:5], v[28:29] op_sel_hi:[1,0,1]
	v_lshlrev_b32_e32 v48, 16, v80
	v_and_b32_e32 v49, 0xffff0000, v80
	v_lshlrev_b32_e32 v50, 16, v81
	v_and_b32_e32 v51, 0xffff0000, v81
	v_cvt_pk_bf16_f32 v52, v28, v29
	v_cvt_pk_bf16_f32 v53, v30, v31
	s_and_b64 vcc, exec, s[40:41]
	global_store_dwordx2 v[36:37], v[52:53], off offset:256
	s_cbranch_vccnz .LBB0_246
	v_sub_f32_e32 v51, v51, v42
	v_sub_f32_e32 v50, v50, v42
	s_waitcnt lgkmcnt(0)
	v_sub_f32_e32 v43, v49, v42
	v_sub_f32_e32 v42, v48, v42
	v_pk_mul_f32 v[52:53], v[44:45], v[42:43]
	v_mov_b32_e32 v45, v44
	v_pk_mul_f32 v[54:55], v[44:45], v[50:51]
	ds_read_b128 v[42:45], v238 offset:192
	ds_read_b128 v[48:51], v238 offset:448
	s_waitcnt lgkmcnt(0)
	v_pk_fma_f32 v[50:51], v[54:55], v[44:45], v[50:51]
	v_pk_fma_f32 v[48:49], v[52:53], v[42:43], v[48:49]

; __device__ __forceinline__ float bflo(unsigned w) { return __uint_as_float(w << 16); }
; __device__ __forceinline__ float bfhi(unsigned w) { return __uint_as_float(w & 0xffff0000u); }
; __device__ __forceinline__ u32x2 pack4(const f32x4 a) { u32x2 v; v.x = cvt_pk_bf16(a[0], a[1]); v.y = cvt_pk_bf16(a[2], a[3]); return v; }
;     __device__ __forceinline__ void apply(const RowInfo& ri, const ColInfo& ci, int row, int col, f32x4 a, f32x4 pv, float& s1, float& s2) const {
;         f32x4 h = pv;
;         if (!ident) { const f32x4 gg = *(const f32x4*)(g + col), bb = *(const f32x4*)(b + col); h = (pv - ri.mu) * ri.rstd * gg + bb; }
;         const f32x4 v = h * ALPHA + a;
;         *(u32x2*)(xb + (size_t)row * DM + col) = pack4(v);
;         s1 += (v[0] + v[1]) + (v[2] + v[3]); s2 += (v[0] * v[0] + v[1] * v[1]) + (v[2] * v[2] + v[3] * v[3]);
; template <class Epi>
; __device__ __forceinline__ void gemm_phase(LAS unsigned char* lds, const bf16_t* Ag, const bf16_t* Btg, const int K, const int nM, const int nN, const Epi& E) {
;     ...
;                 f32x4 pv[2][2];
; #pragma unroll
;                 for (int bj = 0; bj < 2; ++bj)
; #pragma unroll
;                     for (int n = 0; n < 2; ++n) { const u32x2 w = pk[m][bj][n]; pv[bj][n] = (f32x4){bflo(w.x), bfhi(w.x), bflo(w.y), bfhi(w.y)}; }
;                 const RowInfo ri = E.rowinfo(row, lrow, par, lds);
;                 float s1 = 0.f, s2 = 0.f;
; #pragma unroll
;                 for (int bj = 0; bj < 2; ++bj)
; #pragma unroll
;                     for (int n = 0; n < 2; ++n) E.apply(ri, ci[bj][n], row, pn * 256 + bj * 128 + wc * 32 + n * 16 + fq * 4, acc[ai][bj][m][n], pv[bj][n], s1, s2);
.LBB0_251:
	v_lshlrev_b32_e32 v30, 16, v78
	v_and_b32_e32 v31, 0xffff0000, v78
	v_lshlrev_b32_e32 v36, 16, v79
	v_and_b32_e32 v37, 0xffff0000, v79
	s_and_b64 vcc, exec, s[40:41]
	v_mov_b32_e32 v29, v28
	s_cbranch_vccnz .LBB0_253
	v_sub_f32_e32 v31, v31, v26
	v_sub_f32_e32 v30, v30, v26
	v_sub_f32_e32 v25, v37, v26
	v_sub_f32_e32 v24, v36, v26
	v_pk_mul_f32 v[38:39], v[28:29], v[30:31]
	v_mov_b32_e32 v30, v28
	v_mov_b32_e32 v31, v28
	v_pk_mul_f32 v[24:25], v[30:31], v[24:25]
	ds_read_b128 v[30:33], v238
	ds_read_b128 v[34:37], v238 offset:256
	s_waitcnt lgkmcnt(0)
	v_pk_fma_f32 v[36:37], v[24:25], v[32:33], v[36:37]
	v_pk_fma_f32 v[30:31], v[38:39], v[30:31], v[34:35]
.LBB0_253:
	v_add_u32_e32 v24, s57, v229
	v_ashrrev_i32_e32 v25, 31, v24
	v_lshlrev_b64 v[38:39], 11, v[24:25]
	v_pk_fma_f32 v[22:23], v[36:37], s[4:5], v[22:23] op_sel_hi:[1,0,1]
	v_pk_fma_f32 v[30:31], v[30:31], s[4:5], v[20:21] op_sel_hi:[1,0,1]
	v_lshl_add_u64 v[20:21], s[36:37], 0, v[38:39]
	v_lshlrev_b32_e32 v32, 16, v76
	v_and_b32_e32 v33, 0xffff0000, v76
	v_lshlrev_b32_e32 v34, 16, v77
	v_and_b32_e32 v35, 0xffff0000, v77
	v_cvt_pk_bf16_f32 v36, v30, v31
	v_cvt_pk_bf16_f32 v37, v22, v23
	v_lshl_add_u64 v[20:21], v[144:145], 1, v[20:21]
	s_and_b64 vcc, exec, s[40:41]
	global_store_dwordx2 v[20:21], v[36:37], off
	s_cbranch_vccnz .LBB0_255
	v_sub_f32_e32 v33, v33, v26
	v_sub_f32_e32 v32, v32, v26
	v_sub_f32_e32 v35, v35, v26
	v_sub_f32_e32 v34, v34, v26
	v_pk_mul_f32 v[40:41], v[28:29], v[32:33]
	v_mov_b32_e32 v32, v28
	v_mov_b32_e32 v33, v28
	v_pk_mul_f32 v[42:43], v[32:33], v[34:35]
	ds_read_b128 v[32:35], v238 offset:64
	ds_read_b128 v[36:39], v238 offset:320
	s_waitcnt lgkmcnt(0)
	v_pk_fma_f32 v[34:35], v[42:43], v[34:35], v[38:39]
	v_pk_fma_f32 v[32:33], v[40:41], v[32:33], v[36:37]
.LBB0_255:
	v_pk_fma_f32 v[18:19], v[34:35], s[4:5], v[18:19] op_sel_hi:[1,0,1]
	v_pk_fma_f32 v[16:17], v[32:33], s[4:5], v[16:17] op_sel_hi:[1,0,1]
	v_lshlrev_b32_e32 v36, 16, v74
	v_and_b32_e32 v37, 0xffff0000, v74
	v_lshlrev_b32_e32 v38, 16, v75
	v_and_b32_e32 v39, 0xffff0000, v75
	v_cvt_pk_bf16_f32 v32, v16, v17
	v_cvt_pk_bf16_f32 v33, v18, v19
	s_and_b64 vcc, exec, s[40:41]
	global_store_dwordx2 v[20:21], v[32:33], off offset:32
	s_cbranch_vccnz .LBB0_257
	v_sub_f32_e32 v35, v37, v26
	v_sub_f32_e32 v34, v36, v26
	v_sub_f32_e32 v33, v39, v26
	v_sub_f32_e32 v32, v38, v26
	v_pk_mul_f32 v[40:41], v[28:29], v[34:35]
	v_mov_b32_e32 v34, v28
	v_mov_b32_e32 v35, v28
	v_pk_mul_f32 v[42:43], v[34:35], v[32:33]
	ds_read_b128 v[32:35], v238 offset:128
	ds_read_b128 v[36:39], v238 offset:384
	s_waitcnt lgkmcnt(0)
	v_pk_fma_f32 v[38:39], v[42:43], v[34:35], v[38:39]
	v_pk_fma_f32 v[36:37], v[40:41], v[32:33], v[36:37]
.LBB0_257:
	v_pk_fma_f32 v[14:15], v[38:39], s[4:5], v[14:15] op_sel_hi:[1,0,1]
	v_pk_fma_f32 v[12:13], v[36:37], s[4:5], v[12:13] op_sel_hi:[1,0,1]
	v_lshlrev_b32_e32 v32, 16, v72
	v_and_b32_e32 v33, 0xffff0000, v72
	v_lshlrev_b32_e32 v34, 16, v73
	v_and_b32_e32 v35, 0xffff0000, v73
	v_cvt_pk_bf16_f32 v36, v12, v13
	v_cvt_pk_bf16_f32 v37, v14, v15
	s_and_b64 vcc, exec, s[40:41]
	global_store_dwordx2 v[20:21], v[36:37], off offset:256
	s_cbranch_vccnz .LBB0_259
	v_sub_f32_e32 v35, v35, v26
	v_sub_f32_e32 v34, v34, v26
	s_waitcnt lgkmcnt(0)
	v_sub_f32_e32 v27, v33, v26
	v_sub_f32_e32 v26, v32, v26
	v_pk_mul_f32 v[36:37], v[28:29], v[26:27]
	v_mov_b32_e32 v29, v28
	v_pk_mul_f32 v[38:39], v[28:29], v[34:35]
	ds_read_b128 v[26:29], v238 offset:192
	ds_read_b128 v[32:35], v238 offset:448
	s_waitcnt lgkmcnt(0)
	v_pk_fma_f32 v[34:35], v[38:39], v[28:29], v[34:35]
	v_pk_fma_f32 v[32:33], v[36:37], v[26:27], v[32:33]

; template <int WHICH>
; __device__ void phase_mix_dyn(LAS unsigned char* lds, KP& P0, int l0) {
;     ...
;     unsigned* ctr; { KPtr P_ = P0; ctr = (unsigned*)(p.ws + WS_CTR) + (l0 * 2 + WHICH) * 64; }
;     int n1 = 0, n2 = 0;
;     if (tid0 == 0) { n1 = (int)__hip_atomic_fetch_add(ctr, 1u, __ATOMIC_RELAXED, __HIP_MEMORY_SCOPE_AGENT); n2 = (int)__hip_atomic_fetch_add(ctr, 1u, __ATOMIC_RELAXED, __HIP_MEMORY_SCOPE_AGENT); }
.LBB0_297:
	v_readlane_b32 s6, v255, 25
	v_readlane_b32 s7, v255, 26
	s_lshl_b32 s6, s6, 7
	s_ashr_i32 s7, s6, 31
	s_lshl_b64 s[6:7], s[6:7], 2
	s_add_u32 s6, s86, s6
	s_addc_u32 s7, s87, s7
	s_add_u32 s6, s6, 0xeef4100
	s_addc_u32 s7, s7, 0
	v_mov_b32_e32 v138, v198
	v_writelane_b32 v255, s6, 30
	v_mov_b32_e32 v139, 0
	v_cmp_eq_u32_e64 s[40:41], 0, v138
	v_writelane_b32 v255, s7, 31
	v_mov_b32_e32 v140, 0
	s_and_saveexec_b64 s[6:7], s[40:41]
	s_cbranch_execz .LBB0_303
	s_mov_b64 s[24:25], exec
	v_mbcnt_lo_u32_b32 v0, s24, 0
	v_mbcnt_hi_u32_b32 v0, s25, v0
	v_cmp_eq_u32_e32 vcc, 0, v0
	s_and_saveexec_b64 s[14:15], vcc
	s_cbranch_execz .LBB0_300
	s_bcnt1_i32_b64 s12, s[24:25]
	s_lshl_b32 s12, s12, 1
	v_mov_b32_e32 v2, s12
	s_waitcnt lgkmcnt(0)
	v_readlane_b32 s12, v255, 30
	v_readlane_b32 s13, v255, 31
	s_nop 4
	global_atomic_add v2, v1, v2, s[12:13] sc0
.LBB0_300:
	s_or_b64 exec, exec, s[14:15]
	s_waitcnt vmcnt(0)
	v_readfirstlane_b32 s12, v2
	s_nop 1
	v_add_u32_e32 v139, s12, v0
	v_add_u32_e32 v140, 1, v139

; #define LBAR() do { asm volatile("s_waitcnt lgkmcnt(0)" ::: "memory"); __builtin_amdgcn_s_barrier(); asm volatile("" ::: "memory"); } while (0)
; template <int WHICH>
; __device__ void phase_mix_dyn(LAS unsigned char* lds, KP& P0, int l0) {
;     ...
;     for (;;) {
;         if (tid0 == 0) { tick[0] = n1; tick[1] = n2; }
;         LBAR();
;         u = tick[0]; un = tick[1];
;         if (u >= 780) break;
;         if (tid0 == 0) { n1 = n2; n2 = (int)__hip_atomic_fetch_add(ctr, 1u, __ATOMIC_RELAXED, __HIP_MEMORY_SCOPE_AGENT); }
.LBB0_307:
	v_mov_b32_e32 v137, v139
	s_and_saveexec_b64 s[6:7], s[40:41]
	s_cbranch_execz .LBB0_309
	s_waitcnt vmcnt(0)
	v_mov_b32_e32 v136, v140
	v_readlane_b32 s12, v255, 7
	s_nop 1
	v_mov_b32_e32 v0, s12
	v_readlane_b32 s12, v255, 8
	ds_write_b32 v0, v137
	s_nop 0
	v_mov_b32_e32 v0, s12
	ds_write_b32 v0, v136
.LBB0_309:
	s_or_b64 exec, exec, s[6:7]
	v_readlane_b32 s6, v255, 7
	s_waitcnt lgkmcnt(0)
	s_barrier
	s_nop 0
	v_mov_b32_e32 v0, s6
	v_readlane_b32 s6, v255, 8
	ds_read_b32 v0, v0
	s_waitcnt lgkmcnt(0)
	v_readfirstlane_b32 s20, v0
	v_mov_b32_e32 v2, s6
	ds_read_b32 v2, v2
	s_movk_i32 s6, 0x30b
	v_cmp_lt_i32_e32 vcc, s6, v0
	s_mov_b64 s[6:7], -1
	s_waitcnt lgkmcnt(0)
	v_readfirstlane_b32 s21, v2
	s_cbranch_vccnz .LBB0_306
	v_mov_b32_e32 v139, v137
	v_mov_b32_e32 v140, v136
	s_and_saveexec_b64 s[6:7], s[40:41]
	s_cbranch_execz .LBB0_314
	s_mov_b64 s[24:25], exec
	v_mbcnt_lo_u32_b32 v0, s24, 0
	v_mbcnt_hi_u32_b32 v0, s25, v0
	v_cmp_eq_u32_e32 vcc, 0, v0
	s_and_saveexec_b64 s[14:15], vcc
	s_cbranch_execz .LBB0_313
	s_bcnt1_i32_b64 s12, s[24:25]
	v_mov_b32_e32 v2, s12
	v_readlane_b32 s12, v255, 30
	v_readlane_b32 s13, v255, 31
	s_nop 4
	global_atomic_add v140, v1, v2, s[12:13] sc0
.LBB0_313:
	s_or_b64 exec, exec, s[14:15]
	v_mov_b32_e32 v139, v136

; template <int WHICH>
; __device__ void phase_mix_dyn(LAS unsigned char* lds, KP& P0, int l0) {
;     ...
;     for (;;) {
;         if (tid0 == 0) { n1 = n2; n2 = (int)__hip_atomic_fetch_add(ctr, 1u, __ATOMIC_RELAXED, __HIP_MEMORY_SCOPE_AGENT); }
;         KPtr P_ = P0; int l = l0; asm volatile("" : "+s"(P_.q), "+s"(l));
;         const HgRaw cur = nxt;
;         if (un < NMIXU) nxt = hg_load<WHICH>(P_, l, un, tid0);
.LBB0_483:
	v_readlane_b32 s6, v255, 25
	s_mov_b32 s12, s6
	s_mov_b64 s[46:47], s[30:31]
	s_load_dwordx2 s[42:43], s[46:47], 0xe8
	s_cmpk_lt_i32 s21, 0x924
	v_readlane_b32 s7, v255, 26
	s_cselect_b64 s[24:25], -1, 0
	s_cmpk_gt_i32 s21, 0x923
	s_cselect_b64 s[6:7], -1, 0
	s_waitcnt vmcnt(4)
	v_mov_b64_e32 v[8:9], v[52:53]
	s_waitcnt vmcnt(3)
	v_mov_b64_e32 v[12:13], v[68:69]
	s_waitcnt vmcnt(2)
	v_mov_b64_e32 v[20:21], v[56:57]
	s_waitcnt vmcnt(1)
	v_mov_b64_e32 v[16:17], v[64:65]
	s_waitcnt vmcnt(0)
	s_and_saveexec_b64 s[14:15], s[40:41]
	s_cbranch_execz .Lhg_tk_c
	v_mov_b32_e32 v137, v136
	v_readlane_b32 s22, v255, 30
	v_readlane_b32 s23, v255, 31
	s_nop 4
	global_atomic_add v136, v1, v203, s[22:23] sc0
.Lhg_tk_c:
	s_or_b64 exec, exec, s[14:15]
	v_mov_b64_e32 v[24:25], v[60:61]
	s_and_b64 vcc, exec, s[6:7]
	v_mov_b64_e32 v[10:11], v[54:55]
	v_mov_b64_e32 v[14:15], v[70:71]
	v_mov_b64_e32 v[22:23], v[58:59]
	v_mov_b64_e32 v[18:19], v[66:67]
	v_mov_b64_e32 v[26:27], v[62:63]
	s_cbranch_vccnz .LBB0_489
	s_add_i32 s13, s21, 0xfffffcf4
	s_mul_hi_i32 s14, s13, 0x2aaaaaab
	s_lshr_b32 s15, s14, 31
	s_add_i32 s14, s14, s15
	s_mul_i32 s15, s14, -6
	s_add_i32 s13, s15, s13
	s_ashr_i32 s15, s14, 31
	s_lshl_b64 s[14:15], s[14:15], 6
	v_lshl_add_u64 v[8:9], s[14:15], 0, v[2:3]
	s_waitcnt lgkmcnt(0)
	v_mov_b64_e32 v[10:11], s[42:43]
	v_mad_u64_u32 v[10:11], s[14:15], v8, s9, v[10:11]
	s_lshl_b32 s14, s13, 6
	s_ashr_i32 s15, s14, 31
	s_mul_i32 s22, s12, 0x44800
	v_mad_i32_i24 v11, v9, s9, v11
	s_mul_hi_i32 s13, s12, 0x44800
	s_add_u32 s22, s42, s22
	v_lshl_add_u64 v[8:9], s[14:15], 1, v[10:11]
	s_addc_u32 s13, s43, s13
	s_lshl_b64 s[14:15], s[14:15], 2
	v_lshlrev_b32_e32 v0, 1, v72
	s_add_u32 s14, s22, s14
	v_lshl_add_u64 v[20:21], v[8:9], 0, v[0:1]
	s_addc_u32 s15, s13, s15
	v_lshlrev_b32_e32 v0, 2, v72
	v_lshl_add_u64 v[16:17], s[14:15], 0, v[0:1]
	s_mov_b64 s[14:15], 0xef04800
	v_lshl_add_u64 v[24:25], v[16:17], 0, s[14:15]
	v_add_co_u32_e32 v16, vcc, 0xef04000, v16
	global_load_dwordx4 v[8:11], v[20:21], off
	global_load_dwordx4 v[12:15], v[20:21], off offset:768
	v_addc_co_u32_e32 v17, vcc, 0, v17, vcc
	global_load_dwordx4 v[16:19], v[16:17], off offset:2048
	s_nop 0
	global_load_dwordx4 v[20:23], v[20:21], off offset:1536
	s_nop 0
	global_load_dwordx4 v[24:27], v[24:25], off offset:16

; template <int WHICH>
; __device__ void phase_mix_dyn(LAS unsigned char* lds, KP& P0, int l0) {
;     ...
;     unsigned* ctr; { KPtr P_ = P0; ctr = (unsigned*)(p.ws + WS_CTR) + (l0 * 2 + WHICH) * 64; }
;     int n1 = 0, n2 = 0;
;     if (tid0 == 0) { n1 = (int)__hip_atomic_fetch_add(ctr, 1u, __ATOMIC_RELAXED, __HIP_MEMORY_SCOPE_AGENT); n2 = (int)__hip_atomic_fetch_add(ctr, 1u, __ATOMIC_RELAXED, __HIP_MEMORY_SCOPE_AGENT); }
.LBB0_597:
	s_and_b64 vcc, exec, s[6:7]
	s_cbranch_vccz .LBB0_708
	v_readlane_b32 s6, v255, 25
	v_readlane_b32 s7, v255, 26
	s_lshl_b32 s6, s6, 7
	s_ashr_i32 s7, s6, 31
	s_lshl_b64 s[6:7], s[6:7], 2
	s_add_u32 s6, s86, s6
	s_addc_u32 s7, s87, s7
	v_mov_b32_e32 v100, v198
	s_add_u32 s6, s6, 0xeef4000
	s_addc_u32 s7, s7, 0
	v_mov_b32_e32 v101, 0
	v_cmp_eq_u32_e64 s[40:41], 0, v100
	v_mov_b32_e32 v102, 0
	s_and_saveexec_b64 s[20:21], s[40:41]
	s_cbranch_execz .LBB0_604
	s_mov_b64 s[22:23], exec
	v_mbcnt_lo_u32_b32 v0, s22, 0
	v_mbcnt_hi_u32_b32 v0, s23, v0
	v_cmp_eq_u32_e32 vcc, 0, v0
	s_and_saveexec_b64 s[14:15], vcc
	s_cbranch_execz .LBB0_601
	s_bcnt1_i32_b64 s12, s[22:23]
	s_lshl_b32 s12, s12, 1
	v_mov_b32_e32 v2, s12
	global_atomic_add v2, v1, v2, s[6:7] sc0
.LBB0_601:
	s_or_b64 exec, exec, s[14:15]
	s_waitcnt vmcnt(0)
	v_readfirstlane_b32 s12, v2
	s_nop 1
	v_add_u32_e32 v101, s12, v0
	v_add_u32_e32 v102, 1, v101

; #define LBAR() do { asm volatile("s_waitcnt lgkmcnt(0)" ::: "memory"); __builtin_amdgcn_s_barrier(); asm volatile("" ::: "memory"); } while (0)
; template <int WHICH>
; __device__ void phase_mix_dyn(LAS unsigned char* lds, KP& P0, int l0) {
;     ...
;     for (;;) {
;         if (tid0 == 0) { tick[0] = n1; tick[1] = n2; }
;         LBAR();
;         u = tick[0]; un = tick[1];
;         if (u >= 780) break;
;         if (tid0 == 0) { n1 = n2; n2 = (int)__hip_atomic_fetch_add(ctr, 1u, __ATOMIC_RELAXED, __HIP_MEMORY_SCOPE_AGENT); }
.LBB0_607:
	v_mov_b32_e32 v99, v101
	s_and_saveexec_b64 s[14:15], s[40:41]
	s_cbranch_execz .LBB0_609
	s_waitcnt vmcnt(0)
	v_mov_b32_e32 v98, v102
	v_readlane_b32 s12, v255, 7
	s_nop 1
	v_mov_b32_e32 v0, s12
	v_readlane_b32 s12, v255, 8
	ds_write_b32 v0, v99
	s_nop 0
	v_mov_b32_e32 v0, s12
	ds_write_b32 v0, v98
.LBB0_609:
	s_or_b64 exec, exec, s[14:15]
	v_readlane_b32 s12, v255, 7
	s_waitcnt lgkmcnt(0)
	s_barrier
	s_mov_b64 s[14:15], -1
	v_mov_b32_e32 v0, s12
	v_readlane_b32 s12, v255, 8
	ds_read_b32 v0, v0
	s_waitcnt lgkmcnt(0)
	v_readfirstlane_b32 s13, v0
	v_mov_b32_e32 v2, s12
	ds_read_b32 v2, v2
	s_movk_i32 s12, 0x30b
	v_cmp_lt_i32_e32 vcc, s12, v0
	s_waitcnt lgkmcnt(0)
	v_readfirstlane_b32 s62, v2
	s_cbranch_vccnz .LBB0_606
	v_mov_b32_e32 v101, v99
	v_mov_b32_e32 v102, v98
	s_and_saveexec_b64 s[14:15], s[40:41]
	s_cbranch_execz .LBB0_614
	s_mov_b64 s[22:23], exec
	v_mbcnt_lo_u32_b32 v0, s22, 0
	v_mbcnt_hi_u32_b32 v0, s23, v0
	v_cmp_eq_u32_e32 vcc, 0, v0
	s_and_saveexec_b64 s[20:21], vcc
	s_cbranch_execz .LBB0_613
	s_bcnt1_i32_b64 s12, s[22:23]
	v_mov_b32_e32 v2, s12
	global_atomic_add v102, v1, v2, s[6:7] sc0
.LBB0_613:
	s_or_b64 exec, exec, s[20:21]
	v_mov_b32_e32 v101, v98

; template <int WHICH>
; __device__ void phase_mix_dyn(LAS unsigned char* lds, KP& P0, int l0) {
;     ...
;     for (;;) {
;         if (tid0 == 0) { n1 = n2; n2 = (int)__hip_atomic_fetch_add(ctr, 1u, __ATOMIC_RELAXED, __HIP_MEMORY_SCOPE_AGENT); }
;         KPtr P_ = P0; int l = l0; asm volatile("" : "+s"(P_.q), "+s"(l));
;         const HgRaw cur = nxt;
;         if (un < NMIXU) nxt = hg_load<WHICH>(P_, l, un, tid0);
.LBB0_691:
	s_cmpk_lt_i32 s62, 0x924
	s_cselect_b64 s[22:23], -1, 0
	s_cmpk_gt_i32 s62, 0x923
	v_readlane_b32 s14, v255, 25
	s_cselect_b64 s[20:21], -1, 0
	s_waitcnt vmcnt(3)
	v_mov_b64_e32 v[8:9], v[36:37]
	s_waitcnt vmcnt(2)
	v_mov_b64_e32 v[12:13], v[24:25]
	s_waitcnt vmcnt(1)
	v_mov_b64_e32 v[16:17], v[32:33]
	s_waitcnt vmcnt(0)
	s_and_saveexec_b64 s[44:45], s[40:41]
	s_cbranch_execz .Lhg_tk_a
	v_mov_b32_e32 v99, v98
	s_nop 0
	global_atomic_add v98, v1, v203, s[6:7] sc0
.Lhg_tk_a:
	s_or_b64 exec, exec, s[44:45]
	v_mov_b64_e32 v[20:21], v[28:29]
	s_mov_b64 s[24:25], s[30:31]
	s_mov_b32 s12, s14
	s_and_b64 vcc, exec, s[20:21]
	v_mov_b64_e32 v[10:11], v[38:39]
	v_mov_b64_e32 v[14:15], v[26:27]
	v_mov_b64_e32 v[18:19], v[34:35]
	v_mov_b64_e32 v[22:23], v[30:31]
	v_readlane_b32 s15, v255, 26
	s_cbranch_vccnz .LBB0_697
	s_add_i32 s26, s62, 0xfffffcf4
	s_mul_hi_i32 s42, s26, 0x2aaaaaab
	s_load_dwordx2 s[14:15], s[24:25], 0xe8
	s_lshr_b32 s43, s42, 31
	s_add_i32 s42, s42, s43
	s_mul_i32 s43, s42, -6
	s_add_i32 s26, s43, s26
	s_ashr_i32 s43, s42, 31
	s_lshl_b64 s[42:43], s[42:43], 6
	v_lshl_add_u64 v[8:9], s[42:43], 0, v[2:3]
	s_waitcnt lgkmcnt(0)
	v_mov_b64_e32 v[10:11], s[14:15]
	v_mad_u64_u32 v[10:11], s[42:43], v8, s9, v[10:11]
	s_lshl_b32 s42, s26, 6
	s_ashr_i32 s43, s42, 31
	s_mul_hi_i32 s26, s12, 0x44800
	s_mul_i32 s12, s12, 0x44800
	s_add_u32 s12, s14, s12
	v_mad_i32_i24 v11, v9, s9, v11
	s_addc_u32 s26, s15, s26
	s_lshl_b64 s[14:15], s[42:43], 2
	v_lshl_add_u64 v[8:9], s[42:43], 1, v[10:11]
	v_lshlrev_b32_e32 v0, 1, v40
	s_add_u32 s14, s12, s14
	v_lshl_add_u64 v[12:13], v[8:9], 0, v[0:1]
	s_addc_u32 s15, s26, s15
	v_lshlrev_b32_e32 v0, 2, v40
	v_lshl_add_u64 v[16:17], s[14:15], 0, v[0:1]
	s_mov_b64 s[14:15], 0xef04800
	v_lshl_add_u64 v[20:21], v[16:17], 0, s[14:15]
	v_add_co_u32_e32 v16, vcc, 0xef04000, v16
	global_load_dwordx4 v[8:11], v[12:13], off offset:768
	s_nop 0
	global_load_dwordx4 v[12:15], v[12:13], off offset:1536
	v_addc_co_u32_e32 v17, vcc, 0, v17, vcc
	global_load_dwordx4 v[16:19], v[16:17], off offset:2048
	s_nop 0
	global_load_dwordx4 v[20:23], v[20:21], off offset:16

; #define LAS __attribute__((address_space(3)))
; __device__ __forceinline__ u32x4 pack8(const float* o) { u32x4 v; v.x = cvt_pk_bf16(o[0], o[1]); v.y = cvt_pk_bf16(o[2], o[3]); v.z = cvt_pk_bf16(o[4], o[5]); v.w = cvt_pk_bf16(o[6], o[7]); return v; }
; __device__ __forceinline__ u32x2 pack4(const f32x4 a) { u32x2 v; v.x = cvt_pk_bf16(a[0], a[1]); v.y = cvt_pk_bf16(a[2], a[3]); return v; }
; #define LBAR() do { asm volatile("s_waitcnt lgkmcnt(0)" ::: "memory"); __builtin_amdgcn_s_barrier(); asm volatile("" ::: "memory"); } while (0)
; #define MFMA16(a, b, c) __builtin_amdgcn_mfma_f32_16x16x32_bf16((a), (b), (c), 0, 0, 0)
; __device__ __forceinline__ void hgrn_a_unit(LAS unsigned char* lds, KP& P_, int l, int bc, int h, const HgRaw& in) {
;     ...
;     { float kd[8];
; #pragma unroll
;       for (int j = 0; j < 8; ++j) { const float G = Gf[t * 65 + k0 + j], Gl = Gf[63 * 65 + k0 + j]; kd[j] = kk[j] * __builtin_amdgcn_exp2f(Gl - G); }
;       if (t == 63) { f32x4 d0, d1;
; #pragma unroll
;           for (int j = 0; j < 4; ++j) { d0[j] = __builtin_amdgcn_exp2f(Gf[63 * 65 + k0 + j]); d1[j] = __builtin_amdgcn_exp2f(Gf[63 * 65 + k0 + 4 + j]); }
;           float* dp = (float*)(p.ws + WS_DECH) + ((size_t)bc * 6 + h) * 64 + k0; *(f32x4*)dp = d0; *(f32x4*)(dp + 4) = d1; }
;       *(LAS u32x4*)(KT + t * 72 + k0) = pack8(kd); }
;     LBAR();
;     { const int wid = tid >> 6, lane = tid & 63, fr = lane & 15, fq = lane >> 4, kt = wid >> 1;
;       bf16_t* sth = (bf16_t*)(p.ws + WS_STH) + ((size_t)bc * 6 + h) * 4096;
; #pragma unroll
;       for (int q = 0; q < 2; ++q) { const int vt = (wid & 1) * 2 + q; f32x4 acc = (f32x4){0.f, 0.f, 0.f, 0.f};
; #pragma unroll
;           for (int ks = 0; ks < 2; ++ks) { const unsigned ro = (unsigned)((32 * ks + 8 * fq + (fr >> 2)) * 144 + 8 * (fr & 3));
;               const unsigned ka = (unsigned)(size_t)KT + ro + 32u * kt, va = (unsigned)(size_t)VT + ro + 32u * vt;
;               const bf16x8 a = tr_frag(ka, ka + 576u), b = tr_frag(va, va + 576u); acc = MFMA16(a, b, acc); }
;           *(u32x2*)(sth + (size_t)(vt * 16 + fr) * 64 + kt * 16 + fq * 4) = pack4(acc); } }
;     LBAR();
; template <int WHICH>
; __device__ void phase_mix_dyn(LAS unsigned char* lds, KP& P0, int l0) {
;     ...
;         if (un >= NMIXU) break;
;         if (tid0 == 0) { tick[0] = n1; tick[1] = n2; }
;         LBAR();
.LBB0_705:
	s_or_b64 exec, exec, s[42:43]
	s_waitcnt lgkmcnt(0)
	v_sub_f32_e32 v0, v57, v55
	v_exp_f32_e32 v55, v0
	v_sub_f32_e32 v0, v56, v54
	v_pk_add_f32 v[46:47], v[46:47], 1.0 op_sel_hi:[1,0] neg_lo:[1,0] neg_hi:[1,0]
	v_exp_f32_e32 v54, v0
	v_sub_f32_e32 v0, v53, v51
	v_pk_mul_f32 v[28:29], v[28:29], v[46:47]
	v_exp_f32_e32 v47, v0
	v_sub_f32_e32 v0, v52, v50
	v_exp_f32_e32 v46, v0
	v_sub_f32_e32 v0, v49, v31
	v_exp_f32_e32 v31, v0
	v_sub_f32_e32 v0, v48, v30
	v_exp_f32_e32 v30, v0
	v_sub_f32_e32 v0, v27, v25
	v_exp_f32_e32 v25, v0
	v_sub_f32_e32 v0, v26, v24
	v_pk_add_f32 v[42:43], v[42:43], 1.0 op_sel_hi:[1,0] neg_lo:[1,0] neg_hi:[1,0]
	v_exp_f32_e32 v24, v0
	v_pk_mul_f32 v[32:33], v[32:33], v[42:43]
	v_pk_add_f32 v[34:35], v[34:35], 1.0 op_sel_hi:[1,0] neg_lo:[1,0] neg_hi:[1,0]
	v_pk_mul_f32 v[26:27], v[32:33], v[30:31]
	v_pk_add_f32 v[30:31], v[36:37], 1.0 op_sel_hi:[1,0] neg_lo:[1,0] neg_hi:[1,0]
	v_pk_mul_f32 v[34:35], v[44:45], v[34:35]
	v_pk_mul_f32 v[30:31], v[38:39], v[30:31]
	v_pk_mul_f32 v[28:29], v[28:29], v[54:55]
	v_pk_mul_f32 v[34:35], v[34:35], v[46:47]
	v_pk_mul_f32 v[24:25], v[30:31], v[24:25]
	v_lshrrev_b32_e32 v0, 5, v60
	v_cvt_pk_bf16_f32 v24, v24, v25
	v_cvt_pk_bf16_f32 v25, v26, v27
	v_cvt_pk_bf16_f32 v26, v34, v35
	v_cvt_pk_bf16_f32 v27, v28, v29
	ds_write_b128 v61, v[24:27] offset:18688
	s_waitcnt lgkmcnt(0)
	s_barrier
	s_load_dwordx2 s[14:15], s[24:25], 0xe8
	v_ashrrev_i32_e32 v26, 7, v60
	v_and_b32_e32 v39, 2, v0
	v_lshrrev_b32_e32 v0, 1, v60
	v_readlane_b32 s12, v255, 15
	v_lshlrev_b64 v[24:25], 13, v[58:59]
	v_and_b32_e32 v0, 24, v0
	v_bfe_u32 v27, v60, 2, 2
	v_lshl_add_u32 v32, v26, 5, s12
	v_lshlrev_b32_e32 v26, 4, v26
	s_waitcnt lgkmcnt(0)
	v_lshl_add_u64 v[24:25], s[14:15], 0, v[24:25]
	v_or_b32_e32 v28, v0, v27
	v_and_b32_e32 v29, 24, v41
	v_ashrrev_i32_e32 v27, 31, v26
	v_lshl_add_u64 v[24:25], v[26:27], 1, v[24:25]
	v_mad_u32_u24 v41, v28, s10, v29
	v_readlane_b32 s12, v255, 16
	v_lshl_add_u64 v[24:25], v[24:25], 0, v[0:1]
	s_mov_b64 s[14:15], 0xc300000
	v_add_u32_e32 v42, v41, v32
	v_lshl_add_u32 v0, v39, 5, s12
	v_lshl_add_u64 v[36:37], v[24:25], 0, s[14:15]
	v_add_u32_e32 v33, v41, v0
	v_add_u32_e32 v43, 0x240, v42
	ds_read_b64_tr_b16 v[24:25], v42
	ds_read_b64_tr_b16 v[26:27], v43
	s_waitcnt lgkmcnt(0)
	v_add_u32_e32 v34, 0x240, v33
	ds_read_b64_tr_b16 v[28:29], v33
	ds_read_b64_tr_b16 v[30:31], v34
	s_waitcnt lgkmcnt(0)
	v_add_u32_e32 v44, 0x1200, v41
	v_mfma_f32_16x16x32_bf16 v[24:27], v[24:27], v[28:31], 0
	v_add_u32_e32 v45, v44, v32
	v_add_u32_e32 v0, v44, v0
	v_add_u32_e32 v46, 0x240, v45
	ds_read_b64_tr_b16 v[28:29], v45
	ds_read_b64_tr_b16 v[30:31], v46
	s_waitcnt lgkmcnt(0)
	v_add_u32_e32 v47, 0x240, v0
	ds_read_b64_tr_b16 v[32:33], v0
	ds_read_b64_tr_b16 v[34:35], v47
	s_waitcnt lgkmcnt(0)
	v_and_b32_e32 v38, 15, v60
	v_mfma_f32_16x16x32_bf16 v[24:27], v[28:31], v[32:35], v[24:27]
	v_lshlrev_b32_e32 v38, 7, v38
	v_lshl_or_b32 v0, v39, 11, v38
	s_andn2_b64 vcc, exec, s[22:23]
	s_nop 4
	v_cvt_pk_bf16_f32 v24, v24, v25
	v_cvt_pk_bf16_f32 v25, v26, v27
	v_lshl_add_u64 v[26:27], v[36:37], 0, v[0:1]
	v_or_b32_e32 v0, 1, v39
	global_store_dwordx2 v[26:27], v[24:25], off
	v_lshl_add_u32 v32, v0, 5, s12
	v_add_u32_e32 v33, v41, v32
	ds_read_b64_tr_b16 v[24:25], v42
	ds_read_b64_tr_b16 v[26:27], v43
	s_waitcnt lgkmcnt(0)
	v_add_u32_e32 v34, 0x240, v33
	ds_read_b64_tr_b16 v[28:29], v33
	ds_read_b64_tr_b16 v[30:31], v34
	s_waitcnt lgkmcnt(0)
	v_add_u32_e32 v39, v44, v32
	v_mfma_f32_16x16x32_bf16 v[24:27], v[24:27], v[28:31], 0
	ds_read_b64_tr_b16 v[28:29], v45
	ds_read_b64_tr_b16 v[30:31], v46
	s_waitcnt lgkmcnt(0)
	v_add_u32_e32 v41, 0x240, v39
	ds_read_b64_tr_b16 v[32:33], v39
	ds_read_b64_tr_b16 v[34:35], v41
	s_waitcnt lgkmcnt(0)
	v_lshl_or_b32 v0, v0, 11, v38
	v_mfma_f32_16x16x32_bf16 v[24:27], v[28:31], v[32:35], v[24:27]
	s_nop 7
	v_cvt_pk_bf16_f32 v24, v24, v25
	v_cvt_pk_bf16_f32 v25, v26, v27
	v_lshl_add_u64 v[26:27], v[36:37], 0, v[0:1]
	global_store_dwordx2 v[26:27], v[24:25], off
	s_waitcnt lgkmcnt(0)
	s_barrier
	s_cbranch_vccnz .LBB0_690
	s_and_saveexec_b64 s[14:15], s[40:41]
	s_cbranch_execz .LBB0_689
	s_waitcnt vmcnt(0)
	v_readlane_b32 s12, v255, 7
	s_nop 1
	v_mov_b32_e32 v0, s12
	v_readlane_b32 s12, v255, 8
	ds_write_b32 v0, v99
	s_nop 0
	v_mov_b32_e32 v0, s12
	ds_write_b32 v0, v98
	s_branch .LBB0_689

; __device__ __forceinline__ float bflo(unsigned w) { return __uint_as_float(w << 16); }
; __device__ __forceinline__ float bfhi(unsigned w) { return __uint_as_float(w & 0xffff0000u); }
; __device__ __forceinline__ u32x2 pack4(const f32x4 a) { u32x2 v; v.x = cvt_pk_bf16(a[0], a[1]); v.y = cvt_pk_bf16(a[2], a[3]); return v; }
; __device__ __forceinline__ int prow0(int pm) { return (pm >> 4) * LP + PADR + (pm & 15) * 256; }
;     __device__ __forceinline__ u32x2 preload_pk(int row, int col) const { return (u32x2){0u, 0u}; }
;     __device__ __forceinline__ u32x2 preload_pk(int row, int col) const { return (u32x2){0u, 0u}; }
;     __device__ __forceinline__ void apply(const RowInfo& ri, const ColInfo& ci, int row, int col, f32x4 a, f32x4 pv, float& s1, float& s2) const {
;         f32x4 h = pv;
;         if (!ident) { const f32x4 gg = *(const f32x4*)(g + col), bb = *(const f32x4*)(b + col); h = (pv - ri.mu) * ri.rstd * gg + bb; }
;         const f32x4 v = h * ALPHA + a;
;         *(u32x2*)(xb + (size_t)row * DM + col) = pack4(v);
; template <class Epi>
; __device__ __forceinline__ void gemm_phase(LAS unsigned char* lds, const bf16_t* Ag, const bf16_t* Btg, const int K, const int nM, const int nN, const Epi& E) {
;     ...
;                 if (Epi::PRELOAD && m == 0) {
; #pragma unroll
;                     for (int g2 = 0; g2 < 4; ++g2)
; #pragma unroll
;                         for (int bj = 0; bj < 2; ++bj)
; #pragma unroll
;                             for (int n = 0; n < 2; ++n) pk[g2][bj][n] = E.preload_pk(prow0(pm) + ai * 128 + wr * 64 + g2 * 16 + fr, pn * 256 + bj * 128 + wc * 32 + n * 16 + fq * 4);
;                 }
;                 f32x4 pv[2][2];
; #pragma unroll
;                 for (int bj = 0; bj < 2; ++bj)
; #pragma unroll
;                     for (int n = 0; n < 2; ++n) { const u32x2 w = pk[m][bj][n]; pv[bj][n] = (f32x4){bflo(w.x), bfhi(w.x), bflo(w.y), bfhi(w.y)}; }
;                 const RowInfo ri = E.rowinfo(row, lrow, par, lds);
;                 float s1 = 0.f, s2 = 0.f;
; #pragma unroll
;                 for (int bj = 0; bj < 2; ++bj)
; #pragma unroll
;                     for (int n = 0; n < 2; ++n) E.apply(ri, ci[bj][n], row, pn * 256 + bj * 128 + wc * 32 + n * 16 + fq * 4, acc[ai][bj][m][n], pv[bj][n], s1, s2);
.LBB0_748:
	s_lshr_b32 s12, s74, 4
	s_lshl_b32 s15, s74, 8
	s_mulk_i32 s12, 0x1040
	s_and_b32 s15, s15, 0xf00
	s_add_i32 s15, s15, s12
	s_or_b32 s49, s15, 48
	v_add_u32_e32 v146, s49, v164
	v_lshl_or_b32 v144, s76, 8, v166
	v_ashrrev_i32_e32 v147, 31, v146
	v_ashrrev_i32_e32 v145, 31, v144
	v_lshlrev_b64 v[140:141], 11, v[146:147]
	v_lshlrev_b64 v[148:149], 1, v[144:145]
	v_lshl_add_u64 v[140:141], s[36:37], 0, v[140:141]
	v_lshl_add_u64 v[154:155], v[140:141], 0, v[148:149]
	global_load_dwordx2 v[160:161], v[154:155], off
	v_lshlrev_b64 v[142:143], 2, v[144:145]
	v_lshl_add_u64 v[140:141], s[20:21], 0, v[142:143]
	v_lshl_add_u64 v[142:143], s[22:23], 0, v[142:143]
	v_and_b32_e32 v234, 7, v204
	v_bfe_u32 v235, v204, 3, 1
	v_lshrrev_b32_e32 v236, 4, v204
	v_lshlrev_b32_e32 v238, 4, v234
	v_lshl_add_u32 v238, v235, 9, v238
	v_lshlrev_b32_e32 v236, 4, v236
	v_sub_u32_e32 v238, v238, v236
	v_ashrrev_i32_e32 v239, 31, v238
	v_lshl_add_u64 v[240:241], v[140:141], 0, v[238:239]
	v_lshl_add_u64 v[242:243], v[142:143], 0, v[238:239]
	global_load_dwordx4 v[244:247], v[240:241], off
	global_load_dwordx4 v[248:251], v[242:243], off
	v_lshrrev_b32_e32 v237, 6, v198
	v_lshlrev_b32_e32 v237, 9, v237
	v_add_u32_e32 v237, 0x21000, v237
	v_add_u32_e32 v238, v237, v236
	v_lshl_add_u32 v237, v235, 7, v237
	v_lshl_add_u32 v237, v234, 4, v237
	s_waitcnt vmcnt(0)
	ds_write_b128 v237, v[244:247]
	ds_write_b128 v237, v[248:251] offset:256
	s_waitcnt lgkmcnt(0)
	ds_read_b128 v[150:153], v238
	ds_read_b128 v[156:159], v238 offset:256
	s_add_i32 s12, s14, 0
	s_add_i32 s12, s12, 0x20000
	v_lshl_add_u32 v176, v164, 3, s12
	ds_read_b64 v[188:189], v176
	global_load_dwordx2 v[162:163], v[154:155], off offset:32
	global_load_dwordx2 v[180:181], v[154:155], off offset:256
	global_load_dwordx2 v[190:191], v[154:155], off offset:288
	s_lshl_b32 s52, s76, 2
	s_ashr_i32 s53, s52, 31
	s_or_b64 s[52:53], s[52:53], s[90:91]
	s_waitcnt vmcnt(0) lgkmcnt(0)
	v_lshlrev_b32_e32 v175, 16, v160
	v_and_b32_e32 v160, 0xffff0000, v160
	v_lshlrev_b32_e32 v179, 16, v161
	v_and_b32_e32 v182, 0xffff0000, v161
	s_waitcnt lgkmcnt(0)
	v_sub_f32_e32 v161, v160, v188
	v_sub_f32_e32 v160, v175, v188
	v_sub_f32_e32 v183, v182, v188
	v_sub_f32_e32 v182, v179, v188
	v_pk_mul_f32 v[182:183], v[188:189], v[182:183] op_sel:[1,0]
	v_pk_mul_f32 v[160:161], v[188:189], v[160:161] op_sel:[1,0]
	v_pk_fma_f32 v[152:153], v[152:153], v[182:183], v[158:159]
	v_pk_fma_f32 v[150:151], v[150:151], v[160:161], v[156:157]
	v_pk_fma_f32 v[192:193], v[152:153], s[4:5], v[134:135] op_sel_hi:[1,0,1]
	v_pk_fma_f32 v[194:195], v[150:151], s[4:5], v[132:133] op_sel_hi:[1,0,1]
	v_cvt_pk_bf16_f32 v133, v192, v193
	v_cvt_pk_bf16_f32 v132, v194, v195
	global_store_dwordx2 v[154:155], v[132:133], off
	ds_read_b128 v[132:135], v238 offset:64
	s_nop 0
	ds_read_b128 v[150:153], v238 offset:320
	v_lshlrev_b32_e32 v156, 16, v162
	v_and_b32_e32 v157, 0xffff0000, v162
	v_lshlrev_b32_e32 v158, 16, v163
	v_and_b32_e32 v159, 0xffff0000, v163
	v_sub_f32_e32 v157, v157, v188
	v_sub_f32_e32 v156, v156, v188
	v_sub_f32_e32 v159, v159, v188
	v_sub_f32_e32 v158, v158, v188
	v_pk_mul_f32 v[158:159], v[188:189], v[158:159] op_sel:[1,0]
	v_pk_mul_f32 v[156:157], v[188:189], v[156:157] op_sel:[1,0]
	v_lshlrev_b32_e32 v226, 16, v191
	v_mov_b32_e32 v227, v193
	v_xor_b32_e32 v175, 16, v204
	v_cmp_lt_i32_e32 vcc, v175, v206
	v_xor_b32_e32 v179, 32, v204
	s_waitcnt vmcnt(1) lgkmcnt(0)
	v_pk_fma_f32 v[132:133], v[132:133], v[156:157], v[150:151]
	v_pk_fma_f32 v[134:135], v[134:135], v[158:159], v[152:153]
	v_pk_fma_f32 v[210:211], v[132:133], s[4:5], v[128:129] op_sel_hi:[1,0,1]
	v_pk_fma_f32 v[196:197], v[134:135], s[4:5], v[130:131] op_sel_hi:[1,0,1]
	v_cvt_pk_bf16_f32 v128, v210, v211
	v_cvt_pk_bf16_f32 v129, v196, v197
	global_store_dwordx2 v[154:155], v[128:129], off offset:32
	ds_read_b128 v[128:131], v238 offset:128
	s_nop 0
	ds_read_b128 v[132:135], v238 offset:384
	v_lshlrev_b32_e32 v150, 16, v180
	v_and_b32_e32 v151, 0xffff0000, v180
	v_lshlrev_b32_e32 v152, 16, v181
	v_and_b32_e32 v153, 0xffff0000, v181
	v_sub_f32_e32 v151, v151, v188
	v_sub_f32_e32 v150, v150, v188
	v_sub_f32_e32 v153, v153, v188
	v_sub_f32_e32 v152, v152, v188
	v_pk_mul_f32 v[152:153], v[188:189], v[152:153] op_sel:[1,0]
	v_pk_mul_f32 v[150:151], v[188:189], v[150:151] op_sel:[1,0]
	v_cndmask_b32_e32 v175, v204, v175, vcc
	v_lshlrev_b32_e32 v175, 2, v175
	v_cmp_lt_i32_e32 vcc, v179, v206
	s_waitcnt vmcnt(2) lgkmcnt(0)
; __device__ __forceinline__ float bflo(unsigned w) { return __uint_as_float(w << 16); }
; __device__ __forceinline__ float bfhi(unsigned w) { return __uint_as_float(w & 0xffff0000u); }
; __device__ __forceinline__ u32x2 pack4(const f32x4 a) { u32x2 v; v.x = cvt_pk_bf16(a[0], a[1]); v.y = cvt_pk_bf16(a[2], a[3]); return v; }
;     __device__ __forceinline__ void apply(const RowInfo& ri, const ColInfo& ci, int row, int col, f32x4 a, f32x4 pv, float& s1, float& s2) const {
;         f32x4 h = pv;
;         if (!ident) { const f32x4 gg = *(const f32x4*)(g + col), bb = *(const f32x4*)(b + col); h = (pv - ri.mu) * ri.rstd * gg + bb; }
;         const f32x4 v = h * ALPHA + a;
;         *(u32x2*)(xb + (size_t)row * DM + col) = pack4(v);
;         s1 += (v[0] + v[1]) + (v[2] + v[3]); s2 += (v[0] * v[0] + v[1] * v[1]) + (v[2] * v[2] + v[3] * v[3]);
; template <class Epi>
; __device__ __forceinline__ void gemm_phase(LAS unsigned char* lds, const bf16_t* Ag, const bf16_t* Btg, const int K, const int nM, const int nN, const Epi& E) {
;     ...
;                 if (Epi::PRELOAD && m == 0) {
; #pragma unroll
;                     for (int g2 = 0; g2 < 4; ++g2)
; #pragma unroll
;                         for (int bj = 0; bj < 2; ++bj)
; #pragma unroll
;                             for (int n = 0; n < 2; ++n) pk[g2][bj][n] = E.preload_pk(prow0(pm) + ai * 128 + wr * 64 + g2 * 16 + fr, pn * 256 + bj * 128 + wc * 32 + n * 16 + fq * 4);
;                 }
;                 f32x4 pv[2][2];
; #pragma unroll
;                 for (int bj = 0; bj < 2; ++bj)
; #pragma unroll
;                     for (int n = 0; n < 2; ++n) { const u32x2 w = pk[m][bj][n]; pv[bj][n] = (f32x4){bflo(w.x), bfhi(w.x), bflo(w.y), bfhi(w.y)}; }
;                 const RowInfo ri = E.rowinfo(row, lrow, par, lds);
;                 float s1 = 0.f, s2 = 0.f;
; #pragma unroll
;                 for (int bj = 0; bj < 2; ++bj)
; #pragma unroll
;                     for (int n = 0; n < 2; ++n) E.apply(ri, ci[bj][n], row, pn * 256 + bj * 128 + wc * 32 + n * 16 + fq * 4, acc[ai][bj][m][n], pv[bj][n], s1, s2);
;                 if (Epi::STATS) {
;                     s1 += __shfl_xor(s1, 16); s1 += __shfl_xor(s1, 32); s2 += __shfl_xor(s2, 16); s2 += __shfl_xor(s2, 32);
;                     if (fq == 0) *(f32x2*)(E.stat_out + ((size_t)row * 16 + pn * 4 + wc) * 2) = (f32x2){s1, s2};
;                 }
	v_pk_fma_f32 v[128:129], v[150:151], v[128:129], v[132:133]
	v_pk_fma_f32 v[130:131], v[152:153], v[130:131], v[134:135]
	v_pk_fma_f32 v[222:223], v[128:129], s[4:5], v[124:125] op_sel_hi:[1,0,1]
	v_pk_fma_f32 v[216:217], v[130:131], s[4:5], v[126:127] op_sel_hi:[1,0,1]
	v_cvt_pk_bf16_f32 v124, v222, v223
	v_cvt_pk_bf16_f32 v125, v216, v217
	global_store_dwordx2 v[154:155], v[124:125], off offset:256
	ds_read_b128 v[180:183], v238 offset:192
	ds_read_b128 v[184:187], v238 offset:448
	v_add_u32_e32 v124, 16, v146
	v_add_u32_e32 v126, 32, v146
	v_add_u32_e32 v128, 48, v146
	v_ashrrev_i32_e32 v125, 31, v124
	v_ashrrev_i32_e32 v127, 31, v126
	v_ashrrev_i32_e32 v129, 31, v128
	v_lshlrev_b64 v[124:125], 11, v[124:125]
	v_lshlrev_b64 v[126:127], 11, v[126:127]
	v_lshlrev_b64 v[128:129], 11, v[128:129]
	v_lshl_add_u64 v[124:125], s[36:37], 0, v[124:125]
	v_lshl_add_u64 v[126:127], s[36:37], 0, v[126:127]
	v_lshl_add_u64 v[128:129], s[36:37], 0, v[128:129]
	v_lshl_add_u64 v[124:125], v[124:125], 0, v[148:149]
	v_lshl_add_u64 v[126:127], v[126:127], 0, v[148:149]
	v_lshl_add_u64 v[224:225], v[128:129], 0, v[148:149]
	global_load_dwordx2 v[162:163], v[124:125], off
	global_load_dwordx2 v[160:161], v[124:125], off offset:32
	global_load_dwordx2 v[158:159], v[124:125], off offset:256
	global_load_dwordx2 v[156:157], v[124:125], off offset:288
	global_load_dwordx2 v[152:153], v[126:127], off
	global_load_dwordx2 v[150:151], v[126:127], off offset:32
	global_load_dwordx2 v[134:135], v[126:127], off offset:256
	global_load_dwordx2 v[132:133], v[126:127], off offset:288
	global_load_dwordx2 v[130:131], v[224:225], off
	global_load_dwordx2 v[128:129], v[224:225], off offset:32
	s_nop 0
	global_load_dwordx2 v[126:127], v[224:225], off offset:256
	global_load_dwordx2 v[124:125], v[224:225], off offset:288
	v_lshlrev_b32_e32 v224, 16, v190
	v_and_b32_e32 v190, 0xffff0000, v190
	v_and_b32_e32 v225, 0xffff0000, v191
	v_sub_f32_e32 v191, v190, v188
	v_sub_f32_e32 v190, v224, v188
	v_sub_f32_e32 v225, v225, v188
	v_sub_f32_e32 v224, v226, v188
	v_pk_mul_f32 v[224:225], v[188:189], v[224:225] op_sel:[1,0]
	v_pk_mul_f32 v[188:189], v[188:189], v[190:191] op_sel:[1,0]
	v_pk_mov_b32 v[190:191], v[194:195], v[192:193] op_sel:[1,0]
	v_mov_b32_e32 v226, v194
	v_pk_mul_f32 v[192:193], v[192:193], v[192:193]
	v_pk_mul_f32 v[194:195], v[194:195], v[194:195]
	v_pk_add_f32 v[190:191], v[190:191], v[226:227]
	v_pk_mov_b32 v[226:227], v[194:195], v[192:193] op_sel:[1,0]
	v_mov_b32_e32 v195, v193
	v_add_f32_e32 v192, v190, v191
	v_pk_add_f32 v[190:191], v[226:227], v[194:195]
	v_pk_mov_b32 v[194:195], v[210:211], v[196:197] op_sel:[1,0]
	v_mov_b32_e32 v226, v210
	v_mov_b32_e32 v227, v197
	v_pk_mul_f32 v[210:211], v[210:211], v[210:211]
	v_pk_mul_f32 v[196:197], v[196:197], v[196:197]
	v_pk_add_f32 v[194:195], v[194:195], v[226:227]
	v_pk_mov_b32 v[226:227], v[210:211], v[196:197] op_sel:[1,0]
	v_mov_b32_e32 v211, v197
	v_pk_add_f32 v[196:197], v[226:227], v[210:211]
	v_pk_add_f32 v[190:191], v[190:191], v[190:191] op_sel_hi:[0,1]
	v_pk_add_f32 v[196:197], v[196:197], v[196:197] op_sel_hi:[0,1]
	v_mul_f32_e32 v190, v222, v222
	v_mul_f32_e32 v196, v216, v216
	v_add_f32_e32 v210, v222, v223
	v_add_f32_e32 v226, v216, v217
	v_pk_fma_f32 v[222:223], v[222:223], v[222:223], v[190:191] op_sel_hi:[1,1,0]
	v_pk_fma_f32 v[216:217], v[216:217], v[216:217], v[196:197] op_sel_hi:[1,1,0]
	v_pk_add_f32 v[194:195], v[194:195], v[194:195] op_sel:[0,1] op_sel_hi:[1,0]
	v_add_f32_e32 v192, 0, v192
	v_cndmask_b32_e32 v179, v204, v179, vcc
	v_lshlrev_b32_e32 v179, 2, v179
	s_waitcnt vmcnt(15) lgkmcnt(0)
	v_pk_fma_f32 v[180:181], v[188:189], v[180:181], v[184:185]
	v_pk_fma_f32 v[182:183], v[224:225], v[182:183], v[186:187]
	v_pk_fma_f32 v[180:181], v[180:181], s[4:5], v[120:121] op_sel_hi:[1,0,1]
	v_pk_fma_f32 v[182:183], v[182:183], s[4:5], v[122:123] op_sel_hi:[1,0,1]
	v_mov_b32_e32 v222, v180
	v_mov_b32_e32 v216, v181
	v_mov_b32_e32 v196, v182
	v_mov_b32_e32 v190, v183
	v_mul_f32_e32 v211, v180, v180
	v_mul_f32_e32 v227, v181, v181
	v_mul_f32_e32 v195, v182, v182
	v_mul_f32_e32 v193, v183, v183
	v_pk_add_f32 v[120:121], v[222:223], v[216:217]
	v_pk_add_f32 v[122:123], v[196:197], v[190:191]
	v_pk_add_f32 v[184:185], v[210:211], v[226:227]
	v_pk_add_f32 v[120:121], v[120:121], v[122:123]
	v_pk_add_f32 v[122:123], v[194:195], v[192:193]
	v_cvt_pk_bf16_f32 v180, v180, v181
	v_pk_add_f32 v[122:123], v[184:185], v[122:123]
	v_cvt_pk_bf16_f32 v181, v182, v183
	v_pk_add_f32 v[120:121], v[120:121], v[122:123]
	ds_bpermute_b32 v122, v175, v120
	ds_bpermute_b32 v123, v175, v121
	global_store_dwordx2 v[154:155], v[180:181], off offset:288
	s_waitcnt lgkmcnt(0)
	v_pk_add_f32 v[120:121], v[120:121], v[122:123]
	ds_bpermute_b32 v122, v179, v120
	ds_bpermute_b32 v123, v179, v121
	s_and_saveexec_b64 s[14:15], s[44:45]
	s_cbranch_execz .LBB0_750
	s_waitcnt lgkmcnt(0)
	v_pk_add_f32 v[120:121], v[120:121], v[122:123]
	v_lshlrev_b64 v[122:123], 7, v[146:147]
	v_lshl_add_u64 v[122:123], s[34:35], 0, v[122:123]
	v_lshl_add_u64 v[122:123], s[52:53], 3, v[122:123]
	global_store_dwordx2 v[122:123], v[120:121], off
; __device__ __forceinline__ float bflo(unsigned w) { return __uint_as_float(w << 16); }
; __device__ __forceinline__ float bfhi(unsigned w) { return __uint_as_float(w & 0xffff0000u); }
; __device__ __forceinline__ u32x2 pack4(const f32x4 a) { u32x2 v; v.x = cvt_pk_bf16(a[0], a[1]); v.y = cvt_pk_bf16(a[2], a[3]); return v; }
;     __device__ __forceinline__ void apply(const RowInfo& ri, const ColInfo& ci, int row, int col, f32x4 a, f32x4 pv, float& s1, float& s2) const {
;         f32x4 h = pv;
;         if (!ident) { const f32x4 gg = *(const f32x4*)(g + col), bb = *(const f32x4*)(b + col); h = (pv - ri.mu) * ri.rstd * gg + bb; }
;         const f32x4 v = h * ALPHA + a;
;         *(u32x2*)(xb + (size_t)row * DM + col) = pack4(v);
;         s1 += (v[0] + v[1]) + (v[2] + v[3]); s2 += (v[0] * v[0] + v[1] * v[1]) + (v[2] * v[2] + v[3] * v[3]);
; template <class Epi>
; __device__ __forceinline__ void gemm_phase(LAS unsigned char* lds, const bf16_t* Ag, const bf16_t* Btg, const int K, const int nM, const int nN, const Epi& E) {
;     ...
;                 f32x4 pv[2][2];
; #pragma unroll
;                 for (int bj = 0; bj < 2; ++bj)
; #pragma unroll
;                     for (int n = 0; n < 2; ++n) { const u32x2 w = pk[m][bj][n]; pv[bj][n] = (f32x4){bflo(w.x), bfhi(w.x), bflo(w.y), bfhi(w.y)}; }
;                 const RowInfo ri = E.rowinfo(row, lrow, par, lds);
;                 float s1 = 0.f, s2 = 0.f;
; #pragma unroll
;                 for (int bj = 0; bj < 2; ++bj)
; #pragma unroll
;                     for (int n = 0; n < 2; ++n) E.apply(ri, ci[bj][n], row, pn * 256 + bj * 128 + wc * 32 + n * 16 + fq * 4, acc[ai][bj][m][n], pv[bj][n], s1, s2);
;                 if (Epi::STATS) {
;                     s1 += __shfl_xor(s1, 16); s1 += __shfl_xor(s1, 32); s2 += __shfl_xor(s2, 16); s2 += __shfl_xor(s2, 32);
;                     if (fq == 0) *(f32x2*)(E.stat_out + ((size_t)row * 16 + pn * 4 + wc) * 2) = (f32x2){s1, s2};
;                 }
.LBB0_750:
	s_or_b64 exec, exec, s[14:15]
	ds_read_b128 v[180:183], v238
	ds_read_b128 v[184:187], v238 offset:256
	s_waitcnt lgkmcnt(0)
	ds_read_b64 v[122:123], v176 offset:128
	s_waitcnt vmcnt(12) lgkmcnt(0)
	v_lshlrev_b32_e32 v147, 16, v162
	v_and_b32_e32 v162, 0xffff0000, v162
	v_lshlrev_b32_e32 v188, 16, v163
	v_and_b32_e32 v189, 0xffff0000, v163
	v_add_u32_e32 v120, s49, v167
	s_waitcnt lgkmcnt(0)
	v_sub_f32_e32 v163, v162, v122
	v_sub_f32_e32 v162, v147, v122
	v_sub_f32_e32 v189, v189, v122
	v_sub_f32_e32 v188, v188, v122
	v_ashrrev_i32_e32 v121, 31, v120
	v_pk_mul_f32 v[188:189], v[122:123], v[188:189] op_sel:[1,0]
	v_pk_mul_f32 v[162:163], v[122:123], v[162:163] op_sel:[1,0]
	v_lshlrev_b64 v[154:155], 11, v[120:121]
	v_lshl_add_u64 v[154:155], s[36:37], 0, v[154:155]
	v_lshl_add_u64 v[154:155], v[144:145], 1, v[154:155]
	s_waitcnt vmcnt(11)
	v_lshlrev_b32_e32 v147, 16, v160
	v_and_b32_e32 v160, 0xffff0000, v160
	s_waitcnt vmcnt(1)
	v_pk_fma_f32 v[162:163], v[180:181], v[162:163], v[184:185]
	v_pk_fma_f32 v[180:181], v[182:183], v[188:189], v[186:187]
	v_pk_fma_f32 v[162:163], v[162:163], s[4:5], v[116:117] op_sel_hi:[1,0,1]
	v_pk_fma_f32 v[184:185], v[180:181], s[4:5], v[118:119] op_sel_hi:[1,0,1]
	v_cvt_pk_bf16_f32 v116, v162, v163
	v_cvt_pk_bf16_f32 v117, v184, v185
	global_store_dwordx2 v[154:155], v[116:117], off
	ds_read_b128 v[116:119], v238 offset:64
	s_nop 0
	ds_read_b128 v[180:183], v238 offset:320
	v_lshlrev_b32_e32 v186, 16, v161
	v_and_b32_e32 v187, 0xffff0000, v161
	v_sub_f32_e32 v161, v160, v122
	v_sub_f32_e32 v160, v147, v122
	v_sub_f32_e32 v187, v187, v122
	v_sub_f32_e32 v186, v186, v122
	v_pk_mul_f32 v[186:187], v[122:123], v[186:187] op_sel:[1,0]
	v_pk_mul_f32 v[160:161], v[122:123], v[160:161] op_sel:[1,0]
	v_lshlrev_b32_e32 v147, 16, v158
	v_and_b32_e32 v158, 0xffff0000, v158
	v_mul_f32_e32 v189, v184, v184
	s_waitcnt vmcnt(2) lgkmcnt(0)
	v_pk_fma_f32 v[116:117], v[160:161], v[116:117], v[180:181]
	v_pk_fma_f32 v[118:119], v[186:187], v[118:119], v[182:183]
	v_pk_fma_f32 v[180:181], v[116:117], s[4:5], v[112:113] op_sel_hi:[1,0,1]
	v_pk_fma_f32 v[160:161], v[118:119], s[4:5], v[114:115] op_sel_hi:[1,0,1]
	v_cvt_pk_bf16_f32 v112, v180, v181
	v_cvt_pk_bf16_f32 v113, v160, v161
	global_store_dwordx2 v[154:155], v[112:113], off offset:32
	ds_read_b128 v[112:115], v238 offset:128
	s_nop 0
	ds_read_b128 v[116:119], v238 offset:384
	v_lshlrev_b32_e32 v182, 16, v159
	v_and_b32_e32 v183, 0xffff0000, v159
	v_sub_f32_e32 v159, v158, v122
	v_sub_f32_e32 v158, v147, v122
	v_sub_f32_e32 v183, v183, v122
	v_sub_f32_e32 v182, v182, v122
	v_pk_mul_f32 v[182:183], v[122:123], v[182:183] op_sel:[1,0]
	v_pk_mul_f32 v[158:159], v[122:123], v[158:159] op_sel:[1,0]
	v_lshlrev_b32_e32 v147, 16, v156
	v_and_b32_e32 v156, 0xffff0000, v156
	v_mul_f32_e32 v190, v160, v160
	v_mul_f32_e32 v187, v162, v162
	v_mov_b32_e32 v186, v180
	v_mov_b32_e32 v188, v160
	s_waitcnt vmcnt(3) lgkmcnt(0)
	v_pk_fma_f32 v[112:113], v[158:159], v[112:113], v[116:117]
	v_pk_fma_f32 v[114:115], v[182:183], v[114:115], v[118:119]
	v_pk_fma_f32 v[118:119], v[112:113], s[4:5], v[108:109] op_sel_hi:[1,0,1]
	v_pk_fma_f32 v[116:117], v[114:115], s[4:5], v[110:111] op_sel_hi:[1,0,1]
	v_cvt_pk_bf16_f32 v108, v118, v119
	v_cvt_pk_bf16_f32 v109, v116, v117
	global_store_dwordx2 v[154:155], v[108:109], off offset:256
	ds_read_b128 v[108:111], v238 offset:192
	s_nop 0
	ds_read_b128 v[112:115], v238 offset:448
	v_lshlrev_b32_e32 v158, 16, v157
	v_and_b32_e32 v159, 0xffff0000, v157
	v_sub_f32_e32 v157, v156, v122
	v_sub_f32_e32 v156, v147, v122
	v_sub_f32_e32 v159, v159, v122
	v_sub_f32_e32 v158, v158, v122
	v_pk_mul_f32 v[158:159], v[122:123], v[158:159] op_sel:[1,0]
	v_pk_mul_f32 v[122:123], v[122:123], v[156:157] op_sel:[1,0]
	v_add_f32_e32 v156, v162, v163
	v_add_f32_e32 v182, v184, v185
	v_mul_f32_e32 v163, v163, v163
	v_mul_f32_e32 v185, v185, v185
	v_mul_f32_e32 v157, v180, v180
	v_mul_f32_e32 v183, v181, v181
	v_mov_b32_e32 v162, v181
	v_mov_b32_e32 v184, v161
	v_pk_fma_f32 v[160:161], v[160:161], v[160:161], v[190:191] op_sel_hi:[1,1,0]
	v_pk_add_f32 v[162:163], v[186:187], v[162:163]
	v_pk_add_f32 v[180:181], v[188:189], v[184:185]
	v_pk_add_f32 v[156:157], v[156:157], v[182:183]
	v_mov_b32_e32 v160, v1
	v_pk_add_f32 v[162:163], v[162:163], v[180:181]
	v_pk_add_f32 v[156:157], v[156:157], v[160:161]
	v_mul_f32_e32 v161, v118, v118
	v_pk_add_f32 v[156:157], v[162:163], v[156:157]
	v_mul_f32_e32 v163, v119, v119
	v_mul_f32_e32 v181, v116, v116
	v_mul_f32_e32 v183, v117, v117
	v_mov_b32_e32 v160, v118
	v_mov_b32_e32 v162, v119
	v_mov_b32_e32 v180, v116
	v_mov_b32_e32 v182, v117
	v_pk_add_f32 v[116:117], v[160:161], v[162:163]
	v_pk_add_f32 v[118:119], v[180:181], v[182:183]
	s_waitcnt vmcnt(4) lgkmcnt(0)
	v_pk_fma_f32 v[108:109], v[122:123], v[108:109], v[112:113]
	v_pk_fma_f32 v[110:111], v[158:159], v[110:111], v[114:115]
	v_pk_fma_f32 v[108:109], v[108:109], s[4:5], v[104:105] op_sel_hi:[1,0,1]
	v_pk_fma_f32 v[110:111], v[110:111], s[4:5], v[106:107] op_sel_hi:[1,0,1]
	v_mul_f32_e32 v105, v108, v108
	v_mul_f32_e32 v107, v109, v109
	v_mul_f32_e32 v113, v110, v110
	v_mul_f32_e32 v115, v111, v111
	v_mov_b32_e32 v104, v108
	v_mov_b32_e32 v106, v109
	v_mov_b32_e32 v112, v110
	v_mov_b32_e32 v114, v111
	v_pk_add_f32 v[116:117], v[116:117], v[118:119]
	v_pk_add_f32 v[104:105], v[104:105], v[106:107]
	v_pk_add_f32 v[106:107], v[112:113], v[114:115]
	v_pk_add_f32 v[116:117], v[156:157], v[116:117]
	v_pk_add_f32 v[104:105], v[104:105], v[106:107]
	v_cvt_pk_bf16_f32 v108, v108, v109
	v_pk_add_f32 v[104:105], v[116:117], v[104:105]
	ds_bpermute_b32 v106, v175, v104
	ds_bpermute_b32 v107, v175, v105
	v_cvt_pk_bf16_f32 v109, v110, v111
	global_store_dwordx2 v[154:155], v[108:109], off offset:288
	s_waitcnt lgkmcnt(0)
	v_pk_add_f32 v[104:105], v[104:105], v[106:107]
	ds_bpermute_b32 v106, v179, v104
	ds_bpermute_b32 v107, v179, v105
	s_and_saveexec_b64 s[14:15], s[44:45]
	s_cbranch_execz .LBB0_752
	s_waitcnt lgkmcnt(0)
	v_pk_add_f32 v[104:105], v[104:105], v[106:107]
	v_lshlrev_b64 v[106:107], 7, v[120:121]
	v_lshl_add_u64 v[106:107], s[34:35], 0, v[106:107]
	v_lshl_add_u64 v[106:107], s[52:53], 3, v[106:107]
	global_store_dwordx2 v[106:107], v[104:105], off
; __device__ __forceinline__ float bflo(unsigned w) { return __uint_as_float(w << 16); }
; __device__ __forceinline__ float bfhi(unsigned w) { return __uint_as_float(w & 0xffff0000u); }
; __device__ __forceinline__ u32x2 pack4(const f32x4 a) { u32x2 v; v.x = cvt_pk_bf16(a[0], a[1]); v.y = cvt_pk_bf16(a[2], a[3]); return v; }
;     __device__ __forceinline__ void apply(const RowInfo& ri, const ColInfo& ci, int row, int col, f32x4 a, f32x4 pv, float& s1, float& s2) const {
;         f32x4 h = pv;
;         if (!ident) { const f32x4 gg = *(const f32x4*)(g + col), bb = *(const f32x4*)(b + col); h = (pv - ri.mu) * ri.rstd * gg + bb; }
;         const f32x4 v = h * ALPHA + a;
;         *(u32x2*)(xb + (size_t)row * DM + col) = pack4(v);
;         s1 += (v[0] + v[1]) + (v[2] + v[3]); s2 += (v[0] * v[0] + v[1] * v[1]) + (v[2] * v[2] + v[3] * v[3]);
; template <class Epi>
; __device__ __forceinline__ void gemm_phase(LAS unsigned char* lds, const bf16_t* Ag, const bf16_t* Btg, const int K, const int nM, const int nN, const Epi& E) {
;     ...
;                 f32x4 pv[2][2];
; #pragma unroll
;                 for (int bj = 0; bj < 2; ++bj)
; #pragma unroll
;                     for (int n = 0; n < 2; ++n) { const u32x2 w = pk[m][bj][n]; pv[bj][n] = (f32x4){bflo(w.x), bfhi(w.x), bflo(w.y), bfhi(w.y)}; }
;                 const RowInfo ri = E.rowinfo(row, lrow, par, lds);
;                 float s1 = 0.f, s2 = 0.f;
; #pragma unroll
;                 for (int bj = 0; bj < 2; ++bj)
; #pragma unroll
;                     for (int n = 0; n < 2; ++n) E.apply(ri, ci[bj][n], row, pn * 256 + bj * 128 + wc * 32 + n * 16 + fq * 4, acc[ai][bj][m][n], pv[bj][n], s1, s2);
;                 if (Epi::STATS) {
;                     s1 += __shfl_xor(s1, 16); s1 += __shfl_xor(s1, 32); s2 += __shfl_xor(s2, 16); s2 += __shfl_xor(s2, 32);
;                     if (fq == 0) *(f32x2*)(E.stat_out + ((size_t)row * 16 + pn * 4 + wc) * 2) = (f32x2){s1, s2};
;                 }
.LBB0_752:
	s_or_b64 exec, exec, s[14:15]
	s_waitcnt lgkmcnt(0)
	ds_read_b128 v[106:109], v238
	ds_read_b128 v[110:113], v238 offset:256
	ds_read_b64 v[114:115], v176 offset:256
	v_lshlrev_b32_e32 v118, 16, v152
	v_and_b32_e32 v119, 0xffff0000, v152
	v_lshlrev_b32_e32 v120, 16, v153
	v_and_b32_e32 v121, 0xffff0000, v153
	v_add_u32_e32 v104, s49, v168
	s_waitcnt lgkmcnt(0)
	v_sub_f32_e32 v119, v119, v114
	v_sub_f32_e32 v118, v118, v114
	v_sub_f32_e32 v121, v121, v114
	v_sub_f32_e32 v120, v120, v114
	v_ashrrev_i32_e32 v105, 31, v104
	v_pk_mul_f32 v[120:121], v[114:115], v[120:121] op_sel:[1,0]
	v_pk_mul_f32 v[118:119], v[114:115], v[118:119] op_sel:[1,0]
	v_lshlrev_b64 v[116:117], 11, v[104:105]
	v_lshl_add_u64 v[116:117], s[36:37], 0, v[116:117]
	v_lshl_add_u64 v[116:117], v[144:145], 1, v[116:117]
	s_waitcnt vmcnt(5) lgkmcnt(0)
	v_pk_fma_f32 v[106:107], v[106:107], v[118:119], v[110:111]
	v_pk_fma_f32 v[108:109], v[108:109], v[120:121], v[112:113]
	v_pk_fma_f32 v[112:113], v[106:107], s[4:5], v[100:101] op_sel_hi:[1,0,1]
	v_pk_fma_f32 v[110:111], v[108:109], s[4:5], v[102:103] op_sel_hi:[1,0,1]
	v_cvt_pk_bf16_f32 v100, v112, v113
	v_cvt_pk_bf16_f32 v101, v110, v111
	global_store_dwordx2 v[116:117], v[100:101], off
	ds_read_b128 v[100:103], v238 offset:64
	s_nop 0
	ds_read_b128 v[106:109], v238 offset:320
	v_lshlrev_b32_e32 v118, 16, v150
	v_and_b32_e32 v119, 0xffff0000, v150
	v_lshlrev_b32_e32 v120, 16, v151
	v_and_b32_e32 v121, 0xffff0000, v151
	v_sub_f32_e32 v119, v119, v114
	v_sub_f32_e32 v118, v118, v114
	v_sub_f32_e32 v121, v121, v114
	v_sub_f32_e32 v120, v120, v114
	v_pk_mul_f32 v[120:121], v[114:115], v[120:121] op_sel:[1,0]
	v_pk_mul_f32 v[118:119], v[114:115], v[118:119] op_sel:[1,0]
	v_add_f32_e32 v122, v110, v111
	v_mul_f32_e32 v111, v111, v111
	s_waitcnt vmcnt(6) lgkmcnt(0)
	v_pk_fma_f32 v[100:101], v[118:119], v[100:101], v[106:107]
	v_pk_fma_f32 v[102:103], v[120:121], v[102:103], v[108:109]
	v_pk_fma_f32 v[108:109], v[100:101], s[4:5], v[96:97] op_sel_hi:[1,0,1]
	v_pk_fma_f32 v[106:107], v[102:103], s[4:5], v[98:99] op_sel_hi:[1,0,1]
	v_cvt_pk_bf16_f32 v96, v108, v109
	v_cvt_pk_bf16_f32 v97, v106, v107
	global_store_dwordx2 v[116:117], v[96:97], off offset:32
	ds_read_b128 v[96:99], v238 offset:128
	s_nop 0
	ds_read_b128 v[100:103], v238 offset:384
	v_lshlrev_b32_e32 v118, 16, v134
	v_and_b32_e32 v119, 0xffff0000, v134
	v_lshlrev_b32_e32 v120, 16, v135
	v_and_b32_e32 v121, 0xffff0000, v135
	v_sub_f32_e32 v119, v119, v114
	v_sub_f32_e32 v118, v118, v114
	v_sub_f32_e32 v121, v121, v114
	v_sub_f32_e32 v120, v120, v114
	v_pk_mul_f32 v[120:121], v[114:115], v[120:121] op_sel:[1,0]
	v_pk_mul_f32 v[118:119], v[114:115], v[118:119] op_sel:[1,0]
	v_mul_f32_e32 v150, v106, v106
	v_mul_f32_e32 v135, v110, v110
	v_mul_f32_e32 v123, v109, v109
	v_mov_b32_e32 v134, v106
	v_mov_b32_e32 v110, v107
	v_pk_fma_f32 v[106:107], v[106:107], v[106:107], v[150:151] op_sel_hi:[1,1,0]
	v_pk_add_f32 v[110:111], v[134:135], v[110:111]
	v_mov_b32_e32 v106, v1
	s_waitcnt vmcnt(7) lgkmcnt(0)
	v_pk_fma_f32 v[96:97], v[118:119], v[96:97], v[100:101]
	v_pk_fma_f32 v[98:99], v[120:121], v[98:99], v[102:103]
	v_pk_fma_f32 v[102:103], v[96:97], s[4:5], v[92:93] op_sel_hi:[1,0,1]
	v_pk_fma_f32 v[100:101], v[98:99], s[4:5], v[94:95] op_sel_hi:[1,0,1]
	v_cvt_pk_bf16_f32 v92, v102, v103
	v_cvt_pk_bf16_f32 v93, v100, v101
	global_store_dwordx2 v[116:117], v[92:93], off offset:256
	ds_read_b128 v[92:95], v238 offset:192
	s_nop 0
	ds_read_b128 v[96:99], v238 offset:448
	v_lshlrev_b32_e32 v118, 16, v132
	v_and_b32_e32 v119, 0xffff0000, v132
	v_lshlrev_b32_e32 v120, 16, v133
	v_and_b32_e32 v121, 0xffff0000, v133
	v_sub_f32_e32 v119, v119, v114
	v_sub_f32_e32 v118, v118, v114
	v_sub_f32_e32 v121, v121, v114
	v_sub_f32_e32 v120, v120, v114
	v_pk_mul_f32 v[120:121], v[114:115], v[120:121] op_sel:[1,0]
	v_pk_mul_f32 v[114:115], v[114:115], v[118:119] op_sel:[1,0]
	v_add_f32_e32 v118, v112, v113
	v_mul_f32_e32 v133, v112, v112
	v_mul_f32_e32 v113, v113, v113
	v_mul_f32_e32 v119, v108, v108
	v_mov_b32_e32 v132, v108
	v_mov_b32_e32 v112, v109
	v_pk_add_f32 v[108:109], v[132:133], v[112:113]
	v_pk_add_f32 v[112:113], v[118:119], v[122:123]
	v_pk_add_f32 v[108:109], v[108:109], v[110:111]
	v_pk_add_f32 v[106:107], v[112:113], v[106:107]
	v_mul_f32_e32 v111, v103, v103
	v_pk_add_f32 v[106:107], v[108:109], v[106:107]
	v_mul_f32_e32 v109, v102, v102
	v_mul_f32_e32 v113, v100, v100
	v_mul_f32_e32 v119, v101, v101
	v_mov_b32_e32 v108, v102
	v_mov_b32_e32 v110, v103
	v_mov_b32_e32 v112, v100
	v_mov_b32_e32 v118, v101
	v_pk_add_f32 v[100:101], v[108:109], v[110:111]
	v_pk_add_f32 v[102:103], v[112:113], v[118:119]
	s_waitcnt vmcnt(8) lgkmcnt(0)
	v_pk_fma_f32 v[92:93], v[114:115], v[92:93], v[96:97]
	v_pk_fma_f32 v[94:95], v[120:121], v[94:95], v[98:99]
	v_pk_fma_f32 v[92:93], v[92:93], s[4:5], v[88:89] op_sel_hi:[1,0,1]
	v_pk_fma_f32 v[94:95], v[94:95], s[4:5], v[90:91] op_sel_hi:[1,0,1]
	v_mul_f32_e32 v89, v92, v92
	v_mul_f32_e32 v91, v93, v93
	v_mul_f32_e32 v97, v94, v94
	v_mul_f32_e32 v99, v95, v95
	v_mov_b32_e32 v88, v92
	v_mov_b32_e32 v90, v93
	v_mov_b32_e32 v96, v94
	v_mov_b32_e32 v98, v95
	v_pk_add_f32 v[100:101], v[100:101], v[102:103]
	v_pk_add_f32 v[88:89], v[88:89], v[90:91]
	v_pk_add_f32 v[90:91], v[96:97], v[98:99]
	v_pk_add_f32 v[100:101], v[106:107], v[100:101]
	v_pk_add_f32 v[88:89], v[88:89], v[90:91]
	v_cvt_pk_bf16_f32 v92, v92, v93
	v_pk_add_f32 v[88:89], v[100:101], v[88:89]
	ds_bpermute_b32 v90, v175, v88
	ds_bpermute_b32 v91, v175, v89
	v_cvt_pk_bf16_f32 v93, v94, v95
	global_store_dwordx2 v[116:117], v[92:93], off offset:288
	s_waitcnt lgkmcnt(0)
	v_pk_add_f32 v[88:89], v[88:89], v[90:91]
	ds_bpermute_b32 v90, v179, v88
	ds_bpermute_b32 v91, v179, v89
	s_and_saveexec_b64 s[14:15], s[44:45]
	s_cbranch_execz .LBB0_754
	s_waitcnt lgkmcnt(0)
	v_pk_add_f32 v[88:89], v[88:89], v[90:91]
	v_lshlrev_b64 v[90:91], 7, v[104:105]
	v_lshl_add_u64 v[90:91], s[34:35], 0, v[90:91]
	v_lshl_add_u64 v[90:91], s[52:53], 3, v[90:91]
	global_store_dwordx2 v[90:91], v[88:89], off
; __device__ __forceinline__ float bflo(unsigned w) { return __uint_as_float(w << 16); }
; __device__ __forceinline__ float bfhi(unsigned w) { return __uint_as_float(w & 0xffff0000u); }
; __device__ __forceinline__ u32x2 pack4(const f32x4 a) { u32x2 v; v.x = cvt_pk_bf16(a[0], a[1]); v.y = cvt_pk_bf16(a[2], a[3]); return v; }
;     __device__ __forceinline__ void apply(const RowInfo& ri, const ColInfo& ci, int row, int col, f32x4 a, f32x4 pv, float& s1, float& s2) const {
;         f32x4 h = pv;
;         if (!ident) { const f32x4 gg = *(const f32x4*)(g + col), bb = *(const f32x4*)(b + col); h = (pv - ri.mu) * ri.rstd * gg + bb; }
;         const f32x4 v = h * ALPHA + a;
;         *(u32x2*)(xb + (size_t)row * DM + col) = pack4(v);
;         s1 += (v[0] + v[1]) + (v[2] + v[3]); s2 += (v[0] * v[0] + v[1] * v[1]) + (v[2] * v[2] + v[3] * v[3]);
; template <class Epi>
; __device__ __forceinline__ void gemm_phase(LAS unsigned char* lds, const bf16_t* Ag, const bf16_t* Btg, const int K, const int nM, const int nN, const Epi& E) {
;     ...
;                 f32x4 pv[2][2];
; #pragma unroll
;                 for (int bj = 0; bj < 2; ++bj)
; #pragma unroll
;                     for (int n = 0; n < 2; ++n) { const u32x2 w = pk[m][bj][n]; pv[bj][n] = (f32x4){bflo(w.x), bfhi(w.x), bflo(w.y), bfhi(w.y)}; }
;                 const RowInfo ri = E.rowinfo(row, lrow, par, lds);
;                 float s1 = 0.f, s2 = 0.f;
; #pragma unroll
;                 for (int bj = 0; bj < 2; ++bj)
; #pragma unroll
;                     for (int n = 0; n < 2; ++n) E.apply(ri, ci[bj][n], row, pn * 256 + bj * 128 + wc * 32 + n * 16 + fq * 4, acc[ai][bj][m][n], pv[bj][n], s1, s2);
;                 if (Epi::STATS) {
;                     s1 += __shfl_xor(s1, 16); s1 += __shfl_xor(s1, 32); s2 += __shfl_xor(s2, 16); s2 += __shfl_xor(s2, 32);
;                     if (fq == 0) *(f32x2*)(E.stat_out + ((size_t)row * 16 + pn * 4 + wc) * 2) = (f32x2){s1, s2};
;                 }
.LBB0_754:
	s_or_b64 exec, exec, s[14:15]
	s_waitcnt lgkmcnt(0)
	ds_read_b128 v[90:93], v238
	ds_read_b128 v[94:97], v238 offset:256
	ds_read_b64 v[98:99], v176 offset:384
	v_lshlrev_b32_e32 v102, 16, v130
	v_and_b32_e32 v103, 0xffff0000, v130
	v_lshlrev_b32_e32 v104, 16, v131
	v_and_b32_e32 v105, 0xffff0000, v131
	v_add_u32_e32 v88, s49, v169
	s_waitcnt lgkmcnt(0)
	v_sub_f32_e32 v103, v103, v98
	v_sub_f32_e32 v102, v102, v98
	v_sub_f32_e32 v105, v105, v98
	v_sub_f32_e32 v104, v104, v98
	v_ashrrev_i32_e32 v89, 31, v88
	v_pk_mul_f32 v[104:105], v[98:99], v[104:105] op_sel:[1,0]
	v_pk_mul_f32 v[102:103], v[98:99], v[102:103] op_sel:[1,0]
	v_lshlrev_b64 v[100:101], 11, v[88:89]
	v_lshl_add_u64 v[100:101], s[36:37], 0, v[100:101]
	v_lshl_add_u64 v[100:101], v[144:145], 1, v[100:101]
	s_waitcnt vmcnt(9) lgkmcnt(0)
	v_pk_fma_f32 v[90:91], v[90:91], v[102:103], v[94:95]
	v_pk_fma_f32 v[92:93], v[92:93], v[104:105], v[96:97]
	v_pk_fma_f32 v[96:97], v[90:91], s[4:5], v[84:85] op_sel_hi:[1,0,1]
	v_pk_fma_f32 v[94:95], v[92:93], s[4:5], v[86:87] op_sel_hi:[1,0,1]
	v_cvt_pk_bf16_f32 v84, v96, v97
	v_cvt_pk_bf16_f32 v85, v94, v95
	global_store_dwordx2 v[100:101], v[84:85], off
	ds_read_b128 v[84:87], v238 offset:64
	s_nop 0
	ds_read_b128 v[90:93], v238 offset:320
	v_lshlrev_b32_e32 v102, 16, v128
	v_and_b32_e32 v103, 0xffff0000, v128
	v_lshlrev_b32_e32 v104, 16, v129
	v_and_b32_e32 v105, 0xffff0000, v129
	v_sub_f32_e32 v103, v103, v98
	v_sub_f32_e32 v102, v102, v98
	v_sub_f32_e32 v105, v105, v98
	v_sub_f32_e32 v104, v104, v98
	v_pk_mul_f32 v[104:105], v[98:99], v[104:105] op_sel:[1,0]
	v_pk_mul_f32 v[102:103], v[98:99], v[102:103] op_sel:[1,0]
	v_add_f32_e32 v106, v94, v95
	v_mul_f32_e32 v109, v96, v96
	v_mul_f32_e32 v111, v94, v94
	v_mul_f32_e32 v95, v95, v95
	s_waitcnt vmcnt(10) lgkmcnt(0)
	v_pk_fma_f32 v[84:85], v[102:103], v[84:85], v[90:91]
	v_pk_fma_f32 v[86:87], v[104:105], v[86:87], v[92:93]
	v_pk_fma_f32 v[92:93], v[84:85], s[4:5], v[80:81] op_sel_hi:[1,0,1]
	v_pk_fma_f32 v[90:91], v[86:87], s[4:5], v[82:83] op_sel_hi:[1,0,1]
	v_cvt_pk_bf16_f32 v80, v92, v93
	v_cvt_pk_bf16_f32 v81, v90, v91
	global_store_dwordx2 v[100:101], v[80:81], off offset:32
	ds_read_b128 v[80:83], v238 offset:128
	s_nop 0
	ds_read_b128 v[84:87], v238 offset:384
	v_lshlrev_b32_e32 v102, 16, v126
	v_and_b32_e32 v103, 0xffff0000, v126
	v_lshlrev_b32_e32 v104, 16, v127
	v_and_b32_e32 v105, 0xffff0000, v127
	v_sub_f32_e32 v103, v103, v98
	v_sub_f32_e32 v102, v102, v98
	v_sub_f32_e32 v105, v105, v98
	v_sub_f32_e32 v104, v104, v98
	v_pk_mul_f32 v[104:105], v[98:99], v[104:105] op_sel:[1,0]
	v_pk_mul_f32 v[102:103], v[98:99], v[102:103] op_sel:[1,0]
	v_mul_f32_e32 v112, v90, v90
	v_mul_f32_e32 v107, v93, v93
	v_mov_b32_e32 v108, v92
	v_mov_b32_e32 v110, v90
	v_mov_b32_e32 v94, v91
	v_pk_fma_f32 v[90:91], v[90:91], v[90:91], v[112:113] op_sel_hi:[1,1,0]
	v_pk_add_f32 v[94:95], v[110:111], v[94:95]
	v_mov_b32_e32 v90, v1
	s_waitcnt vmcnt(11) lgkmcnt(0)
	v_pk_fma_f32 v[80:81], v[102:103], v[80:81], v[84:85]
	v_pk_fma_f32 v[82:83], v[104:105], v[82:83], v[86:87]
	v_pk_fma_f32 v[86:87], v[80:81], s[4:5], v[76:77] op_sel_hi:[1,0,1]
	v_pk_fma_f32 v[84:85], v[82:83], s[4:5], v[78:79] op_sel_hi:[1,0,1]
	v_cvt_pk_bf16_f32 v76, v86, v87
	v_cvt_pk_bf16_f32 v77, v84, v85
	global_store_dwordx2 v[100:101], v[76:77], off offset:256
	ds_read_b128 v[76:79], v238 offset:192
	s_nop 0
	ds_read_b128 v[80:83], v238 offset:448
	v_lshlrev_b32_e32 v102, 16, v124
	v_and_b32_e32 v103, 0xffff0000, v124
	v_lshlrev_b32_e32 v104, 16, v125
	v_and_b32_e32 v105, 0xffff0000, v125
	v_sub_f32_e32 v103, v103, v98
	v_sub_f32_e32 v102, v102, v98
	v_sub_f32_e32 v105, v105, v98
	v_sub_f32_e32 v104, v104, v98
	v_pk_mul_f32 v[104:105], v[98:99], v[104:105] op_sel:[1,0]
	v_pk_mul_f32 v[98:99], v[98:99], v[102:103] op_sel:[1,0]
	v_add_f32_e32 v102, v96, v97
	v_mul_f32_e32 v97, v97, v97
	v_mul_f32_e32 v103, v92, v92
	v_mov_b32_e32 v96, v93
	v_pk_add_f32 v[92:93], v[108:109], v[96:97]
	v_pk_add_f32 v[96:97], v[102:103], v[106:107]
	v_pk_add_f32 v[92:93], v[92:93], v[94:95]
	v_pk_add_f32 v[90:91], v[96:97], v[90:91]
	v_mul_f32_e32 v95, v87, v87
	v_pk_add_f32 v[90:91], v[92:93], v[90:91]
	v_mul_f32_e32 v93, v86, v86
	v_mul_f32_e32 v97, v84, v84
	v_mul_f32_e32 v103, v85, v85
	v_mov_b32_e32 v92, v86
	v_mov_b32_e32 v94, v87
	v_mov_b32_e32 v96, v84
	v_mov_b32_e32 v102, v85
	v_pk_add_f32 v[84:85], v[92:93], v[94:95]
	v_pk_add_f32 v[86:87], v[96:97], v[102:103]
	s_waitcnt vmcnt(12) lgkmcnt(0)
	v_pk_fma_f32 v[76:77], v[98:99], v[76:77], v[80:81]
	v_pk_fma_f32 v[78:79], v[104:105], v[78:79], v[82:83]
	v_pk_fma_f32 v[76:77], v[76:77], s[4:5], v[72:73] op_sel_hi:[1,0,1]
	v_pk_fma_f32 v[78:79], v[78:79], s[4:5], v[74:75] op_sel_hi:[1,0,1]
	v_mul_f32_e32 v73, v76, v76
	v_mul_f32_e32 v75, v77, v77
	v_mul_f32_e32 v81, v78, v78
	v_mul_f32_e32 v83, v79, v79
	v_mov_b32_e32 v72, v76
	v_mov_b32_e32 v74, v77
	v_mov_b32_e32 v80, v78
	v_mov_b32_e32 v82, v79
	v_pk_add_f32 v[84:85], v[84:85], v[86:87]
	v_pk_add_f32 v[72:73], v[72:73], v[74:75]
	v_pk_add_f32 v[74:75], v[80:81], v[82:83]
	v_pk_add_f32 v[84:85], v[90:91], v[84:85]
	v_pk_add_f32 v[72:73], v[72:73], v[74:75]
	v_cvt_pk_bf16_f32 v76, v76, v77
	v_pk_add_f32 v[72:73], v[84:85], v[72:73]
	ds_bpermute_b32 v74, v175, v72
	ds_bpermute_b32 v75, v175, v73
	v_cvt_pk_bf16_f32 v77, v78, v79
	global_store_dwordx2 v[100:101], v[76:77], off offset:288
	s_waitcnt lgkmcnt(0)
	v_pk_add_f32 v[72:73], v[72:73], v[74:75]
	ds_bpermute_b32 v74, v179, v72
	ds_bpermute_b32 v75, v179, v73
	s_and_saveexec_b64 s[14:15], s[44:45]
	s_cbranch_execz .LBB0_756
	s_waitcnt lgkmcnt(0)
	v_pk_add_f32 v[72:73], v[72:73], v[74:75]
	v_lshlrev_b64 v[74:75], 7, v[88:89]
	v_lshl_add_u64 v[74:75], s[34:35], 0, v[74:75]
	v_lshl_add_u64 v[74:75], s[52:53], 3, v[74:75]
	global_store_dwordx2 v[74:75], v[72:73], off
; __device__ __forceinline__ float bflo(unsigned w) { return __uint_as_float(w << 16); }
; __device__ __forceinline__ float bfhi(unsigned w) { return __uint_as_float(w & 0xffff0000u); }
; __device__ __forceinline__ u32x2 pack4(const f32x4 a) { u32x2 v; v.x = cvt_pk_bf16(a[0], a[1]); v.y = cvt_pk_bf16(a[2], a[3]); return v; }
; __device__ __forceinline__ int prow0(int pm) { return (pm >> 4) * LP + PADR + (pm & 15) * 256; }
;     __device__ __forceinline__ u32x2 preload_pk(int row, int col) const { return (u32x2){0u, 0u}; }
;     __device__ __forceinline__ u32x2 preload_pk(int row, int col) const { return (u32x2){0u, 0u}; }
;     __device__ __forceinline__ void apply(const RowInfo& ri, const ColInfo& ci, int row, int col, f32x4 a, f32x4 pv, float& s1, float& s2) const {
;         f32x4 h = pv;
;         if (!ident) { const f32x4 gg = *(const f32x4*)(g + col), bb = *(const f32x4*)(b + col); h = (pv - ri.mu) * ri.rstd * gg + bb; }
;         const f32x4 v = h * ALPHA + a;
;         *(u32x2*)(xb + (size_t)row * DM + col) = pack4(v);
;         s1 += (v[0] + v[1]) + (v[2] + v[3]); s2 += (v[0] * v[0] + v[1] * v[1]) + (v[2] * v[2] + v[3] * v[3]);
; template <class Epi>
; __device__ __forceinline__ void gemm_phase(LAS unsigned char* lds, const bf16_t* Ag, const bf16_t* Btg, const int K, const int nM, const int nN, const Epi& E) {
;     ...
;                             for (int n = 0; n < 2; ++n) pk[g2][bj][n] = E.preload_pk(prow0(pm) + ai * 128 + wr * 64 + g2 * 16 + fr, pn * 256 + bj * 128 + wc * 32 + n * 16 + fq * 4);
;                 }
;                 f32x4 pv[2][2];
; #pragma unroll
;                 for (int bj = 0; bj < 2; ++bj)
; #pragma unroll
;                     for (int n = 0; n < 2; ++n) { const u32x2 w = pk[m][bj][n]; pv[bj][n] = (f32x4){bflo(w.x), bfhi(w.x), bflo(w.y), bfhi(w.y)}; }
;                 const RowInfo ri = E.rowinfo(row, lrow, par, lds);
;                 float s1 = 0.f, s2 = 0.f;
; #pragma unroll
;                 for (int bj = 0; bj < 2; ++bj)
; #pragma unroll
;                     for (int n = 0; n < 2; ++n) E.apply(ri, ci[bj][n], row, pn * 256 + bj * 128 + wc * 32 + n * 16 + fq * 4, acc[ai][bj][m][n], pv[bj][n], s1, s2);
.LBB0_756:
	s_or_b64 exec, exec, s[14:15]
	v_add_u32_e32 v72, 0x80, v146
	v_ashrrev_i32_e32 v73, 31, v72
	v_lshlrev_b64 v[72:73], 11, v[72:73]
	v_lshl_add_u64 v[72:73], s[36:37], 0, v[72:73]
	v_lshl_add_u64 v[96:97], v[72:73], 0, v[148:149]
	global_load_dwordx2 v[108:109], v[96:97], off
	ds_read_b128 v[100:103], v238
	ds_read_b128 v[104:107], v238 offset:256
	global_load_dwordx2 v[110:111], v[96:97], off offset:32
	v_add_u32_e32 v72, 0x90, v146
	s_waitcnt lgkmcnt(1)
	v_add_u32_e32 v74, 0xa0, v146
	v_add_u32_e32 v76, 0xb0, v146
	v_ashrrev_i32_e32 v73, 31, v72
	s_waitcnt lgkmcnt(0)
	v_ashrrev_i32_e32 v75, 31, v74
	v_ashrrev_i32_e32 v77, 31, v76
	ds_read_b64 v[98:99], v176 offset:1024
	v_lshlrev_b64 v[72:73], 11, v[72:73]
	v_lshlrev_b64 v[74:75], 11, v[74:75]
	v_lshlrev_b64 v[76:77], 11, v[76:77]
	v_lshl_add_u64 v[72:73], s[36:37], 0, v[72:73]
	v_lshl_add_u64 v[74:75], s[36:37], 0, v[74:75]
	v_lshl_add_u64 v[76:77], s[36:37], 0, v[76:77]
	v_lshl_add_u64 v[72:73], v[72:73], 0, v[148:149]
	v_lshl_add_u64 v[74:75], v[74:75], 0, v[148:149]
	v_lshl_add_u64 v[112:113], v[76:77], 0, v[148:149]
	global_load_dwordx2 v[94:95], v[72:73], off
	global_load_dwordx2 v[92:93], v[72:73], off offset:32
	global_load_dwordx2 v[90:91], v[72:73], off offset:256
	global_load_dwordx2 v[88:89], v[72:73], off offset:288
	global_load_dwordx2 v[86:87], v[74:75], off
	global_load_dwordx2 v[84:85], v[74:75], off offset:32
	global_load_dwordx2 v[82:83], v[74:75], off offset:256
	global_load_dwordx2 v[80:81], v[74:75], off offset:288
	global_load_dwordx2 v[78:79], v[112:113], off
	global_load_dwordx2 v[76:77], v[112:113], off offset:32
	s_nop 0
	global_load_dwordx2 v[74:75], v[112:113], off offset:256
	global_load_dwordx2 v[72:73], v[112:113], off offset:288
	s_waitcnt vmcnt(13) lgkmcnt(0)
	v_lshlrev_b32_e32 v112, 16, v108
	v_and_b32_e32 v108, 0xffff0000, v108
	v_lshlrev_b32_e32 v114, 16, v109
	v_and_b32_e32 v113, 0xffff0000, v109
	s_waitcnt lgkmcnt(0)
	v_sub_f32_e32 v109, v108, v98
	v_sub_f32_e32 v108, v112, v98
	v_sub_f32_e32 v113, v113, v98
	v_sub_f32_e32 v112, v114, v98
	v_pk_mul_f32 v[112:113], v[98:99], v[112:113] op_sel:[1,0]
	v_pk_mul_f32 v[108:109], v[98:99], v[108:109] op_sel:[1,0]
	s_waitcnt vmcnt(13)
	v_pk_fma_f32 v[102:103], v[102:103], v[112:113], v[106:107]
	v_pk_fma_f32 v[100:101], v[100:101], v[108:109], v[104:105]
	v_pk_fma_f32 v[70:71], v[102:103], s[4:5], v[70:71] op_sel_hi:[1,0,1]
	v_pk_fma_f32 v[68:69], v[100:101], s[4:5], v[68:69] op_sel_hi:[1,0,1]
	v_cvt_pk_bf16_f32 v101, v70, v71
	v_cvt_pk_bf16_f32 v100, v68, v69
	global_store_dwordx2 v[96:97], v[100:101], off
	ds_read_b128 v[100:103], v238 offset:64
	s_nop 0
	ds_read_b128 v[104:107], v238 offset:320
	global_load_dwordx2 v[108:109], v[96:97], off offset:256
	s_waitcnt vmcnt(14) lgkmcnt(0)
	v_lshlrev_b32_e32 v112, 16, v110
	v_and_b32_e32 v110, 0xffff0000, v110
	v_lshlrev_b32_e32 v114, 16, v111
	v_and_b32_e32 v113, 0xffff0000, v111
	v_sub_f32_e32 v111, v110, v98
	v_sub_f32_e32 v110, v112, v98
	v_sub_f32_e32 v113, v113, v98
	v_sub_f32_e32 v112, v114, v98
	v_pk_mul_f32 v[112:113], v[98:99], v[112:113] op_sel:[1,0]
	v_pk_mul_f32 v[110:111], v[98:99], v[110:111] op_sel:[1,0]
	s_waitcnt vmcnt(2)
	v_pk_fma_f32 v[102:103], v[102:103], v[112:113], v[106:107]
	v_pk_fma_f32 v[100:101], v[100:101], v[110:111], v[104:105]
	v_pk_fma_f32 v[104:105], v[102:103], s[4:5], v[66:67] op_sel_hi:[1,0,1]
	v_pk_fma_f32 v[106:107], v[100:101], s[4:5], v[64:65] op_sel_hi:[1,0,1]
	v_cvt_pk_bf16_f32 v65, v104, v105
	v_cvt_pk_bf16_f32 v64, v106, v107
	global_store_dwordx2 v[96:97], v[64:65], off offset:32
	ds_read_b128 v[64:67], v238 offset:128
	s_nop 0
	ds_read_b128 v[100:103], v238 offset:384
	global_load_dwordx2 v[110:111], v[96:97], off offset:288
	s_waitcnt vmcnt(2) lgkmcnt(0)
	v_lshlrev_b32_e32 v112, 16, v108
	v_and_b32_e32 v108, 0xffff0000, v108
	v_lshlrev_b32_e32 v114, 16, v109
	v_and_b32_e32 v113, 0xffff0000, v109
	v_sub_f32_e32 v109, v108, v98
	v_sub_f32_e32 v108, v112, v98
	v_sub_f32_e32 v113, v113, v98
	v_sub_f32_e32 v112, v114, v98
	v_pk_mul_f32 v[112:113], v[98:99], v[112:113] op_sel:[1,0]
	v_pk_mul_f32 v[108:109], v[98:99], v[108:109] op_sel:[1,0]
	s_waitcnt vmcnt(2)
	v_pk_fma_f32 v[66:67], v[112:113], v[66:67], v[102:103]
	v_pk_fma_f32 v[64:65], v[108:109], v[64:65], v[100:101]
	v_pk_fma_f32 v[100:101], v[66:67], s[4:5], v[62:63] op_sel_hi:[1,0,1]
	v_pk_fma_f32 v[102:103], v[64:65], s[4:5], v[60:61] op_sel_hi:[1,0,1]
	v_cvt_pk_bf16_f32 v61, v100, v101
	v_cvt_pk_bf16_f32 v60, v102, v103
	global_store_dwordx2 v[96:97], v[60:61], off offset:256
	ds_read_b128 v[60:63], v238 offset:192
	s_nop 0
	ds_read_b128 v[64:67], v238 offset:448
	s_waitcnt vmcnt(1) lgkmcnt(0)
	v_lshlrev_b32_e32 v108, 16, v110
	v_and_b32_e32 v109, 0xffff0000, v110
	v_lshlrev_b32_e32 v110, 16, v111
	v_and_b32_e32 v111, 0xffff0000, v111
	v_sub_f32_e32 v109, v109, v98
	v_sub_f32_e32 v108, v108, v98
	v_sub_f32_e32 v111, v111, v98
	v_sub_f32_e32 v110, v110, v98
	v_pk_mul_f32 v[110:111], v[98:99], v[110:111] op_sel:[1,0]
	v_pk_mul_f32 v[98:99], v[98:99], v[108:109] op_sel:[1,0]
	v_pk_mov_b32 v[108:109], v[68:69], v[70:71] op_sel:[1,0]
	v_mov_b32_e32 v112, v68
	v_mov_b32_e32 v113, v71
	v_pk_mul_f32 v[70:71], v[70:71], v[70:71]
	v_pk_mul_f32 v[68:69], v[68:69], v[68:69]
	v_pk_add_f32 v[108:109], v[108:109], v[112:113]
	v_pk_mov_b32 v[112:113], v[68:69], v[70:71] op_sel:[1,0]
	v_mov_b32_e32 v69, v71
	v_add_f32_e32 v70, v108, v109
	v_pk_add_f32 v[68:69], v[112:113], v[68:69]
	v_pk_mov_b32 v[108:109], v[106:107], v[104:105] op_sel:[1,0]
	v_mov_b32_e32 v112, v106
	v_mov_b32_e32 v113, v105
	v_pk_mul_f32 v[106:107], v[106:107], v[106:107]
	v_pk_mul_f32 v[104:105], v[104:105], v[104:105]
	v_pk_add_f32 v[108:109], v[108:109], v[112:113]
	v_pk_mov_b32 v[112:113], v[106:107], v[104:105] op_sel:[1,0]
	v_mov_b32_e32 v107, v105
	v_pk_add_f32 v[104:105], v[112:113], v[106:107]
	v_pk_add_f32 v[68:69], v[68:69], v[68:69] op_sel_hi:[0,1]
	v_pk_add_f32 v[104:105], v[104:105], v[104:105] op_sel_hi:[0,1]
	v_mul_f32_e32 v68, v102, v102
	v_mul_f32_e32 v104, v100, v100
	v_pk_add_f32 v[106:107], v[108:109], v[108:109] op_sel:[0,1] op_sel_hi:[1,0]
	v_add_f32_e32 v108, v102, v103
	v_add_f32_e32 v112, v100, v101
	v_pk_fma_f32 v[102:103], v[102:103], v[102:103], v[68:69] op_sel_hi:[1,1,0]
	v_pk_fma_f32 v[100:101], v[100:101], v[100:101], v[104:105] op_sel_hi:[1,1,0]
	v_add_f32_e32 v70, 0, v70
	s_waitcnt vmcnt(1)
; __device__ __forceinline__ float bflo(unsigned w) { return __uint_as_float(w << 16); }
; __device__ __forceinline__ float bfhi(unsigned w) { return __uint_as_float(w & 0xffff0000u); }
; __device__ __forceinline__ u32x2 pack4(const f32x4 a) { u32x2 v; v.x = cvt_pk_bf16(a[0], a[1]); v.y = cvt_pk_bf16(a[2], a[3]); return v; }
;     __device__ __forceinline__ void apply(const RowInfo& ri, const ColInfo& ci, int row, int col, f32x4 a, f32x4 pv, float& s1, float& s2) const {
;         f32x4 h = pv;
;         if (!ident) { const f32x4 gg = *(const f32x4*)(g + col), bb = *(const f32x4*)(b + col); h = (pv - ri.mu) * ri.rstd * gg + bb; }
;         const f32x4 v = h * ALPHA + a;
;         *(u32x2*)(xb + (size_t)row * DM + col) = pack4(v);
;         s1 += (v[0] + v[1]) + (v[2] + v[3]); s2 += (v[0] * v[0] + v[1] * v[1]) + (v[2] * v[2] + v[3] * v[3]);
; template <class Epi>
; __device__ __forceinline__ void gemm_phase(LAS unsigned char* lds, const bf16_t* Ag, const bf16_t* Btg, const int K, const int nM, const int nN, const Epi& E) {
;     ...
;                 f32x4 pv[2][2];
; #pragma unroll
;                 for (int bj = 0; bj < 2; ++bj)
; #pragma unroll
;                     for (int n = 0; n < 2; ++n) { const u32x2 w = pk[m][bj][n]; pv[bj][n] = (f32x4){bflo(w.x), bfhi(w.x), bflo(w.y), bfhi(w.y)}; }
;                 const RowInfo ri = E.rowinfo(row, lrow, par, lds);
;                 float s1 = 0.f, s2 = 0.f;
; #pragma unroll
;                 for (int bj = 0; bj < 2; ++bj)
; #pragma unroll
;                     for (int n = 0; n < 2; ++n) E.apply(ri, ci[bj][n], row, pn * 256 + bj * 128 + wc * 32 + n * 16 + fq * 4, acc[ai][bj][m][n], pv[bj][n], s1, s2);
;                 if (Epi::STATS) {
;                     s1 += __shfl_xor(s1, 16); s1 += __shfl_xor(s1, 32); s2 += __shfl_xor(s2, 16); s2 += __shfl_xor(s2, 32);
;                     if (fq == 0) *(f32x2*)(E.stat_out + ((size_t)row * 16 + pn * 4 + wc) * 2) = (f32x2){s1, s2};
;                 }
	v_pk_fma_f32 v[60:61], v[98:99], v[60:61], v[64:65]
	v_pk_fma_f32 v[62:63], v[110:111], v[62:63], v[66:67]
	v_pk_fma_f32 v[60:61], v[60:61], s[4:5], v[56:57] op_sel_hi:[1,0,1]
	v_pk_fma_f32 v[62:63], v[62:63], s[4:5], v[58:59] op_sel_hi:[1,0,1]
	v_mov_b32_e32 v102, v60
	v_mov_b32_e32 v100, v61
	v_mov_b32_e32 v104, v62
	v_mov_b32_e32 v68, v63
	v_mul_f32_e32 v109, v60, v60
	v_mul_f32_e32 v113, v61, v61
	v_mul_f32_e32 v107, v62, v62
	v_mul_f32_e32 v71, v63, v63
	v_pk_add_f32 v[56:57], v[102:103], v[100:101]
	v_pk_add_f32 v[58:59], v[104:105], v[68:69]
	v_pk_add_f32 v[64:65], v[108:109], v[112:113]
	v_pk_add_f32 v[56:57], v[56:57], v[58:59]
	v_pk_add_f32 v[58:59], v[106:107], v[70:71]
	v_cvt_pk_bf16_f32 v60, v60, v61
	v_pk_add_f32 v[58:59], v[64:65], v[58:59]
	v_cvt_pk_bf16_f32 v61, v62, v63
	v_pk_add_f32 v[56:57], v[56:57], v[58:59]
	ds_bpermute_b32 v58, v175, v56
	ds_bpermute_b32 v59, v175, v57
	global_store_dwordx2 v[96:97], v[60:61], off offset:288
	s_waitcnt lgkmcnt(0)
	v_pk_add_f32 v[56:57], v[56:57], v[58:59]
	ds_bpermute_b32 v58, v179, v56
	ds_bpermute_b32 v59, v179, v57
	s_and_saveexec_b64 s[14:15], s[44:45]
	s_cbranch_execz .LBB0_758
	v_add_u32_e32 v60, s49, v170
	v_ashrrev_i32_e32 v61, 31, v60
	s_waitcnt lgkmcnt(0)
	v_pk_add_f32 v[56:57], v[56:57], v[58:59]
	v_lshlrev_b64 v[58:59], 7, v[60:61]
	v_lshl_add_u64 v[58:59], s[34:35], 0, v[58:59]
	v_lshl_add_u64 v[58:59], s[52:53], 3, v[58:59]
	global_store_dwordx2 v[58:59], v[56:57], off
.LBB0_758:
	s_or_b64 exec, exec, s[14:15]
	s_waitcnt lgkmcnt(0)
	ds_read_b128 v[58:61], v238
	ds_read_b128 v[62:65], v238 offset:256
	ds_read_b64 v[66:67], v176 offset:1152
	v_lshlrev_b32_e32 v70, 16, v94
	v_and_b32_e32 v71, 0xffff0000, v94
	v_lshlrev_b32_e32 v94, 16, v95
	v_and_b32_e32 v95, 0xffff0000, v95
	v_add_u32_e32 v56, s49, v171
	s_waitcnt lgkmcnt(0)
	v_sub_f32_e32 v71, v71, v66
	v_sub_f32_e32 v70, v70, v66
	v_sub_f32_e32 v95, v95, v66
	v_sub_f32_e32 v94, v94, v66
	v_ashrrev_i32_e32 v57, 31, v56
	v_pk_mul_f32 v[94:95], v[66:67], v[94:95] op_sel:[1,0]
	v_pk_mul_f32 v[70:71], v[66:67], v[70:71] op_sel:[1,0]
	v_lshlrev_b64 v[68:69], 11, v[56:57]
	v_lshl_add_u64 v[68:69], s[36:37], 0, v[68:69]
	v_lshl_add_u64 v[68:69], v[144:145], 1, v[68:69]
	s_waitcnt vmcnt(2) lgkmcnt(0)
	v_pk_fma_f32 v[58:59], v[58:59], v[70:71], v[62:63]
	v_pk_fma_f32 v[60:61], v[60:61], v[94:95], v[64:65]
	v_pk_fma_f32 v[64:65], v[58:59], s[4:5], v[52:53] op_sel_hi:[1,0,1]
	v_pk_fma_f32 v[62:63], v[60:61], s[4:5], v[54:55] op_sel_hi:[1,0,1]
	v_cvt_pk_bf16_f32 v52, v64, v65
	v_cvt_pk_bf16_f32 v53, v62, v63
	global_store_dwordx2 v[68:69], v[52:53], off
	ds_read_b128 v[52:55], v238 offset:64
	s_nop 0
	ds_read_b128 v[58:61], v238 offset:320
	v_lshlrev_b32_e32 v70, 16, v92
	v_and_b32_e32 v71, 0xffff0000, v92
	v_lshlrev_b32_e32 v92, 16, v93
	v_and_b32_e32 v93, 0xffff0000, v93
	v_sub_f32_e32 v71, v71, v66
	v_sub_f32_e32 v70, v70, v66
	v_sub_f32_e32 v93, v93, v66
	v_sub_f32_e32 v92, v92, v66
	v_pk_mul_f32 v[92:93], v[66:67], v[92:93] op_sel:[1,0]
	v_pk_mul_f32 v[70:71], v[66:67], v[70:71] op_sel:[1,0]
	v_mul_f32_e32 v95, v62, v62
	s_waitcnt vmcnt(3) lgkmcnt(0)
	v_pk_fma_f32 v[52:53], v[70:71], v[52:53], v[58:59]
	v_pk_fma_f32 v[54:55], v[92:93], v[54:55], v[60:61]
	v_pk_fma_f32 v[60:61], v[52:53], s[4:5], v[48:49] op_sel_hi:[1,0,1]
	v_pk_fma_f32 v[58:59], v[54:55], s[4:5], v[50:51] op_sel_hi:[1,0,1]
	v_cvt_pk_bf16_f32 v48, v60, v61
	v_cvt_pk_bf16_f32 v49, v58, v59
	global_store_dwordx2 v[68:69], v[48:49], off offset:32
	ds_read_b128 v[48:51], v238 offset:128
	s_nop 0
	ds_read_b128 v[52:55], v238 offset:384
	v_lshlrev_b32_e32 v70, 16, v90
	v_and_b32_e32 v71, 0xffff0000, v90
	v_lshlrev_b32_e32 v90, 16, v91
	v_and_b32_e32 v91, 0xffff0000, v91
	v_sub_f32_e32 v71, v71, v66
	v_sub_f32_e32 v70, v70, v66
	v_sub_f32_e32 v91, v91, v66
	v_sub_f32_e32 v90, v90, v66
	v_pk_mul_f32 v[90:91], v[66:67], v[90:91] op_sel:[1,0]
	v_pk_mul_f32 v[70:71], v[66:67], v[70:71] op_sel:[1,0]
	v_mul_f32_e32 v96, v58, v58
	v_mul_f32_e32 v93, v64, v64
	v_mov_b32_e32 v92, v60
	v_mov_b32_e32 v94, v58
	s_waitcnt vmcnt(4) lgkmcnt(0)
	v_pk_fma_f32 v[48:49], v[70:71], v[48:49], v[52:53]
	v_pk_fma_f32 v[50:51], v[90:91], v[50:51], v[54:55]
	v_pk_fma_f32 v[54:55], v[48:49], s[4:5], v[44:45] op_sel_hi:[1,0,1]
	v_pk_fma_f32 v[52:53], v[50:51], s[4:5], v[46:47] op_sel_hi:[1,0,1]
	v_cvt_pk_bf16_f32 v44, v54, v55
	v_cvt_pk_bf16_f32 v45, v52, v53
	global_store_dwordx2 v[68:69], v[44:45], off offset:256
	ds_read_b128 v[44:47], v238 offset:192
	s_nop 0
	ds_read_b128 v[48:51], v238 offset:448
	v_lshlrev_b32_e32 v70, 16, v88
	v_and_b32_e32 v71, 0xffff0000, v88
	v_lshlrev_b32_e32 v88, 16, v89
	v_and_b32_e32 v89, 0xffff0000, v89
	v_sub_f32_e32 v71, v71, v66
	v_sub_f32_e32 v70, v70, v66
	v_sub_f32_e32 v89, v89, v66
	v_sub_f32_e32 v88, v88, v66
	v_pk_mul_f32 v[88:89], v[66:67], v[88:89] op_sel:[1,0]
	v_pk_mul_f32 v[66:67], v[66:67], v[70:71] op_sel:[1,0]
	v_add_f32_e32 v70, v64, v65
	v_add_f32_e32 v90, v62, v63
	v_mul_f32_e32 v65, v65, v65
	v_mul_f32_e32 v63, v63, v63
	v_mul_f32_e32 v71, v60, v60
	v_mul_f32_e32 v91, v61, v61
	v_mov_b32_e32 v64, v61
	v_mov_b32_e32 v62, v59
	v_pk_fma_f32 v[58:59], v[58:59], v[58:59], v[96:97] op_sel_hi:[1,1,0]
	v_pk_add_f32 v[60:61], v[92:93], v[64:65]
	v_pk_add_f32 v[62:63], v[94:95], v[62:63]
	v_pk_add_f32 v[64:65], v[70:71], v[90:91]
	v_mov_b32_e32 v58, v1
	v_pk_add_f32 v[60:61], v[60:61], v[62:63]
	v_pk_add_f32 v[58:59], v[64:65], v[58:59]
	v_mul_f32_e32 v63, v55, v55
	v_pk_add_f32 v[58:59], v[60:61], v[58:59]
	v_mul_f32_e32 v61, v54, v54
	v_mul_f32_e32 v65, v52, v52
	v_mul_f32_e32 v71, v53, v53
	v_mov_b32_e32 v60, v54
	v_mov_b32_e32 v62, v55
	v_mov_b32_e32 v64, v52
	v_mov_b32_e32 v70, v53
	v_pk_add_f32 v[52:53], v[60:61], v[62:63]
	v_pk_add_f32 v[54:55], v[64:65], v[70:71]
	s_waitcnt vmcnt(5) lgkmcnt(0)
	v_pk_fma_f32 v[44:45], v[66:67], v[44:45], v[48:49]
	v_pk_fma_f32 v[46:47], v[88:89], v[46:47], v[50:51]
	v_pk_fma_f32 v[44:45], v[44:45], s[4:5], v[40:41] op_sel_hi:[1,0,1]
	v_pk_fma_f32 v[46:47], v[46:47], s[4:5], v[42:43] op_sel_hi:[1,0,1]
	v_mul_f32_e32 v41, v44, v44
	v_mul_f32_e32 v43, v45, v45
	v_mul_f32_e32 v49, v46, v46
	v_mul_f32_e32 v51, v47, v47
	v_mov_b32_e32 v40, v44
	v_mov_b32_e32 v42, v45
	v_mov_b32_e32 v48, v46
	v_mov_b32_e32 v50, v47
	v_pk_add_f32 v[52:53], v[52:53], v[54:55]
	v_pk_add_f32 v[40:41], v[40:41], v[42:43]
	v_pk_add_f32 v[42:43], v[48:49], v[50:51]
	v_pk_add_f32 v[52:53], v[58:59], v[52:53]
	v_pk_add_f32 v[40:41], v[40:41], v[42:43]
	v_cvt_pk_bf16_f32 v44, v44, v45
	v_pk_add_f32 v[40:41], v[52:53], v[40:41]
	ds_bpermute_b32 v42, v175, v40
	ds_bpermute_b32 v43, v175, v41
	v_cvt_pk_bf16_f32 v45, v46, v47
	global_store_dwordx2 v[68:69], v[44:45], off offset:288
	s_waitcnt lgkmcnt(0)
	v_pk_add_f32 v[40:41], v[40:41], v[42:43]
	ds_bpermute_b32 v42, v179, v40
	ds_bpermute_b32 v43, v179, v41
	s_and_saveexec_b64 s[14:15], s[44:45]
	s_cbranch_execz .LBB0_760
; __device__ __forceinline__ float bflo(unsigned w) { return __uint_as_float(w << 16); }
; __device__ __forceinline__ float bfhi(unsigned w) { return __uint_as_float(w & 0xffff0000u); }
; __device__ __forceinline__ u32x2 pack4(const f32x4 a) { u32x2 v; v.x = cvt_pk_bf16(a[0], a[1]); v.y = cvt_pk_bf16(a[2], a[3]); return v; }
;     __device__ __forceinline__ void apply(const RowInfo& ri, const ColInfo& ci, int row, int col, f32x4 a, f32x4 pv, float& s1, float& s2) const {
;         f32x4 h = pv;
;         if (!ident) { const f32x4 gg = *(const f32x4*)(g + col), bb = *(const f32x4*)(b + col); h = (pv - ri.mu) * ri.rstd * gg + bb; }
;         const f32x4 v = h * ALPHA + a;
;         *(u32x2*)(xb + (size_t)row * DM + col) = pack4(v);
;         s1 += (v[0] + v[1]) + (v[2] + v[3]); s2 += (v[0] * v[0] + v[1] * v[1]) + (v[2] * v[2] + v[3] * v[3]);
; template <class Epi>
; __device__ __forceinline__ void gemm_phase(LAS unsigned char* lds, const bf16_t* Ag, const bf16_t* Btg, const int K, const int nM, const int nN, const Epi& E) {
;     ...
;                 f32x4 pv[2][2];
; #pragma unroll
;                 for (int bj = 0; bj < 2; ++bj)
; #pragma unroll
;                     for (int n = 0; n < 2; ++n) { const u32x2 w = pk[m][bj][n]; pv[bj][n] = (f32x4){bflo(w.x), bfhi(w.x), bflo(w.y), bfhi(w.y)}; }
;                 const RowInfo ri = E.rowinfo(row, lrow, par, lds);
;                 float s1 = 0.f, s2 = 0.f;
; #pragma unroll
;                 for (int bj = 0; bj < 2; ++bj)
; #pragma unroll
;                     for (int n = 0; n < 2; ++n) E.apply(ri, ci[bj][n], row, pn * 256 + bj * 128 + wc * 32 + n * 16 + fq * 4, acc[ai][bj][m][n], pv[bj][n], s1, s2);
;                 if (Epi::STATS) {
;                     s1 += __shfl_xor(s1, 16); s1 += __shfl_xor(s1, 32); s2 += __shfl_xor(s2, 16); s2 += __shfl_xor(s2, 32);
;                     if (fq == 0) *(f32x2*)(E.stat_out + ((size_t)row * 16 + pn * 4 + wc) * 2) = (f32x2){s1, s2};
;                 }
	s_waitcnt lgkmcnt(0)
	v_pk_add_f32 v[40:41], v[40:41], v[42:43]
	v_lshlrev_b64 v[42:43], 7, v[56:57]
	v_lshl_add_u64 v[42:43], s[34:35], 0, v[42:43]
	v_lshl_add_u64 v[42:43], s[52:53], 3, v[42:43]
	global_store_dwordx2 v[42:43], v[40:41], off
.LBB0_760:
	s_or_b64 exec, exec, s[14:15]
	s_waitcnt lgkmcnt(0)
	ds_read_b128 v[42:45], v238
	ds_read_b128 v[46:49], v238 offset:256
	ds_read_b64 v[50:51], v176 offset:1280
	v_lshlrev_b32_e32 v54, 16, v86
	v_and_b32_e32 v55, 0xffff0000, v86
	v_lshlrev_b32_e32 v56, 16, v87
	v_and_b32_e32 v57, 0xffff0000, v87
	v_add_u32_e32 v40, s49, v172
	s_waitcnt lgkmcnt(0)
	v_sub_f32_e32 v55, v55, v50
	v_sub_f32_e32 v54, v54, v50
	v_sub_f32_e32 v57, v57, v50
	v_sub_f32_e32 v56, v56, v50
	v_ashrrev_i32_e32 v41, 31, v40
	v_pk_mul_f32 v[56:57], v[50:51], v[56:57] op_sel:[1,0]
	v_pk_mul_f32 v[54:55], v[50:51], v[54:55] op_sel:[1,0]
	v_lshlrev_b64 v[52:53], 11, v[40:41]
	v_lshl_add_u64 v[52:53], s[36:37], 0, v[52:53]
	v_lshl_add_u64 v[52:53], v[144:145], 1, v[52:53]
	s_waitcnt vmcnt(6) lgkmcnt(0)
	v_pk_fma_f32 v[42:43], v[42:43], v[54:55], v[46:47]
	v_pk_fma_f32 v[44:45], v[44:45], v[56:57], v[48:49]
	v_pk_fma_f32 v[48:49], v[42:43], s[4:5], v[36:37] op_sel_hi:[1,0,1]
	v_pk_fma_f32 v[46:47], v[44:45], s[4:5], v[38:39] op_sel_hi:[1,0,1]
	v_cvt_pk_bf16_f32 v36, v48, v49
	v_cvt_pk_bf16_f32 v37, v46, v47
	global_store_dwordx2 v[52:53], v[36:37], off
	ds_read_b128 v[36:39], v238 offset:64
	s_nop 0
	ds_read_b128 v[42:45], v238 offset:320
	v_lshlrev_b32_e32 v54, 16, v84
	v_and_b32_e32 v55, 0xffff0000, v84
	v_lshlrev_b32_e32 v56, 16, v85
	v_and_b32_e32 v57, 0xffff0000, v85
	v_sub_f32_e32 v55, v55, v50
	v_sub_f32_e32 v54, v54, v50
	v_sub_f32_e32 v57, v57, v50
	v_sub_f32_e32 v56, v56, v50
	v_pk_mul_f32 v[56:57], v[50:51], v[56:57] op_sel:[1,0]
	v_pk_mul_f32 v[54:55], v[50:51], v[54:55] op_sel:[1,0]
	v_add_f32_e32 v58, v46, v47
	v_mul_f32_e32 v61, v48, v48
	v_mul_f32_e32 v63, v46, v46
	v_mul_f32_e32 v47, v47, v47
	s_waitcnt vmcnt(7) lgkmcnt(0)
	v_pk_fma_f32 v[36:37], v[54:55], v[36:37], v[42:43]
	v_pk_fma_f32 v[38:39], v[56:57], v[38:39], v[44:45]
	v_pk_fma_f32 v[44:45], v[36:37], s[4:5], v[32:33] op_sel_hi:[1,0,1]
	v_pk_fma_f32 v[42:43], v[38:39], s[4:5], v[34:35] op_sel_hi:[1,0,1]
	v_cvt_pk_bf16_f32 v32, v44, v45
	v_cvt_pk_bf16_f32 v33, v42, v43
	global_store_dwordx2 v[52:53], v[32:33], off offset:32
	ds_read_b128 v[32:35], v238 offset:128
	s_nop 0
	ds_read_b128 v[36:39], v238 offset:384
	v_lshlrev_b32_e32 v54, 16, v82
	v_and_b32_e32 v55, 0xffff0000, v82
	v_lshlrev_b32_e32 v56, 16, v83
	v_and_b32_e32 v57, 0xffff0000, v83
	v_sub_f32_e32 v55, v55, v50
	v_sub_f32_e32 v54, v54, v50
	v_sub_f32_e32 v57, v57, v50
	v_sub_f32_e32 v56, v56, v50
	v_pk_mul_f32 v[56:57], v[50:51], v[56:57] op_sel:[1,0]
	v_pk_mul_f32 v[54:55], v[50:51], v[54:55] op_sel:[1,0]
	v_mul_f32_e32 v64, v42, v42
	v_mul_f32_e32 v59, v45, v45
	v_mov_b32_e32 v60, v44
	v_mov_b32_e32 v62, v42
	v_mov_b32_e32 v46, v43
	v_pk_fma_f32 v[42:43], v[42:43], v[42:43], v[64:65] op_sel_hi:[1,1,0]
	v_pk_add_f32 v[46:47], v[62:63], v[46:47]
	v_mov_b32_e32 v42, v1
	s_waitcnt vmcnt(8) lgkmcnt(0)
	v_pk_fma_f32 v[32:33], v[54:55], v[32:33], v[36:37]
	v_pk_fma_f32 v[34:35], v[56:57], v[34:35], v[38:39]
	v_pk_fma_f32 v[38:39], v[32:33], s[4:5], v[28:29] op_sel_hi:[1,0,1]
	v_pk_fma_f32 v[36:37], v[34:35], s[4:5], v[30:31] op_sel_hi:[1,0,1]
	v_cvt_pk_bf16_f32 v28, v38, v39
	v_cvt_pk_bf16_f32 v29, v36, v37
	global_store_dwordx2 v[52:53], v[28:29], off offset:256
	ds_read_b128 v[28:31], v238 offset:192
	s_nop 0
	ds_read_b128 v[32:35], v238 offset:448
	v_lshlrev_b32_e32 v54, 16, v80
	v_and_b32_e32 v55, 0xffff0000, v80
	v_lshlrev_b32_e32 v56, 16, v81
	v_and_b32_e32 v57, 0xffff0000, v81
	v_sub_f32_e32 v55, v55, v50
	v_sub_f32_e32 v54, v54, v50
	v_sub_f32_e32 v57, v57, v50
	v_sub_f32_e32 v56, v56, v50
	v_pk_mul_f32 v[56:57], v[50:51], v[56:57] op_sel:[1,0]
	v_pk_mul_f32 v[50:51], v[50:51], v[54:55] op_sel:[1,0]
	v_add_f32_e32 v54, v48, v49
	v_mul_f32_e32 v49, v49, v49
	v_mul_f32_e32 v55, v44, v44
	v_mov_b32_e32 v48, v45
	v_pk_add_f32 v[44:45], v[60:61], v[48:49]
	v_pk_add_f32 v[48:49], v[54:55], v[58:59]
	v_pk_add_f32 v[44:45], v[44:45], v[46:47]
	v_pk_add_f32 v[42:43], v[48:49], v[42:43]
	v_mul_f32_e32 v47, v39, v39
	v_pk_add_f32 v[42:43], v[44:45], v[42:43]
	v_mul_f32_e32 v45, v38, v38
	v_mul_f32_e32 v49, v36, v36
	v_mul_f32_e32 v55, v37, v37
	v_mov_b32_e32 v44, v38
	v_mov_b32_e32 v46, v39
	v_mov_b32_e32 v48, v36
	v_mov_b32_e32 v54, v37
	v_pk_add_f32 v[36:37], v[44:45], v[46:47]
	v_pk_add_f32 v[38:39], v[48:49], v[54:55]
	s_waitcnt vmcnt(9) lgkmcnt(0)
	v_pk_fma_f32 v[28:29], v[50:51], v[28:29], v[32:33]
	v_pk_fma_f32 v[30:31], v[56:57], v[30:31], v[34:35]
	v_pk_fma_f32 v[28:29], v[28:29], s[4:5], v[24:25] op_sel_hi:[1,0,1]
	v_pk_fma_f32 v[30:31], v[30:31], s[4:5], v[26:27] op_sel_hi:[1,0,1]
	v_mul_f32_e32 v25, v28, v28
	v_mul_f32_e32 v27, v29, v29
	v_mul_f32_e32 v33, v30, v30
	v_mul_f32_e32 v35, v31, v31
	v_mov_b32_e32 v24, v28
	v_mov_b32_e32 v26, v29
	v_mov_b32_e32 v32, v30
	v_mov_b32_e32 v34, v31
	v_pk_add_f32 v[36:37], v[36:37], v[38:39]
	v_pk_add_f32 v[24:25], v[24:25], v[26:27]
	v_pk_add_f32 v[26:27], v[32:33], v[34:35]
	v_pk_add_f32 v[36:37], v[42:43], v[36:37]
	v_pk_add_f32 v[24:25], v[24:25], v[26:27]
	v_cvt_pk_bf16_f32 v28, v28, v29
	v_pk_add_f32 v[24:25], v[36:37], v[24:25]
	ds_bpermute_b32 v26, v175, v24
	ds_bpermute_b32 v27, v175, v25
	v_cvt_pk_bf16_f32 v29, v30, v31
	global_store_dwordx2 v[52:53], v[28:29], off offset:288
	s_waitcnt lgkmcnt(0)
	v_pk_add_f32 v[24:25], v[24:25], v[26:27]
	ds_bpermute_b32 v26, v179, v24
	ds_bpermute_b32 v27, v179, v25
	s_and_saveexec_b64 s[14:15], s[44:45]
	s_cbranch_execz .LBB0_762
	s_waitcnt lgkmcnt(0)
	v_pk_add_f32 v[24:25], v[24:25], v[26:27]
	v_lshlrev_b64 v[26:27], 7, v[40:41]
	v_lshl_add_u64 v[26:27], s[34:35], 0, v[26:27]
	v_lshl_add_u64 v[26:27], s[52:53], 3, v[26:27]
	global_store_dwordx2 v[26:27], v[24:25], off
; __device__ __forceinline__ float bflo(unsigned w) { return __uint_as_float(w << 16); }
; __device__ __forceinline__ float bfhi(unsigned w) { return __uint_as_float(w & 0xffff0000u); }
; __device__ __forceinline__ u32x2 pack4(const f32x4 a) { u32x2 v; v.x = cvt_pk_bf16(a[0], a[1]); v.y = cvt_pk_bf16(a[2], a[3]); return v; }
;     __device__ __forceinline__ void apply(const RowInfo& ri, const ColInfo& ci, int row, int col, f32x4 a, f32x4 pv, float& s1, float& s2) const {
;         f32x4 h = pv;
;         if (!ident) { const f32x4 gg = *(const f32x4*)(g + col), bb = *(const f32x4*)(b + col); h = (pv - ri.mu) * ri.rstd * gg + bb; }
;         const f32x4 v = h * ALPHA + a;
;         *(u32x2*)(xb + (size_t)row * DM + col) = pack4(v);
;         s1 += (v[0] + v[1]) + (v[2] + v[3]); s2 += (v[0] * v[0] + v[1] * v[1]) + (v[2] * v[2] + v[3] * v[3]);
; template <class Epi>
; __device__ __forceinline__ void gemm_phase(LAS unsigned char* lds, const bf16_t* Ag, const bf16_t* Btg, const int K, const int nM, const int nN, const Epi& E) {
;     ...
;                 f32x4 pv[2][2];
; #pragma unroll
;                 for (int bj = 0; bj < 2; ++bj)
; #pragma unroll
;                     for (int n = 0; n < 2; ++n) { const u32x2 w = pk[m][bj][n]; pv[bj][n] = (f32x4){bflo(w.x), bfhi(w.x), bflo(w.y), bfhi(w.y)}; }
;                 const RowInfo ri = E.rowinfo(row, lrow, par, lds);
;                 float s1 = 0.f, s2 = 0.f;
; #pragma unroll
;                 for (int bj = 0; bj < 2; ++bj)
; #pragma unroll
;                     for (int n = 0; n < 2; ++n) E.apply(ri, ci[bj][n], row, pn * 256 + bj * 128 + wc * 32 + n * 16 + fq * 4, acc[ai][bj][m][n], pv[bj][n], s1, s2);
;                 if (Epi::STATS) {
;                     s1 += __shfl_xor(s1, 16); s1 += __shfl_xor(s1, 32); s2 += __shfl_xor(s2, 16); s2 += __shfl_xor(s2, 32);
;                     if (fq == 0) *(f32x2*)(E.stat_out + ((size_t)row * 16 + pn * 4 + wc) * 2) = (f32x2){s1, s2};
;                 }
.LBB0_762:
	s_or_b64 exec, exec, s[14:15]
	s_waitcnt lgkmcnt(0)
	ds_read_b128 v[26:29], v238
	ds_read_b128 v[30:33], v238 offset:256
	ds_read_b64 v[34:35], v176 offset:1408
	v_lshlrev_b32_e32 v38, 16, v78
	v_and_b32_e32 v39, 0xffff0000, v78
	v_lshlrev_b32_e32 v40, 16, v79
	v_and_b32_e32 v41, 0xffff0000, v79
	v_add_u32_e32 v24, s49, v173
	s_waitcnt lgkmcnt(0)
	v_sub_f32_e32 v39, v39, v34
	v_sub_f32_e32 v38, v38, v34
	v_sub_f32_e32 v41, v41, v34
	v_sub_f32_e32 v40, v40, v34
	v_ashrrev_i32_e32 v25, 31, v24
	v_pk_mul_f32 v[40:41], v[34:35], v[40:41] op_sel:[1,0]
	v_pk_mul_f32 v[38:39], v[34:35], v[38:39] op_sel:[1,0]
	v_lshlrev_b64 v[36:37], 11, v[24:25]
	v_lshl_add_u64 v[36:37], s[36:37], 0, v[36:37]
	v_lshl_add_u64 v[36:37], v[144:145], 1, v[36:37]
	s_waitcnt vmcnt(10) lgkmcnt(0)
	v_pk_fma_f32 v[26:27], v[26:27], v[38:39], v[30:31]
	v_pk_fma_f32 v[28:29], v[28:29], v[40:41], v[32:33]
	v_pk_fma_f32 v[32:33], v[26:27], s[4:5], v[20:21] op_sel_hi:[1,0,1]
	v_pk_fma_f32 v[30:31], v[28:29], s[4:5], v[22:23] op_sel_hi:[1,0,1]
	v_cvt_pk_bf16_f32 v20, v32, v33
	v_cvt_pk_bf16_f32 v21, v30, v31
	global_store_dwordx2 v[36:37], v[20:21], off
	ds_read_b128 v[20:23], v238 offset:64
	s_nop 0
	ds_read_b128 v[26:29], v238 offset:320
	v_lshlrev_b32_e32 v38, 16, v76
	v_and_b32_e32 v39, 0xffff0000, v76
	v_lshlrev_b32_e32 v40, 16, v77
	v_and_b32_e32 v41, 0xffff0000, v77
	v_sub_f32_e32 v39, v39, v34
	v_sub_f32_e32 v38, v38, v34
	v_sub_f32_e32 v41, v41, v34
	v_sub_f32_e32 v40, v40, v34
	v_pk_mul_f32 v[40:41], v[34:35], v[40:41] op_sel:[1,0]
	v_pk_mul_f32 v[38:39], v[34:35], v[38:39] op_sel:[1,0]
	v_add_f32_e32 v42, v30, v31
	v_mul_f32_e32 v45, v32, v32
	v_mul_f32_e32 v47, v30, v30
	v_mul_f32_e32 v31, v31, v31
	s_waitcnt vmcnt(11) lgkmcnt(0)
	v_pk_fma_f32 v[20:21], v[38:39], v[20:21], v[26:27]
	v_pk_fma_f32 v[22:23], v[40:41], v[22:23], v[28:29]
	v_pk_fma_f32 v[28:29], v[20:21], s[4:5], v[16:17] op_sel_hi:[1,0,1]
	v_pk_fma_f32 v[26:27], v[22:23], s[4:5], v[18:19] op_sel_hi:[1,0,1]
	v_cvt_pk_bf16_f32 v16, v28, v29
	v_cvt_pk_bf16_f32 v17, v26, v27
	global_store_dwordx2 v[36:37], v[16:17], off offset:32
	ds_read_b128 v[16:19], v238 offset:128
	s_nop 0
	ds_read_b128 v[20:23], v238 offset:384
	v_lshlrev_b32_e32 v38, 16, v74
	v_and_b32_e32 v39, 0xffff0000, v74
	v_lshlrev_b32_e32 v40, 16, v75
	v_and_b32_e32 v41, 0xffff0000, v75
	v_sub_f32_e32 v39, v39, v34
	v_sub_f32_e32 v38, v38, v34
	v_sub_f32_e32 v41, v41, v34
	v_sub_f32_e32 v40, v40, v34
	v_pk_mul_f32 v[40:41], v[34:35], v[40:41] op_sel:[1,0]
	v_pk_mul_f32 v[38:39], v[34:35], v[38:39] op_sel:[1,0]
	v_mul_f32_e32 v48, v26, v26
	v_mul_f32_e32 v43, v29, v29
	v_mov_b32_e32 v44, v28
	v_mov_b32_e32 v46, v26
	v_mov_b32_e32 v30, v27
	v_pk_fma_f32 v[26:27], v[26:27], v[26:27], v[48:49] op_sel_hi:[1,1,0]
	v_pk_add_f32 v[30:31], v[46:47], v[30:31]
	v_mov_b32_e32 v26, v1
	s_waitcnt vmcnt(12) lgkmcnt(0)
	v_pk_fma_f32 v[16:17], v[38:39], v[16:17], v[20:21]
	v_pk_fma_f32 v[18:19], v[40:41], v[18:19], v[22:23]
	v_pk_fma_f32 v[22:23], v[16:17], s[4:5], v[12:13] op_sel_hi:[1,0,1]
	v_pk_fma_f32 v[20:21], v[18:19], s[4:5], v[14:15] op_sel_hi:[1,0,1]
	v_cvt_pk_bf16_f32 v12, v22, v23
	v_cvt_pk_bf16_f32 v13, v20, v21
	global_store_dwordx2 v[36:37], v[12:13], off offset:256
	ds_read_b128 v[12:15], v238 offset:192
	s_nop 0
	ds_read_b128 v[16:19], v238 offset:448
	v_lshlrev_b32_e32 v38, 16, v72
	v_and_b32_e32 v39, 0xffff0000, v72
	v_lshlrev_b32_e32 v40, 16, v73
	v_and_b32_e32 v41, 0xffff0000, v73
	v_sub_f32_e32 v39, v39, v34
	v_sub_f32_e32 v38, v38, v34
	v_sub_f32_e32 v41, v41, v34
	v_sub_f32_e32 v40, v40, v34
	v_pk_mul_f32 v[40:41], v[34:35], v[40:41] op_sel:[1,0]
	v_pk_mul_f32 v[34:35], v[34:35], v[38:39] op_sel:[1,0]
	v_add_f32_e32 v38, v32, v33
	v_mul_f32_e32 v33, v33, v33
	v_mul_f32_e32 v39, v28, v28
	v_mov_b32_e32 v32, v29
	v_pk_add_f32 v[28:29], v[44:45], v[32:33]
	v_pk_add_f32 v[32:33], v[38:39], v[42:43]
	v_pk_add_f32 v[28:29], v[28:29], v[30:31]
	v_pk_add_f32 v[26:27], v[32:33], v[26:27]
	v_mul_f32_e32 v31, v23, v23
	v_pk_add_f32 v[26:27], v[28:29], v[26:27]
	v_mul_f32_e32 v29, v22, v22
	v_mul_f32_e32 v33, v20, v20
	v_mul_f32_e32 v39, v21, v21
	v_mov_b32_e32 v28, v22
	v_mov_b32_e32 v30, v23
	v_mov_b32_e32 v32, v20
	v_mov_b32_e32 v38, v21
	v_pk_add_f32 v[20:21], v[28:29], v[30:31]
	v_pk_add_f32 v[22:23], v[32:33], v[38:39]
	s_waitcnt vmcnt(13) lgkmcnt(0)
	v_pk_fma_f32 v[12:13], v[34:35], v[12:13], v[16:17]
	v_pk_fma_f32 v[14:15], v[40:41], v[14:15], v[18:19]
	v_pk_fma_f32 v[12:13], v[12:13], s[4:5], v[8:9] op_sel_hi:[1,0,1]
	v_pk_fma_f32 v[14:15], v[14:15], s[4:5], v[10:11] op_sel_hi:[1,0,1]
	v_mul_f32_e32 v9, v12, v12
	v_mul_f32_e32 v11, v13, v13
	v_mul_f32_e32 v17, v14, v14
	v_mul_f32_e32 v19, v15, v15
	v_mov_b32_e32 v8, v12
	v_mov_b32_e32 v10, v13
	v_mov_b32_e32 v16, v14
	v_mov_b32_e32 v18, v15
	v_pk_add_f32 v[20:21], v[20:21], v[22:23]
	v_pk_add_f32 v[8:9], v[8:9], v[10:11]
	v_pk_add_f32 v[10:11], v[16:17], v[18:19]
	v_pk_add_f32 v[20:21], v[26:27], v[20:21]
	v_pk_add_f32 v[8:9], v[8:9], v[10:11]
	v_cvt_pk_bf16_f32 v12, v12, v13
	v_pk_add_f32 v[8:9], v[20:21], v[8:9]
	ds_bpermute_b32 v10, v175, v8
	ds_bpermute_b32 v11, v175, v9
	v_cvt_pk_bf16_f32 v13, v14, v15
	global_store_dwordx2 v[36:37], v[12:13], off offset:288
	s_waitcnt lgkmcnt(0)
	v_pk_add_f32 v[8:9], v[8:9], v[10:11]
	ds_bpermute_b32 v10, v179, v8
	ds_bpermute_b32 v11, v179, v9
	s_and_saveexec_b64 s[14:15], s[44:45]
	s_cbranch_execz .LBB0_764
	s_waitcnt lgkmcnt(0)
	v_pk_add_f32 v[8:9], v[8:9], v[10:11]
	v_lshlrev_b64 v[10:11], 7, v[24:25]
	v_lshl_add_u64 v[10:11], s[34:35], 0, v[10:11]
	v_lshl_add_u64 v[10:11], s[52:53], 3, v[10:11]
	global_store_dwordx2 v[10:11], v[8:9], off
